# stacked on fold-both attention: LN wave sums via permlane32/16 swap + DPP instead of bpermute; swiglu GEMM tail requests next tile's first k-tile before the epilogue, dword stores via DPP neighbour ex
# speedup vs baseline: 1.0345x; 1.0011x over previous
; DI float shx(float v, int lane, int m) { return __int_as_float(__builtin_amdgcn_ds_bpermute((lane ^ m) << 2, __float_as_int(v))); }
; DI float wave_sum(float v, int lane) {
; #pragma unroll
;     for (int o = 32; o > 0; o >>= 1) v += shx(v, lane, o);
;     return v;
; }
; DI void ln_phase(const Params& p, int mode, const float* g, const float* bb, const float* modl, int s_next, int nrows) {
;     ...
;             const float* mrow = modl + (size_t)(row < NL ? (row >> 13) : 8) * 9216;
;             const float4* sh = (const float4*)(mrow + (3 * s_next) * 1024);
;             const float4* sc = (const float4*)(mrow + (3 * s_next + 1) * 1024);
; #pragma unroll
;             for (int i = 0; i < 4; ++i) { sh4[i] = sh[lane + 64 * i]; sc4[i] = sc[lane + 64 * i]; }
;         }
;         __builtin_amdgcn_sched_barrier(0);
;         if (mode != 0) {
;             float s = 0.f;
; #pragma unroll
;             for (int i = 0; i < 16; ++i) s += v[i];
;             const float mu = wave_sum(s, lane) * (1.f / DM);
;             float q = 0.f;
; #pragma unroll
;             for (int i = 0; i < 16; ++i) { v[i] -= mu; q += v[i] * v[i]; }
;             const float rs = rsqrtf(wave_sum(q, lane) * (1.f / DM) + EPSV);
.LBB0_15:
	s_or_b64 exec, exec, s[14:15]
	v_min_i32_e32 v39, 0x10000, v39
	v_ashrrev_i32_e32 v39, 13, v39
	v_mul_hi_i32_i24_e32 v51, 0x9000, v39
	v_mul_i32_i24_e32 v50, 0x9000, v39
	v_lshl_add_u64 v[50:51], s[54:55], 0, v[50:51]
	s_mov_b64 s[0:1], 0x1000
	v_lshl_add_u64 v[52:53], v[50:51], 0, s[0:1]
	v_mov_b32_e32 v39, v161
	v_mov_b32_e32 v41, v161
	v_mov_b32_e32 v43, v161
	v_lshl_add_u64 v[78:79], v[50:51], 0, v[160:161]
	v_lshl_add_u64 v[50:51], v[52:53], 0, v[160:161]
	v_lshl_add_u64 v[54:55], v[52:53], 0, v[38:39]
	v_lshl_add_u64 v[66:67], v[52:53], 0, v[40:41]
	v_lshl_add_u64 v[70:71], v[52:53], 0, v[42:43]
	global_load_dwordx4 v[50:53], v[50:51], off
	s_nop 0
	global_load_dwordx4 v[54:57], v[54:55], off
	s_nop 0
	global_load_dwordx4 v[58:61], v[78:79], off
	global_load_dwordx4 v[62:65], v[78:79], off offset:1024
	s_nop 0
	global_load_dwordx4 v[66:69], v[66:67], off
	s_nop 0
	global_load_dwordx4 v[70:73], v[70:71], off
	s_nop 0
	global_load_dwordx4 v[74:77], v[78:79], off offset:2048
	s_nop 0
	global_load_dwordx4 v[78:81], v[78:79], off offset:3072
	v_add_f32_e32 v39, 0, v28
	v_add_f32_e32 v39, v29, v39
	v_add_f32_e32 v39, v30, v39
	v_add_f32_e32 v39, v31, v39
	v_add_f32_e32 v39, v20, v39
	v_add_f32_e32 v39, v21, v39
	v_add_f32_e32 v39, v22, v39
	v_add_f32_e32 v39, v23, v39
	v_add_f32_e32 v39, v12, v39
	v_add_f32_e32 v39, v13, v39
	v_add_f32_e32 v39, v14, v39
	v_add_f32_e32 v39, v15, v39
	v_add_f32_e32 v39, v0, v39
	v_add_f32_e32 v39, v1, v39
	v_add_f32_e32 v39, v2, v39
	v_add_f32_e32 v39, v3, v39
	v_mov_b32_e32 v41, v39
	s_nop 1
	v_permlane32_swap_b32_e32 v41, v39
	s_and_b64 s[0:1], exec, vcc
	s_or_b64 s[12:13], s[0:1], s[12:13]
	s_waitcnt lgkmcnt(0)
	v_add_f32_e32 v39, v39, v41
	v_mov_b32_e32 v41, v39
	s_nop 1
	v_permlane16_swap_b32_e32 v41, v39
	s_waitcnt lgkmcnt(0)
	v_add_f32_e32 v39, v39, v41
	s_nop 1
	v_mov_b32_dpp v41, v39 row_ror:8 row_mask:0xf bank_mask:0xf
	s_waitcnt lgkmcnt(0)
	v_add_f32_e32 v39, v39, v41
	s_nop 1
	v_mov_b32_dpp v41, v39 row_ror:4 row_mask:0xf bank_mask:0xf
	s_waitcnt lgkmcnt(0)
	v_add_f32_e32 v39, v39, v41
	s_nop 1
	v_mov_b32_dpp v41, v39 quad_perm:[2,3,0,1] row_mask:0xf bank_mask:0xf
	s_waitcnt lgkmcnt(0)
	v_add_f32_e32 v39, v39, v41
	s_nop 1
	v_mov_b32_dpp v41, v39 quad_perm:[1,0,3,2] row_mask:0xf bank_mask:0xf
	s_waitcnt lgkmcnt(0)
	v_add_f32_e32 v39, v39, v41
	v_mul_f32_e32 v82, 0x3a800000, v39
	v_pk_add_f32 v[30:31], v[30:31], v[82:83] op_sel_hi:[1,0] neg_lo:[0,1] neg_hi:[0,1]
	v_pk_add_f32 v[28:29], v[28:29], v[82:83] op_sel_hi:[1,0] neg_lo:[0,1] neg_hi:[0,1]
	v_pk_add_f32 v[22:23], v[22:23], v[82:83] op_sel_hi:[1,0] neg_lo:[0,1] neg_hi:[0,1]
	v_pk_add_f32 v[20:21], v[20:21], v[82:83] op_sel_hi:[1,0] neg_lo:[0,1] neg_hi:[0,1]
	v_pk_add_f32 v[14:15], v[14:15], v[82:83] op_sel_hi:[1,0] neg_lo:[0,1] neg_hi:[0,1]
	v_pk_add_f32 v[12:13], v[12:13], v[82:83] op_sel_hi:[1,0] neg_lo:[0,1] neg_hi:[0,1]
	v_pk_add_f32 v[2:3], v[2:3], v[82:83] op_sel_hi:[1,0] neg_lo:[0,1] neg_hi:[0,1]
	v_pk_add_f32 v[0:1], v[0:1], v[82:83] op_sel_hi:[1,0] neg_lo:[0,1] neg_hi:[0,1]
	v_pk_mul_f32 v[82:83], v[30:31], v[30:31]
	v_pk_mul_f32 v[84:85], v[28:29], v[28:29]
	v_pk_mul_f32 v[86:87], v[22:23], v[22:23]
	v_pk_mul_f32 v[88:89], v[20:21], v[20:21]
	v_pk_mul_f32 v[90:91], v[14:15], v[14:15]
	v_pk_mul_f32 v[92:93], v[12:13], v[12:13]
	v_pk_mul_f32 v[94:95], v[2:3], v[2:3]
	v_pk_mul_f32 v[96:97], v[0:1], v[0:1]
	s_waitcnt vmcnt(7)
	v_pk_add_f32 v[50:51], v[50:51], 1.0 op_sel_hi:[1,0]
	v_pk_add_f32 v[52:53], v[52:53], 1.0 op_sel_hi:[1,0]
	s_waitcnt vmcnt(6)
; DI unsigned pk_bf16(float a, float b) { f32x2 v = {a, b}; bf16v2 r = __builtin_convertvector(v, bf16v2); return __builtin_bit_cast(unsigned, r); }
; DI float shx(float v, int lane, int m) { return __int_as_float(__builtin_amdgcn_ds_bpermute((lane ^ m) << 2, __float_as_int(v))); }
; DI float wave_sum(float v, int lane) {
; #pragma unroll
;     for (int o = 32; o > 0; o >>= 1) v += shx(v, lane, o);
;     return v;
; }
; DI void ln_phase(const Params& p, int mode, const float* g, const float* bb, const float* modl, int s_next, int nrows) {
;     ...
;         if (mode != 2) {
;             float s = 0.f;
; #pragma unroll
;             for (int i = 0; i < 16; ++i) s += v[i];
;             const float mu = wave_sum(s, lane) * (1.f / DM);
;             float q = 0.f;
; #pragma unroll
;             for (int i = 0; i < 16; ++i) { v[i] -= mu; q += v[i] * v[i]; }
;             const float rs = rsqrtf(wave_sum(q, lane) * (1.f / DM) + EPSV);
;             bf16_t* hrow = p.H + (size_t)row * DM;
; #pragma unroll
;             for (int i = 0; i < 4; ++i) {
;                 const float4 a = sh4[i], c4 = sc4[i];
;                 u32x2 w;
;                 w.x = pk_bf16(v[4 * i] * rs * (1.f + c4.x) + a.x, v[4 * i + 1] * rs * (1.f + c4.y) + a.y);
;                 w.y = pk_bf16(v[4 * i + 2] * rs * (1.f + c4.z) + a.z, v[4 * i + 3] * rs * (1.f + c4.w) + a.w);
;                 ((u32x2*)hrow)[lane + 64 * i] = w;
;             }
;         }
	v_pk_add_f32 v[54:55], v[54:55], 1.0 op_sel_hi:[1,0]
	v_pk_add_f32 v[56:57], v[56:57], 1.0 op_sel_hi:[1,0]
	s_waitcnt vmcnt(3)
	v_pk_add_f32 v[66:67], v[66:67], 1.0 op_sel_hi:[1,0]
	v_pk_add_f32 v[68:69], v[68:69], 1.0 op_sel_hi:[1,0]
	s_waitcnt vmcnt(2)
	v_pk_add_f32 v[70:71], v[70:71], 1.0 op_sel_hi:[1,0]
	v_add_f32_e32 v39, v84, v85
	v_add_f32_e32 v39, v82, v39
	v_add_f32_e32 v39, v83, v39
	v_add_f32_e32 v39, v88, v39
	v_add_f32_e32 v39, v89, v39
	v_add_f32_e32 v39, v86, v39
	v_add_f32_e32 v39, v87, v39
	v_add_f32_e32 v39, v92, v39
	v_add_f32_e32 v39, v93, v39
	v_add_f32_e32 v39, v90, v39
	v_add_f32_e32 v39, v91, v39
	v_add_f32_e32 v39, v96, v39
	v_add_f32_e32 v39, v97, v39
	v_add_f32_e32 v39, v94, v39
	v_add_f32_e32 v39, v95, v39
	v_mov_b32_e32 v41, v39
	s_nop 1
	v_permlane32_swap_b32_e32 v41, v39
	v_pk_add_f32 v[72:73], v[72:73], 1.0 op_sel_hi:[1,0]
	v_lshl_add_u64 v[34:35], v[34:35], 0, s[8:9]
	s_waitcnt lgkmcnt(0)
	v_add_f32_e32 v39, v39, v41
	v_mov_b32_e32 v41, v39
	s_nop 1
	v_permlane16_swap_b32_e32 v41, v39
	s_waitcnt lgkmcnt(0)
	v_add_f32_e32 v39, v39, v41
	s_nop 1
	v_mov_b32_dpp v41, v39 row_ror:8 row_mask:0xf bank_mask:0xf
	s_waitcnt lgkmcnt(0)
	v_add_f32_e32 v39, v39, v41
	s_nop 1
	v_mov_b32_dpp v41, v39 row_ror:4 row_mask:0xf bank_mask:0xf
	s_waitcnt lgkmcnt(0)
	v_add_f32_e32 v39, v39, v41
	s_nop 1
	v_mov_b32_dpp v41, v39 quad_perm:[2,3,0,1] row_mask:0xf bank_mask:0xf
	s_waitcnt lgkmcnt(0)
	v_add_f32_e32 v39, v39, v41
	s_nop 1
	v_mov_b32_dpp v41, v39 quad_perm:[1,0,3,2] row_mask:0xf bank_mask:0xf
	s_waitcnt lgkmcnt(0)
	v_add_f32_e32 v39, v39, v41
	v_fmamk_f32 v39, v39, 0x3a800000, v162
	v_mul_f32_e32 v41, 0x4b800000, v39
	v_cmp_gt_f32_e32 vcc, s74, v39
	s_nop 1
	v_cndmask_b32_e32 v39, v39, v41, vcc
	v_rsq_f32_e32 v39, v39
	s_nop 0
	v_mul_f32_e32 v41, 0x45800000, v39
	v_cndmask_b32_e32 v82, v39, v41, vcc
	v_pk_mul_f32 v[28:29], v[28:29], v[82:83] op_sel_hi:[1,0]
	v_pk_mul_f32 v[30:31], v[30:31], v[82:83] op_sel_hi:[1,0]
	v_pk_mul_f32 v[20:21], v[20:21], v[82:83] op_sel_hi:[1,0]
	v_pk_mul_f32 v[22:23], v[22:23], v[82:83] op_sel_hi:[1,0]
	v_pk_mul_f32 v[12:13], v[12:13], v[82:83] op_sel_hi:[1,0]
	v_pk_mul_f32 v[14:15], v[14:15], v[82:83] op_sel_hi:[1,0]
	v_pk_mul_f32 v[0:1], v[0:1], v[82:83] op_sel_hi:[1,0]
	v_pk_mul_f32 v[2:3], v[2:3], v[82:83] op_sel_hi:[1,0]
	v_pk_fma_f32 v[28:29], v[50:51], v[28:29], v[58:59]
	v_pk_fma_f32 v[30:31], v[52:53], v[30:31], v[60:61]
	v_pk_fma_f32 v[20:21], v[54:55], v[20:21], v[62:63]
	v_pk_fma_f32 v[22:23], v[56:57], v[22:23], v[64:65]
	s_waitcnt vmcnt(1)
	v_pk_fma_f32 v[12:13], v[66:67], v[12:13], v[74:75]
	v_pk_fma_f32 v[14:15], v[68:69], v[14:15], v[76:77]
	s_waitcnt vmcnt(0)
	v_pk_fma_f32 v[0:1], v[70:71], v[0:1], v[78:79]
	v_pk_fma_f32 v[2:3], v[72:73], v[2:3], v[80:81]
	v_cvt_pk_bf16_f32 v28, v28, v29
	v_cvt_pk_bf16_f32 v29, v30, v31
	v_cvt_pk_bf16_f32 v20, v20, v21
	v_cvt_pk_bf16_f32 v21, v22, v23
	v_cvt_pk_bf16_f32 v12, v12, v13
	v_cvt_pk_bf16_f32 v13, v14, v15
	v_cvt_pk_bf16_f32 v0, v0, v1
	v_cvt_pk_bf16_f32 v1, v2, v3
	global_store_dwordx2 v[36:37], v[28:29], off offset:-1024
	global_store_dwordx2 v[36:37], v[20:21], off offset:-512
	global_store_dwordx2 v[36:37], v[12:13], off
	global_store_dwordx2 v[36:37], v[0:1], off offset:512
	v_lshl_add_u64 v[36:37], v[36:37], 0, s[10:11]
	v_mov_b32_e32 v39, v49
	v_mov_b64_e32 v[2:3], v[26:27]
	v_mov_b64_e32 v[0:1], v[24:25]
	v_mov_b64_e32 v[14:15], v[18:19]
	v_mov_b64_e32 v[12:13], v[16:17]
	v_mov_b64_e32 v[22:23], v[10:11]
	v_mov_b64_e32 v[20:21], v[8:9]
	v_mov_b64_e32 v[30:31], v[6:7]
	v_mov_b64_e32 v[28:29], v[4:5]
	s_andn2_b64 exec, exec, s[12:13]
	s_cbranch_execz .LBB0_18

; DI float shx(float v, int lane, int m) { return __int_as_float(__builtin_amdgcn_ds_bpermute((lane ^ m) << 2, __float_as_int(v))); }
; DI float wave_sum(float v, int lane) {
; #pragma unroll
;     for (int o = 32; o > 0; o >>= 1) v += shx(v, lane, o);
;     return v;
; }
; DI void ln_phase(const Params& p, int mode, const float* g, const float* bb, const float* modl, int s_next, int nrows) {
;     ...
; #pragma unroll
;             for (int i = 0; i < 4; ++i) {
;                 v[4 * i] = v[4 * i] * rs * g4[i].x + b4[i].x; v[4 * i + 1] = v[4 * i + 1] * rs * g4[i].y + b4[i].y;
;                 v[4 * i + 2] = v[4 * i + 2] * rs * g4[i].z + b4[i].z; v[4 * i + 3] = v[4 * i + 3] * rs * g4[i].w + b4[i].w;
;             }
;         }
;         if (mode == 2) {
; #pragma unroll
;             for (int i = 0; i < 4; ++i) ((float4*)dst)[lane + 64 * i] = make_float4(v[4 * i], v[4 * i + 1], v[4 * i + 2], v[4 * i + 3]);
;         }
;         if (mode != 2) {
;             float s = 0.f;
; #pragma unroll
;             for (int i = 0; i < 16; ++i) s += v[i];
;             const float mu = wave_sum(s, lane) * (1.f / DM);
.LBB0_340:
	s_or_b64 exec, exec, s[4:5]
	v_pk_mul_f32 v[60:61], v[60:61], v[112:113] op_sel_hi:[1,0]
	v_pk_mul_f32 v[62:63], v[62:63], v[112:113] op_sel_hi:[1,0]
	v_pk_fma_f32 v[60:61], v[0:1], v[60:61], v[8:9]
	v_pk_fma_f32 v[62:63], v[2:3], v[62:63], v[10:11]
	v_add_f32_e32 v105, 0, v60
	v_add_f32_e32 v105, v61, v105
	v_pk_mul_f32 v[56:57], v[56:57], v[112:113] op_sel_hi:[1,0]
	v_add_f32_e32 v105, v62, v105
	v_add_f32_e32 v105, v63, v105
	v_pk_fma_f32 v[56:57], v[4:5], v[56:57], v[12:13]
	v_pk_mul_f32 v[58:59], v[58:59], v[112:113] op_sel_hi:[1,0]
	v_add_f32_e32 v105, v56, v105
	v_pk_fma_f32 v[58:59], v[6:7], v[58:59], v[14:15]
	v_add_f32_e32 v105, v57, v105
	v_pk_mul_f32 v[52:53], v[52:53], v[112:113] op_sel_hi:[1,0]
	v_add_f32_e32 v105, v58, v105
	v_add_f32_e32 v105, v59, v105
	v_pk_fma_f32 v[52:53], v[16:17], v[52:53], v[24:25]
	v_pk_mul_f32 v[54:55], v[54:55], v[112:113] op_sel_hi:[1,0]
	v_add_f32_e32 v105, v52, v105
	v_pk_fma_f32 v[54:55], v[18:19], v[54:55], v[26:27]
	v_add_f32_e32 v105, v53, v105
	v_pk_mul_f32 v[48:49], v[48:49], v[112:113] op_sel_hi:[1,0]
	v_add_f32_e32 v105, v54, v105
	v_pk_fma_f32 v[48:49], v[20:21], v[48:49], v[28:29]
	v_add_f32_e32 v105, v55, v105
	v_pk_mul_f32 v[50:51], v[50:51], v[112:113] op_sel_hi:[1,0]
	v_add_f32_e32 v105, v48, v105
	v_pk_fma_f32 v[50:51], v[22:23], v[50:51], v[30:31]
	v_add_f32_e32 v105, v49, v105
	v_add_f32_e32 v105, v50, v105
	v_add_f32_e32 v105, v51, v105
	v_mov_b32_e32 v107, v105
	s_nop 1
	v_permlane32_swap_b32_e32 v107, v105
	s_and_b64 s[4:5], exec, s[0:1]
	s_waitcnt vmcnt(5)
	v_pk_add_f32 v[88:89], v[88:89], 1.0 op_sel_hi:[1,0]
	v_pk_add_f32 v[90:91], v[90:91], 1.0 op_sel_hi:[1,0]
	s_waitcnt vmcnt(4)
	v_pk_add_f32 v[84:85], v[84:85], 1.0 op_sel_hi:[1,0]
	s_waitcnt lgkmcnt(0)
	v_add_f32_e32 v105, v105, v107
	v_mov_b32_e32 v107, v105
	s_nop 1
	v_permlane16_swap_b32_e32 v107, v105
	v_pk_add_f32 v[86:87], v[86:87], 1.0 op_sel_hi:[1,0]
	s_waitcnt vmcnt(0)
	v_pk_add_f32 v[92:93], v[92:93], 1.0 op_sel_hi:[1,0]
	v_pk_add_f32 v[94:95], v[94:95], 1.0 op_sel_hi:[1,0]
	v_pk_add_f32 v[80:81], v[80:81], 1.0 op_sel_hi:[1,0]
	s_waitcnt lgkmcnt(0)
	v_add_f32_e32 v105, v105, v107
	s_nop 1
	v_mov_b32_dpp v107, v105 row_ror:8 row_mask:0xf bank_mask:0xf
	v_pk_add_f32 v[82:83], v[82:83], 1.0 op_sel_hi:[1,0]
	s_or_b64 s[20:21], s[4:5], s[20:21]
	v_lshl_add_u64 v[98:99], v[98:99], 0, s[12:13]
	v_lshl_add_u64 v[100:101], v[100:101], 0, s[16:17]
	s_waitcnt lgkmcnt(0)
	v_add_f32_e32 v105, v105, v107
	s_nop 1
	v_mov_b32_dpp v107, v105 row_ror:4 row_mask:0xf bank_mask:0xf
	s_waitcnt lgkmcnt(0)
	v_add_f32_e32 v105, v105, v107
	s_nop 1
	v_mov_b32_dpp v107, v105 quad_perm:[2,3,0,1] row_mask:0xf bank_mask:0xf
	s_waitcnt lgkmcnt(0)
	v_add_f32_e32 v105, v105, v107
	s_nop 1
	v_mov_b32_dpp v107, v105 quad_perm:[1,0,3,2] row_mask:0xf bank_mask:0xf
	s_waitcnt lgkmcnt(0)
; DI unsigned pk_bf16(float a, float b) { f32x2 v = {a, b}; bf16v2 r = __builtin_convertvector(v, bf16v2); return __builtin_bit_cast(unsigned, r); }
; DI void ln_phase(const Params& p, int mode, const float* g, const float* bb, const float* modl, int s_next, int nrows) {
;     ...
;             const float mu = wave_sum(s, lane) * (1.f / DM);
;             float q = 0.f;
; #pragma unroll
;             for (int i = 0; i < 16; ++i) { v[i] -= mu; q += v[i] * v[i]; }
;             const float rs = rsqrtf(wave_sum(q, lane) * (1.f / DM) + EPSV);
;             bf16_t* hrow = p.H + (size_t)row * DM;
; #pragma unroll
;             for (int i = 0; i < 4; ++i) {
;                 const float4 a = sh4[i], c4 = sc4[i];
;                 u32x2 w;
;                 w.x = pk_bf16(v[4 * i] * rs * (1.f + c4.x) + a.x, v[4 * i + 1] * rs * (1.f + c4.y) + a.y);
;                 w.y = pk_bf16(v[4 * i + 2] * rs * (1.f + c4.z) + a.z, v[4 * i + 3] * rs * (1.f + c4.w) + a.w);
;                 ((u32x2*)hrow)[lane + 64 * i] = w;
;             }
	v_add_f32_e32 v105, v105, v107
	v_mul_f32_e32 v110, 0x3a800000, v105
	v_pk_add_f32 v[60:61], v[60:61], v[110:111] op_sel_hi:[1,0] neg_lo:[0,1] neg_hi:[0,1]
	v_pk_add_f32 v[62:63], v[62:63], v[110:111] op_sel_hi:[1,0] neg_lo:[0,1] neg_hi:[0,1]
	v_pk_mul_f32 v[120:121], v[60:61], v[60:61]
	v_pk_mul_f32 v[122:123], v[62:63], v[62:63]
	v_add_f32_e32 v105, v120, v121
	v_pk_add_f32 v[56:57], v[56:57], v[110:111] op_sel_hi:[1,0] neg_lo:[0,1] neg_hi:[0,1]
	v_add_f32_e32 v105, v122, v105
	v_pk_mul_f32 v[124:125], v[56:57], v[56:57]
	v_add_f32_e32 v105, v123, v105
	v_pk_add_f32 v[58:59], v[58:59], v[110:111] op_sel_hi:[1,0] neg_lo:[0,1] neg_hi:[0,1]
	v_add_f32_e32 v105, v124, v105
	v_pk_mul_f32 v[126:127], v[58:59], v[58:59]
	v_add_f32_e32 v105, v125, v105
	v_pk_add_f32 v[52:53], v[52:53], v[110:111] op_sel_hi:[1,0] neg_lo:[0,1] neg_hi:[0,1]
	v_add_f32_e32 v105, v126, v105
	v_pk_mul_f32 v[128:129], v[52:53], v[52:53]
	v_add_f32_e32 v105, v127, v105
	v_pk_add_f32 v[54:55], v[54:55], v[110:111] op_sel_hi:[1,0] neg_lo:[0,1] neg_hi:[0,1]
	v_add_f32_e32 v105, v128, v105
	v_pk_mul_f32 v[130:131], v[54:55], v[54:55]
	v_add_f32_e32 v105, v129, v105
	v_pk_add_f32 v[48:49], v[48:49], v[110:111] op_sel_hi:[1,0] neg_lo:[0,1] neg_hi:[0,1]
	v_add_f32_e32 v105, v130, v105
	v_pk_add_f32 v[50:51], v[50:51], v[110:111] op_sel_hi:[1,0] neg_lo:[0,1] neg_hi:[0,1]
	v_pk_mul_f32 v[110:111], v[48:49], v[48:49]
	v_add_f32_e32 v105, v131, v105
	v_add_f32_e32 v105, v110, v105
	v_pk_mul_f32 v[132:133], v[50:51], v[50:51]
	v_add_f32_e32 v105, v111, v105
	v_add_f32_e32 v105, v132, v105
	v_add_f32_e32 v105, v133, v105
	v_mov_b32_e32 v107, v105
	s_nop 1
	v_permlane32_swap_b32_e32 v107, v105
	s_waitcnt lgkmcnt(0)
	v_add_f32_e32 v105, v105, v107
	v_mov_b32_e32 v107, v105
	s_nop 1
	v_permlane16_swap_b32_e32 v107, v105
	s_waitcnt lgkmcnt(0)
	v_add_f32_e32 v105, v105, v107
	s_nop 1
	v_mov_b32_dpp v107, v105 row_ror:8 row_mask:0xf bank_mask:0xf
	s_waitcnt lgkmcnt(0)
	v_add_f32_e32 v105, v105, v107
	s_nop 1
	v_mov_b32_dpp v107, v105 row_ror:4 row_mask:0xf bank_mask:0xf
	s_waitcnt lgkmcnt(0)
	v_add_f32_e32 v105, v105, v107
	s_nop 1
	v_mov_b32_dpp v107, v105 quad_perm:[2,3,0,1] row_mask:0xf bank_mask:0xf
	s_waitcnt lgkmcnt(0)
	v_add_f32_e32 v105, v105, v107
	s_nop 1
	v_mov_b32_dpp v107, v105 quad_perm:[1,0,3,2] row_mask:0xf bank_mask:0xf
	s_waitcnt lgkmcnt(0)
	v_add_f32_e32 v105, v105, v107
	v_fmamk_f32 v105, v105, 0x3a800000, v162
	v_mul_f32_e32 v107, 0x4b800000, v105
	v_cmp_gt_f32_e64 s[0:1], s42, v105
	s_nop 1
	v_cndmask_b32_e64 v105, v105, v107, s[0:1]
	v_rsq_f32_e32 v105, v105
	s_nop 0
	v_mul_f32_e32 v107, 0x45800000, v105
	v_cndmask_b32_e64 v110, v105, v107, s[0:1]
	v_pk_mul_f32 v[60:61], v[60:61], v[110:111] op_sel_hi:[1,0]
	v_pk_mul_f32 v[62:63], v[62:63], v[110:111] op_sel_hi:[1,0]
	v_pk_mul_f32 v[56:57], v[56:57], v[110:111] op_sel_hi:[1,0]
	v_pk_mul_f32 v[58:59], v[58:59], v[110:111] op_sel_hi:[1,0]
	v_pk_mul_f32 v[52:53], v[52:53], v[110:111] op_sel_hi:[1,0]
	v_pk_mul_f32 v[54:55], v[54:55], v[110:111] op_sel_hi:[1,0]
	v_pk_mul_f32 v[48:49], v[48:49], v[110:111] op_sel_hi:[1,0]
	v_pk_mul_f32 v[50:51], v[50:51], v[110:111] op_sel_hi:[1,0]
	v_pk_fma_f32 v[60:61], v[88:89], v[60:61], v[68:69]
	v_pk_fma_f32 v[62:63], v[90:91], v[62:63], v[70:71]
	v_pk_fma_f32 v[56:57], v[84:85], v[56:57], v[76:77]
	v_pk_fma_f32 v[58:59], v[86:87], v[58:59], v[78:79]
	v_pk_fma_f32 v[52:53], v[92:93], v[52:53], v[72:73]
	v_pk_fma_f32 v[54:55], v[94:95], v[54:55], v[74:75]
	v_pk_fma_f32 v[48:49], v[80:81], v[48:49], v[64:65]
	v_pk_fma_f32 v[50:51], v[82:83], v[50:51], v[66:67]
	v_cvt_pk_bf16_f32 v60, v60, v61
	v_cvt_pk_bf16_f32 v61, v62, v63
	v_cvt_pk_bf16_f32 v56, v56, v57
	v_cvt_pk_bf16_f32 v57, v58, v59
	v_cvt_pk_bf16_f32 v52, v52, v53
	v_cvt_pk_bf16_f32 v53, v54, v55
	v_cvt_pk_bf16_f32 v48, v48, v49
	v_cvt_pk_bf16_f32 v49, v50, v51
	global_store_dwordx2 v[102:103], v[60:61], off offset:-1024
	global_store_dwordx2 v[102:103], v[56:57], off offset:-512
	global_store_dwordx2 v[102:103], v[52:53], off
	global_store_dwordx2 v[102:103], v[48:49], off offset:512
	v_lshl_add_u64 v[102:103], v[102:103], 0, s[18:19]
	v_mov_b32_e32 v64, v118
	v_mov_b64_e32 v[62:63], v[34:35]
	v_mov_b64_e32 v[60:61], v[32:33]
	v_mov_b64_e32 v[50:51], v[46:47]
	v_mov_b64_e32 v[48:49], v[44:45]
	v_mov_b64_e32 v[58:59], v[38:39]
	v_mov_b64_e32 v[56:57], v[36:37]
	v_mov_b64_e32 v[54:55], v[42:43]
	v_mov_b64_e32 v[52:53], v[40:41]
	s_andn2_b64 exec, exec, s[20:21]
	s_cbranch_execz .LBB0_345

; DI void ln_phase(const Params& p, int mode, const float* g, const float* bb, const float* modl, int s_next, int nrows) {
;     ...
;             const float* mrow = modl + (size_t)(row < NL ? (row >> 13) : 8) * 9216;
;             const float4* sh = (const float4*)(mrow + (3 * s_next) * 1024);
;             const float4* sc = (const float4*)(mrow + (3 * s_next + 1) * 1024);
; #pragma unroll
;             for (int i = 0; i < 4; ++i) { sh4[i] = sh[lane + 64 * i]; sc4[i] = sc[lane + 64 * i]; }
;         }
;         __builtin_amdgcn_sched_barrier(0);
;         if (mode != 0) {
;             float s = 0.f;
; #pragma unroll
;             for (int i = 0; i < 16; ++i) s += v[i];
;             const float mu = wave_sum(s, lane) * (1.f / DM);
;             float q = 0.f;
; #pragma unroll
;             for (int i = 0; i < 16; ++i) { v[i] -= mu; q += v[i] * v[i]; }
;             const float rs = rsqrtf(wave_sum(q, lane) * (1.f / DM) + EPSV);
;             if (mode == 1 && lane == 0) *(f32x2*)(p.STATS + (size_t)row * 2) = (f32x2){mu, rs};
.LBB0_343:
	s_or_b64 exec, exec, s[22:23]
	v_min_i32_e32 v64, 0x10000, v64
	v_ashrrev_i32_e32 v64, 13, v64
	v_mul_hi_i32_i24_e32 v65, 0x9000, v64
	v_mul_i32_i24_e32 v64, 0x9000, v64
	v_lshl_add_u64 v[64:65], s[14:15], 0, v[64:65]
	s_mov_b64 s[4:5], 0x1000
	v_lshl_add_u64 v[66:67], v[64:65], 0, s[4:5]
	v_mov_b32_e32 v105, v161
	v_mov_b32_e32 v107, v161
	v_mov_b32_e32 v109, v161
	v_lshl_add_u64 v[72:73], v[64:65], 0, v[160:161]
	v_lshl_add_u64 v[64:65], v[66:67], 0, v[160:161]
	v_lshl_add_u64 v[74:75], v[66:67], 0, v[104:105]
	v_lshl_add_u64 v[92:93], v[66:67], 0, v[106:107]
	v_lshl_add_u64 v[80:81], v[66:67], 0, v[108:109]
	global_load_dwordx4 v[68:71], v[72:73], off
	global_load_dwordx4 v[76:79], v[72:73], off offset:1024
	global_load_dwordx4 v[88:91], v[64:65], off
	global_load_dwordx4 v[84:87], v[74:75], off
	s_nop 0
	global_load_dwordx4 v[64:67], v[72:73], off offset:3072
	s_nop 0
	global_load_dwordx4 v[72:75], v[72:73], off offset:2048
	s_nop 0
	global_load_dwordx4 v[80:83], v[80:81], off
	s_nop 0
	global_load_dwordx4 v[92:95], v[92:93], off
	v_add_f32_e32 v105, 0, v60
	v_add_f32_e32 v105, v61, v105
	v_add_f32_e32 v105, v62, v105
	v_add_f32_e32 v105, v63, v105
	v_add_f32_e32 v105, v56, v105
	v_add_f32_e32 v105, v57, v105
	v_add_f32_e32 v105, v58, v105
	v_add_f32_e32 v105, v59, v105
	v_add_f32_e32 v105, v52, v105
	v_add_f32_e32 v105, v53, v105
	v_add_f32_e32 v105, v54, v105
	v_add_f32_e32 v105, v55, v105
	v_add_f32_e32 v105, v48, v105
	v_add_f32_e32 v105, v49, v105
	v_add_f32_e32 v105, v50, v105
	v_add_f32_e32 v105, v51, v105
	v_mov_b32_e32 v107, v105
	s_nop 1
	v_permlane32_swap_b32_e32 v107, v105
	s_waitcnt lgkmcnt(0)
	v_add_f32_e32 v105, v105, v107
	v_mov_b32_e32 v107, v105
	s_nop 1
	v_permlane16_swap_b32_e32 v107, v105
	s_waitcnt lgkmcnt(0)
	v_add_f32_e32 v105, v105, v107
	s_nop 1
	v_mov_b32_dpp v107, v105 row_ror:8 row_mask:0xf bank_mask:0xf
	s_waitcnt lgkmcnt(0)
	v_add_f32_e32 v105, v105, v107
	s_nop 1
	v_mov_b32_dpp v107, v105 row_ror:4 row_mask:0xf bank_mask:0xf
	s_waitcnt lgkmcnt(0)
	v_add_f32_e32 v105, v105, v107
	s_nop 1
	v_mov_b32_dpp v107, v105 quad_perm:[2,3,0,1] row_mask:0xf bank_mask:0xf
	s_waitcnt lgkmcnt(0)
	v_add_f32_e32 v105, v105, v107
	s_nop 1
	v_mov_b32_dpp v107, v105 quad_perm:[1,0,3,2] row_mask:0xf bank_mask:0xf
	s_waitcnt lgkmcnt(0)
	v_add_f32_e32 v105, v105, v107
	v_mul_f32_e32 v110, 0x3a800000, v105
	v_pk_add_f32 v[60:61], v[60:61], v[110:111] op_sel_hi:[1,0] neg_lo:[0,1] neg_hi:[0,1]
	v_pk_add_f32 v[62:63], v[62:63], v[110:111] op_sel_hi:[1,0] neg_lo:[0,1] neg_hi:[0,1]
	v_pk_add_f32 v[56:57], v[56:57], v[110:111] op_sel_hi:[1,0] neg_lo:[0,1] neg_hi:[0,1]
	v_pk_add_f32 v[58:59], v[58:59], v[110:111] op_sel_hi:[1,0] neg_lo:[0,1] neg_hi:[0,1]
	v_pk_add_f32 v[52:53], v[52:53], v[110:111] op_sel_hi:[1,0] neg_lo:[0,1] neg_hi:[0,1]
	v_pk_mul_f32 v[120:121], v[60:61], v[60:61]
	v_pk_mul_f32 v[122:123], v[62:63], v[62:63]
	v_pk_mul_f32 v[124:125], v[56:57], v[56:57]
	v_pk_mul_f32 v[126:127], v[58:59], v[58:59]
	v_pk_mul_f32 v[128:129], v[52:53], v[52:53]
	v_add_f32_e32 v105, v120, v121
	v_add_f32_e32 v105, v122, v105
	v_add_f32_e32 v105, v123, v105
	v_add_f32_e32 v105, v124, v105
	v_add_f32_e32 v105, v125, v105
	v_add_f32_e32 v105, v126, v105
	v_add_f32_e32 v105, v127, v105
	v_pk_add_f32 v[54:55], v[54:55], v[110:111] op_sel_hi:[1,0] neg_lo:[0,1] neg_hi:[0,1]
	v_add_f32_e32 v105, v128, v105
	v_pk_mul_f32 v[130:131], v[54:55], v[54:55]
	v_add_f32_e32 v105, v129, v105
	v_pk_add_f32 v[48:49], v[48:49], v[110:111] op_sel_hi:[1,0] neg_lo:[0,1] neg_hi:[0,1]
	v_add_f32_e32 v105, v130, v105
	v_pk_mul_f32 v[132:133], v[48:49], v[48:49]
	v_add_f32_e32 v105, v131, v105
	v_pk_add_f32 v[50:51], v[50:51], v[110:111] op_sel_hi:[1,0] neg_lo:[0,1] neg_hi:[0,1]
	v_add_f32_e32 v105, v132, v105
	v_pk_mul_f32 v[134:135], v[50:51], v[50:51]
	v_add_f32_e32 v105, v133, v105
	v_add_f32_e32 v105, v134, v105
	v_add_f32_e32 v105, v135, v105
	v_mov_b32_e32 v107, v105
	s_nop 1
	v_permlane32_swap_b32_e32 v107, v105
	s_waitcnt lgkmcnt(0)
	v_add_f32_e32 v105, v105, v107
	v_mov_b32_e32 v107, v105
	s_nop 1
	v_permlane16_swap_b32_e32 v107, v105
	s_waitcnt lgkmcnt(0)
	v_add_f32_e32 v105, v105, v107
	s_nop 1
	v_mov_b32_dpp v107, v105 row_ror:8 row_mask:0xf bank_mask:0xf
	s_waitcnt lgkmcnt(0)
	v_add_f32_e32 v105, v105, v107
	s_nop 1
	v_mov_b32_dpp v107, v105 row_ror:4 row_mask:0xf bank_mask:0xf
	s_waitcnt lgkmcnt(0)
	v_add_f32_e32 v105, v105, v107
	s_nop 1
	v_mov_b32_dpp v107, v105 quad_perm:[2,3,0,1] row_mask:0xf bank_mask:0xf
	s_waitcnt lgkmcnt(0)
	v_add_f32_e32 v105, v105, v107
	s_nop 1
	v_mov_b32_dpp v107, v105 quad_perm:[1,0,3,2] row_mask:0xf bank_mask:0xf
	s_waitcnt lgkmcnt(0)
	v_add_f32_e32 v105, v105, v107
	v_fmamk_f32 v105, v105, 0x3a800000, v162
	v_mul_f32_e32 v107, 0x4b800000, v105
	v_cmp_gt_f32_e64 s[4:5], s42, v105
	s_nop 1
	v_cndmask_b32_e64 v105, v105, v107, s[4:5]
	v_rsq_f32_e32 v105, v105
	s_nop 0
	v_mul_f32_e32 v107, 0x45800000, v105
	v_cndmask_b32_e64 v112, v105, v107, s[4:5]
	s_and_saveexec_b64 s[4:5], vcc
	s_cbranch_execz .LBB0_340
	v_mov_b32_e32 v111, v112
	global_store_dwordx2 v[100:101], v[110:111], off
	s_branch .LBB0_340

; DI float shx(float v, int lane, int m) { return __int_as_float(__builtin_amdgcn_ds_bpermute((lane ^ m) << 2, __float_as_int(v))); }
; DI float wave_sum(float v, int lane) {
; #pragma unroll
;     for (int o = 32; o > 0; o >>= 1) v += shx(v, lane, o);
;     return v;
; }
; DI void ln_phase(const Params& p, int mode, const float* g, const float* bb, const float* modl, int s_next, int nrows) {
;     ...
; #pragma unroll
;             for (int i = 0; i < 4; ++i) {
;                 v[4 * i] = v[4 * i] * rs * g4[i].x + b4[i].x; v[4 * i + 1] = v[4 * i + 1] * rs * g4[i].y + b4[i].y;
;                 v[4 * i + 2] = v[4 * i + 2] * rs * g4[i].z + b4[i].z; v[4 * i + 3] = v[4 * i + 3] * rs * g4[i].w + b4[i].w;
;             }
;         }
;         if (mode == 2) {
; #pragma unroll
;             for (int i = 0; i < 4; ++i) ((float4*)dst)[lane + 64 * i] = make_float4(v[4 * i], v[4 * i + 1], v[4 * i + 2], v[4 * i + 3]);
;         }
;         if (mode != 2) {
;             float s = 0.f;
; #pragma unroll
;             for (int i = 0; i < 16; ++i) s += v[i];
;             const float mu = wave_sum(s, lane) * (1.f / DM);
.LBB0_349:
	s_or_b64 exec, exec, s[4:5]
	v_pk_mul_f32 v[60:61], v[60:61], v[112:113] op_sel_hi:[1,0]
	v_pk_mul_f32 v[62:63], v[62:63], v[112:113] op_sel_hi:[1,0]
	v_pk_fma_f32 v[60:61], v[0:1], v[60:61], v[8:9]
	v_pk_fma_f32 v[62:63], v[2:3], v[62:63], v[10:11]
	v_add_f32_e32 v105, 0, v60
	v_add_f32_e32 v105, v61, v105
	v_pk_mul_f32 v[56:57], v[56:57], v[112:113] op_sel_hi:[1,0]
	v_add_f32_e32 v105, v62, v105
	v_add_f32_e32 v105, v63, v105
	v_pk_fma_f32 v[56:57], v[4:5], v[56:57], v[12:13]
	v_pk_mul_f32 v[58:59], v[58:59], v[112:113] op_sel_hi:[1,0]
	v_add_f32_e32 v105, v56, v105
	v_pk_fma_f32 v[58:59], v[6:7], v[58:59], v[14:15]
	v_add_f32_e32 v105, v57, v105
	v_pk_mul_f32 v[52:53], v[52:53], v[112:113] op_sel_hi:[1,0]
	v_add_f32_e32 v105, v58, v105
	v_add_f32_e32 v105, v59, v105
	v_pk_fma_f32 v[52:53], v[16:17], v[52:53], v[24:25]
	v_pk_mul_f32 v[54:55], v[54:55], v[112:113] op_sel_hi:[1,0]
	v_add_f32_e32 v105, v52, v105
	v_pk_fma_f32 v[54:55], v[18:19], v[54:55], v[26:27]
	v_add_f32_e32 v105, v53, v105
	v_pk_mul_f32 v[48:49], v[48:49], v[112:113] op_sel_hi:[1,0]
	v_add_f32_e32 v105, v54, v105
	v_pk_fma_f32 v[48:49], v[20:21], v[48:49], v[28:29]
	v_add_f32_e32 v105, v55, v105
	v_pk_mul_f32 v[50:51], v[50:51], v[112:113] op_sel_hi:[1,0]
	v_add_f32_e32 v105, v48, v105
	v_pk_fma_f32 v[50:51], v[22:23], v[50:51], v[30:31]
	v_add_f32_e32 v105, v49, v105
	v_add_f32_e32 v105, v50, v105
	v_add_f32_e32 v105, v51, v105
	v_mov_b32_e32 v107, v105
	s_nop 1
	v_permlane32_swap_b32_e32 v107, v105
	s_and_b64 s[4:5], exec, s[0:1]
	s_waitcnt vmcnt(5)
	v_pk_add_f32 v[88:89], v[88:89], 1.0 op_sel_hi:[1,0]
	v_pk_add_f32 v[90:91], v[90:91], 1.0 op_sel_hi:[1,0]
	s_waitcnt vmcnt(4)
	v_pk_add_f32 v[84:85], v[84:85], 1.0 op_sel_hi:[1,0]
	s_waitcnt lgkmcnt(0)
	v_add_f32_e32 v105, v105, v107
	v_mov_b32_e32 v107, v105
	s_nop 1
	v_permlane16_swap_b32_e32 v107, v105
	v_pk_add_f32 v[86:87], v[86:87], 1.0 op_sel_hi:[1,0]
	s_waitcnt vmcnt(0)
	v_pk_add_f32 v[92:93], v[92:93], 1.0 op_sel_hi:[1,0]
	v_pk_add_f32 v[94:95], v[94:95], 1.0 op_sel_hi:[1,0]
	v_pk_add_f32 v[80:81], v[80:81], 1.0 op_sel_hi:[1,0]
	s_waitcnt lgkmcnt(0)
	v_add_f32_e32 v105, v105, v107
	s_nop 1
	v_mov_b32_dpp v107, v105 row_ror:8 row_mask:0xf bank_mask:0xf
	v_pk_add_f32 v[82:83], v[82:83], 1.0 op_sel_hi:[1,0]
	s_or_b64 s[20:21], s[4:5], s[20:21]
	v_lshl_add_u64 v[98:99], v[98:99], 0, s[14:15]
	v_lshl_add_u64 v[100:101], v[100:101], 0, s[16:17]
	s_waitcnt lgkmcnt(0)
	v_add_f32_e32 v105, v105, v107
	s_nop 1
	v_mov_b32_dpp v107, v105 row_ror:4 row_mask:0xf bank_mask:0xf
	s_waitcnt lgkmcnt(0)
	v_add_f32_e32 v105, v105, v107
	s_nop 1
	v_mov_b32_dpp v107, v105 quad_perm:[2,3,0,1] row_mask:0xf bank_mask:0xf
	s_waitcnt lgkmcnt(0)
	v_add_f32_e32 v105, v105, v107
	s_nop 1
	v_mov_b32_dpp v107, v105 quad_perm:[1,0,3,2] row_mask:0xf bank_mask:0xf
	s_waitcnt lgkmcnt(0)
; DI unsigned pk_bf16(float a, float b) { f32x2 v = {a, b}; bf16v2 r = __builtin_convertvector(v, bf16v2); return __builtin_bit_cast(unsigned, r); }
; DI void ln_phase(const Params& p, int mode, const float* g, const float* bb, const float* modl, int s_next, int nrows) {
;     ...
;             const float mu = wave_sum(s, lane) * (1.f / DM);
;             float q = 0.f;
; #pragma unroll
;             for (int i = 0; i < 16; ++i) { v[i] -= mu; q += v[i] * v[i]; }
;             const float rs = rsqrtf(wave_sum(q, lane) * (1.f / DM) + EPSV);
;             bf16_t* hrow = p.H + (size_t)row * DM;
; #pragma unroll
;             for (int i = 0; i < 4; ++i) {
;                 const float4 a = sh4[i], c4 = sc4[i];
;                 u32x2 w;
;                 w.x = pk_bf16(v[4 * i] * rs * (1.f + c4.x) + a.x, v[4 * i + 1] * rs * (1.f + c4.y) + a.y);
;                 w.y = pk_bf16(v[4 * i + 2] * rs * (1.f + c4.z) + a.z, v[4 * i + 3] * rs * (1.f + c4.w) + a.w);
;                 ((u32x2*)hrow)[lane + 64 * i] = w;
;             }
	v_add_f32_e32 v105, v105, v107
	v_mul_f32_e32 v110, 0x3a800000, v105
	v_pk_add_f32 v[60:61], v[60:61], v[110:111] op_sel_hi:[1,0] neg_lo:[0,1] neg_hi:[0,1]
	v_pk_add_f32 v[62:63], v[62:63], v[110:111] op_sel_hi:[1,0] neg_lo:[0,1] neg_hi:[0,1]
	v_pk_mul_f32 v[120:121], v[60:61], v[60:61]
	v_pk_mul_f32 v[122:123], v[62:63], v[62:63]
	v_add_f32_e32 v105, v120, v121
	v_pk_add_f32 v[56:57], v[56:57], v[110:111] op_sel_hi:[1,0] neg_lo:[0,1] neg_hi:[0,1]
	v_add_f32_e32 v105, v122, v105
	v_pk_mul_f32 v[124:125], v[56:57], v[56:57]
	v_add_f32_e32 v105, v123, v105
	v_pk_add_f32 v[58:59], v[58:59], v[110:111] op_sel_hi:[1,0] neg_lo:[0,1] neg_hi:[0,1]
	v_add_f32_e32 v105, v124, v105
	v_pk_mul_f32 v[126:127], v[58:59], v[58:59]
	v_add_f32_e32 v105, v125, v105
	v_pk_add_f32 v[52:53], v[52:53], v[110:111] op_sel_hi:[1,0] neg_lo:[0,1] neg_hi:[0,1]
	v_add_f32_e32 v105, v126, v105
	v_pk_mul_f32 v[128:129], v[52:53], v[52:53]
	v_add_f32_e32 v105, v127, v105
	v_pk_add_f32 v[54:55], v[54:55], v[110:111] op_sel_hi:[1,0] neg_lo:[0,1] neg_hi:[0,1]
	v_add_f32_e32 v105, v128, v105
	v_pk_mul_f32 v[130:131], v[54:55], v[54:55]
	v_add_f32_e32 v105, v129, v105
	v_pk_add_f32 v[48:49], v[48:49], v[110:111] op_sel_hi:[1,0] neg_lo:[0,1] neg_hi:[0,1]
	v_add_f32_e32 v105, v130, v105
	v_pk_add_f32 v[50:51], v[50:51], v[110:111] op_sel_hi:[1,0] neg_lo:[0,1] neg_hi:[0,1]
	v_pk_mul_f32 v[110:111], v[48:49], v[48:49]
	v_add_f32_e32 v105, v131, v105
	v_add_f32_e32 v105, v110, v105
	v_pk_mul_f32 v[132:133], v[50:51], v[50:51]
	v_add_f32_e32 v105, v111, v105
	v_add_f32_e32 v105, v132, v105
	v_add_f32_e32 v105, v133, v105
	v_mov_b32_e32 v107, v105
	s_nop 1
	v_permlane32_swap_b32_e32 v107, v105
	s_waitcnt lgkmcnt(0)
	v_add_f32_e32 v105, v105, v107
	v_mov_b32_e32 v107, v105
	s_nop 1
	v_permlane16_swap_b32_e32 v107, v105
	s_waitcnt lgkmcnt(0)
	v_add_f32_e32 v105, v105, v107
	s_nop 1
	v_mov_b32_dpp v107, v105 row_ror:8 row_mask:0xf bank_mask:0xf
	s_waitcnt lgkmcnt(0)
	v_add_f32_e32 v105, v105, v107
	s_nop 1
	v_mov_b32_dpp v107, v105 row_ror:4 row_mask:0xf bank_mask:0xf
	s_waitcnt lgkmcnt(0)
	v_add_f32_e32 v105, v105, v107
	s_nop 1
	v_mov_b32_dpp v107, v105 quad_perm:[2,3,0,1] row_mask:0xf bank_mask:0xf
	s_waitcnt lgkmcnt(0)
	v_add_f32_e32 v105, v105, v107
	s_nop 1
	v_mov_b32_dpp v107, v105 quad_perm:[1,0,3,2] row_mask:0xf bank_mask:0xf
	s_waitcnt lgkmcnt(0)
	v_add_f32_e32 v105, v105, v107
	v_fmamk_f32 v105, v105, 0x3a800000, v162
	v_mul_f32_e32 v107, 0x4b800000, v105
	v_cmp_gt_f32_e64 s[0:1], s42, v105
	s_nop 1
	v_cndmask_b32_e64 v105, v105, v107, s[0:1]
	v_rsq_f32_e32 v105, v105
	s_nop 0
	v_mul_f32_e32 v107, 0x45800000, v105
	v_cndmask_b32_e64 v110, v105, v107, s[0:1]
	v_pk_mul_f32 v[60:61], v[60:61], v[110:111] op_sel_hi:[1,0]
	v_pk_mul_f32 v[62:63], v[62:63], v[110:111] op_sel_hi:[1,0]
	v_pk_mul_f32 v[56:57], v[56:57], v[110:111] op_sel_hi:[1,0]
	v_pk_mul_f32 v[58:59], v[58:59], v[110:111] op_sel_hi:[1,0]
	v_pk_mul_f32 v[52:53], v[52:53], v[110:111] op_sel_hi:[1,0]
	v_pk_mul_f32 v[54:55], v[54:55], v[110:111] op_sel_hi:[1,0]
	v_pk_mul_f32 v[48:49], v[48:49], v[110:111] op_sel_hi:[1,0]
	v_pk_mul_f32 v[50:51], v[50:51], v[110:111] op_sel_hi:[1,0]
	v_pk_fma_f32 v[60:61], v[88:89], v[60:61], v[68:69]
	v_pk_fma_f32 v[62:63], v[90:91], v[62:63], v[70:71]
	v_pk_fma_f32 v[56:57], v[84:85], v[56:57], v[76:77]
	v_pk_fma_f32 v[58:59], v[86:87], v[58:59], v[78:79]
	v_pk_fma_f32 v[52:53], v[92:93], v[52:53], v[72:73]
	v_pk_fma_f32 v[54:55], v[94:95], v[54:55], v[74:75]
	v_pk_fma_f32 v[48:49], v[80:81], v[48:49], v[64:65]
	v_pk_fma_f32 v[50:51], v[82:83], v[50:51], v[66:67]
	v_cvt_pk_bf16_f32 v60, v60, v61
	v_cvt_pk_bf16_f32 v61, v62, v63
	v_cvt_pk_bf16_f32 v56, v56, v57
	v_cvt_pk_bf16_f32 v57, v58, v59
	v_cvt_pk_bf16_f32 v52, v52, v53
	v_cvt_pk_bf16_f32 v53, v54, v55
	v_cvt_pk_bf16_f32 v48, v48, v49
	v_cvt_pk_bf16_f32 v49, v50, v51
	global_store_dwordx2 v[102:103], v[60:61], off offset:-1024
	global_store_dwordx2 v[102:103], v[56:57], off offset:-512
	global_store_dwordx2 v[102:103], v[52:53], off
	global_store_dwordx2 v[102:103], v[48:49], off offset:512
	v_lshl_add_u64 v[102:103], v[102:103], 0, s[18:19]
	v_mov_b32_e32 v64, v118
	v_mov_b64_e32 v[62:63], v[34:35]
	v_mov_b64_e32 v[60:61], v[32:33]
	v_mov_b64_e32 v[50:51], v[46:47]
	v_mov_b64_e32 v[48:49], v[44:45]
	v_mov_b64_e32 v[58:59], v[38:39]
	v_mov_b64_e32 v[56:57], v[36:37]
	v_mov_b64_e32 v[54:55], v[42:43]
	v_mov_b64_e32 v[52:53], v[40:41]
	s_andn2_b64 exec, exec, s[20:21]
	s_cbranch_execz .LBB0_354

; DI void ln_phase(const Params& p, int mode, const float* g, const float* bb, const float* modl, int s_next, int nrows) {
;     ...
;             const float* mrow = modl + (size_t)(row < NL ? (row >> 13) : 8) * 9216;
;             const float4* sh = (const float4*)(mrow + (3 * s_next) * 1024);
;             const float4* sc = (const float4*)(mrow + (3 * s_next + 1) * 1024);
; #pragma unroll
;             for (int i = 0; i < 4; ++i) { sh4[i] = sh[lane + 64 * i]; sc4[i] = sc[lane + 64 * i]; }
;         }
;         __builtin_amdgcn_sched_barrier(0);
;         if (mode != 0) {
;             float s = 0.f;
; #pragma unroll
;             for (int i = 0; i < 16; ++i) s += v[i];
;             const float mu = wave_sum(s, lane) * (1.f / DM);
;             float q = 0.f;
; #pragma unroll
;             for (int i = 0; i < 16; ++i) { v[i] -= mu; q += v[i] * v[i]; }
;             const float rs = rsqrtf(wave_sum(q, lane) * (1.f / DM) + EPSV);
;             if (mode == 1 && lane == 0) *(f32x2*)(p.STATS + (size_t)row * 2) = (f32x2){mu, rs};
.LBB0_352:
	s_or_b64 exec, exec, s[22:23]
	v_min_i32_e32 v64, 0x10000, v64
	v_ashrrev_i32_e32 v64, 13, v64
	v_mul_hi_i32_i24_e32 v65, 0x9000, v64
	v_mul_i32_i24_e32 v64, 0x9000, v64
	v_lshl_add_u64 v[64:65], s[12:13], 0, v[64:65]
	s_mov_b64 s[4:5], 0x1000
	v_lshl_add_u64 v[66:67], v[64:65], 0, s[4:5]
	v_mov_b32_e32 v105, v161
	v_mov_b32_e32 v107, v161
	v_mov_b32_e32 v109, v161
	v_lshl_add_u64 v[72:73], v[64:65], 0, v[160:161]
	v_lshl_add_u64 v[64:65], v[66:67], 0, v[160:161]
	v_lshl_add_u64 v[74:75], v[66:67], 0, v[104:105]
	v_lshl_add_u64 v[92:93], v[66:67], 0, v[106:107]
	v_lshl_add_u64 v[80:81], v[66:67], 0, v[108:109]
	global_load_dwordx4 v[68:71], v[72:73], off
	global_load_dwordx4 v[76:79], v[72:73], off offset:1024
	global_load_dwordx4 v[88:91], v[64:65], off
	global_load_dwordx4 v[84:87], v[74:75], off
	s_nop 0
	global_load_dwordx4 v[64:67], v[72:73], off offset:3072
	s_nop 0
	global_load_dwordx4 v[72:75], v[72:73], off offset:2048
	s_nop 0
	global_load_dwordx4 v[80:83], v[80:81], off
	s_nop 0
	global_load_dwordx4 v[92:95], v[92:93], off
	v_add_f32_e32 v105, 0, v60
	v_add_f32_e32 v105, v61, v105
	v_add_f32_e32 v105, v62, v105
	v_add_f32_e32 v105, v63, v105
	v_add_f32_e32 v105, v56, v105
	v_add_f32_e32 v105, v57, v105
	v_add_f32_e32 v105, v58, v105
	v_add_f32_e32 v105, v59, v105
	v_add_f32_e32 v105, v52, v105
	v_add_f32_e32 v105, v53, v105
	v_add_f32_e32 v105, v54, v105
	v_add_f32_e32 v105, v55, v105
	v_add_f32_e32 v105, v48, v105
	v_add_f32_e32 v105, v49, v105
	v_add_f32_e32 v105, v50, v105
	v_add_f32_e32 v105, v51, v105
	v_mov_b32_e32 v107, v105
	s_nop 1
	v_permlane32_swap_b32_e32 v107, v105
	s_waitcnt lgkmcnt(0)
	v_add_f32_e32 v105, v105, v107
	v_mov_b32_e32 v107, v105
	s_nop 1
	v_permlane16_swap_b32_e32 v107, v105
	s_waitcnt lgkmcnt(0)
	v_add_f32_e32 v105, v105, v107
	s_nop 1
	v_mov_b32_dpp v107, v105 row_ror:8 row_mask:0xf bank_mask:0xf
	s_waitcnt lgkmcnt(0)
	v_add_f32_e32 v105, v105, v107
	s_nop 1
	v_mov_b32_dpp v107, v105 row_ror:4 row_mask:0xf bank_mask:0xf
	s_waitcnt lgkmcnt(0)
	v_add_f32_e32 v105, v105, v107
	s_nop 1
	v_mov_b32_dpp v107, v105 quad_perm:[2,3,0,1] row_mask:0xf bank_mask:0xf
	s_waitcnt lgkmcnt(0)
	v_add_f32_e32 v105, v105, v107
	s_nop 1
	v_mov_b32_dpp v107, v105 quad_perm:[1,0,3,2] row_mask:0xf bank_mask:0xf
	s_waitcnt lgkmcnt(0)
	v_add_f32_e32 v105, v105, v107
	v_mul_f32_e32 v110, 0x3a800000, v105
	v_pk_add_f32 v[60:61], v[60:61], v[110:111] op_sel_hi:[1,0] neg_lo:[0,1] neg_hi:[0,1]
	v_pk_add_f32 v[62:63], v[62:63], v[110:111] op_sel_hi:[1,0] neg_lo:[0,1] neg_hi:[0,1]
	v_pk_add_f32 v[56:57], v[56:57], v[110:111] op_sel_hi:[1,0] neg_lo:[0,1] neg_hi:[0,1]
	v_pk_add_f32 v[58:59], v[58:59], v[110:111] op_sel_hi:[1,0] neg_lo:[0,1] neg_hi:[0,1]
	v_pk_add_f32 v[52:53], v[52:53], v[110:111] op_sel_hi:[1,0] neg_lo:[0,1] neg_hi:[0,1]
	v_pk_mul_f32 v[120:121], v[60:61], v[60:61]
	v_pk_mul_f32 v[122:123], v[62:63], v[62:63]
	v_pk_mul_f32 v[124:125], v[56:57], v[56:57]
	v_pk_mul_f32 v[126:127], v[58:59], v[58:59]
	v_pk_mul_f32 v[128:129], v[52:53], v[52:53]
	v_add_f32_e32 v105, v120, v121
	v_add_f32_e32 v105, v122, v105
	v_add_f32_e32 v105, v123, v105
	v_add_f32_e32 v105, v124, v105
	v_add_f32_e32 v105, v125, v105
	v_add_f32_e32 v105, v126, v105
	v_add_f32_e32 v105, v127, v105
	v_pk_add_f32 v[54:55], v[54:55], v[110:111] op_sel_hi:[1,0] neg_lo:[0,1] neg_hi:[0,1]
	v_add_f32_e32 v105, v128, v105
	v_pk_mul_f32 v[130:131], v[54:55], v[54:55]
	v_add_f32_e32 v105, v129, v105
	v_pk_add_f32 v[48:49], v[48:49], v[110:111] op_sel_hi:[1,0] neg_lo:[0,1] neg_hi:[0,1]
	v_add_f32_e32 v105, v130, v105
	v_pk_mul_f32 v[132:133], v[48:49], v[48:49]
	v_add_f32_e32 v105, v131, v105
	v_pk_add_f32 v[50:51], v[50:51], v[110:111] op_sel_hi:[1,0] neg_lo:[0,1] neg_hi:[0,1]
	v_add_f32_e32 v105, v132, v105
	v_pk_mul_f32 v[134:135], v[50:51], v[50:51]
	v_add_f32_e32 v105, v133, v105
	v_add_f32_e32 v105, v134, v105
	v_add_f32_e32 v105, v135, v105
	v_mov_b32_e32 v107, v105
	s_nop 1
	v_permlane32_swap_b32_e32 v107, v105
	s_waitcnt lgkmcnt(0)
	v_add_f32_e32 v105, v105, v107
	v_mov_b32_e32 v107, v105
	s_nop 1
	v_permlane16_swap_b32_e32 v107, v105
	s_waitcnt lgkmcnt(0)
	v_add_f32_e32 v105, v105, v107
	s_nop 1
	v_mov_b32_dpp v107, v105 row_ror:8 row_mask:0xf bank_mask:0xf
	s_waitcnt lgkmcnt(0)
	v_add_f32_e32 v105, v105, v107
	s_nop 1
	v_mov_b32_dpp v107, v105 row_ror:4 row_mask:0xf bank_mask:0xf
	s_waitcnt lgkmcnt(0)
	v_add_f32_e32 v105, v105, v107
	s_nop 1
	v_mov_b32_dpp v107, v105 quad_perm:[2,3,0,1] row_mask:0xf bank_mask:0xf
	s_waitcnt lgkmcnt(0)
	v_add_f32_e32 v105, v105, v107
	s_nop 1
	v_mov_b32_dpp v107, v105 quad_perm:[1,0,3,2] row_mask:0xf bank_mask:0xf
	s_waitcnt lgkmcnt(0)
	v_add_f32_e32 v105, v105, v107
	v_fmamk_f32 v105, v105, 0x3a800000, v162
	v_mul_f32_e32 v107, 0x4b800000, v105
	v_cmp_gt_f32_e64 s[4:5], s42, v105
	s_nop 1
	v_cndmask_b32_e64 v105, v105, v107, s[4:5]
	v_rsq_f32_e32 v105, v105
	s_nop 0
	v_mul_f32_e32 v107, 0x45800000, v105
	v_cndmask_b32_e64 v112, v105, v107, s[4:5]
	s_and_saveexec_b64 s[4:5], vcc
	s_cbranch_execz .LBB0_349
	v_mov_b32_e32 v111, v112
	global_store_dwordx2 v[100:101], v[110:111], off
	s_branch .LBB0_349

; DI void ln_phase(const Params& p, int mode, const float* g, const float* bb, const float* modl, int s_next, int nrows) {
;     ...
;         if (mode != 0) {
;             float s = 0.f;
; #pragma unroll
;             for (int i = 0; i < 16; ++i) s += v[i];
;             const float mu = wave_sum(s, lane) * (1.f / DM);
;             float q = 0.f;
; #pragma unroll
;             for (int i = 0; i < 16; ++i) { v[i] -= mu; q += v[i] * v[i]; }
;             const float rs = rsqrtf(wave_sum(q, lane) * (1.f / DM) + EPSV);
;             if (mode == 1 && lane == 0) *(f32x2*)(p.STATS + (size_t)row * 2) = (f32x2){mu, rs};
; #pragma unroll
;             for (int i = 0; i < 4; ++i) {
;                 v[4 * i] = v[4 * i] * rs * g4[i].x + b4[i].x; v[4 * i + 1] = v[4 * i + 1] * rs * g4[i].y + b4[i].y;
;                 v[4 * i + 2] = v[4 * i + 2] * rs * g4[i].z + b4[i].z; v[4 * i + 3] = v[4 * i + 3] * rs * g4[i].w + b4[i].w;
;             }
;         }
;         if (mode == 2) {
; #pragma unroll
;             for (int i = 0; i < 4; ++i) ((float4*)dst)[lane + 64 * i] = make_float4(v[4 * i], v[4 * i + 1], v[4 * i + 2], v[4 * i + 3]);
.LBB0_359:
	s_or_b64 exec, exec, s[12:13]
	s_and_b64 s[0:1], exec, vcc
	s_or_b64 s[10:11], s[0:1], s[10:11]
	v_add_f32_e32 v75, 0, v52
	v_add_f32_e32 v75, v53, v75
	v_add_f32_e32 v75, v54, v75
	v_add_f32_e32 v75, v55, v75
	v_add_f32_e32 v75, v44, v75
	v_add_f32_e32 v75, v45, v75
	v_add_f32_e32 v75, v46, v75
	v_add_f32_e32 v75, v47, v75
	v_add_f32_e32 v75, v36, v75
	v_add_f32_e32 v75, v37, v75
	v_add_f32_e32 v75, v38, v75
	v_add_f32_e32 v75, v39, v75
	v_add_f32_e32 v75, v32, v75
	v_add_f32_e32 v75, v33, v75
	v_add_f32_e32 v75, v34, v75
	v_add_f32_e32 v75, v35, v75
	v_mov_b32_e32 v76, v75
	s_nop 1
	v_permlane32_swap_b32_e32 v76, v75
	v_lshl_add_u64 v[92:93], v[66:67], 0, v[160:161]
	v_lshl_add_u64 v[68:69], v[68:69], 0, s[8:9]
	v_lshl_add_u64 v[66:67], v[66:67], 0, s[8:9]
	s_waitcnt lgkmcnt(0)
	v_add_f32_e32 v75, v75, v76
	v_mov_b32_e32 v76, v75
	s_nop 1
	v_permlane16_swap_b32_e32 v76, v75
	s_waitcnt lgkmcnt(0)
	v_add_f32_e32 v75, v75, v76
	s_nop 1
	v_mov_b32_dpp v76, v75 row_ror:8 row_mask:0xf bank_mask:0xf
	s_waitcnt lgkmcnt(0)
	v_add_f32_e32 v75, v75, v76
	s_nop 1
	v_mov_b32_dpp v76, v75 row_ror:4 row_mask:0xf bank_mask:0xf
	s_waitcnt lgkmcnt(0)
	v_add_f32_e32 v75, v75, v76
	s_nop 1
	v_mov_b32_dpp v76, v75 quad_perm:[2,3,0,1] row_mask:0xf bank_mask:0xf
	s_waitcnt lgkmcnt(0)
	v_add_f32_e32 v75, v75, v76
	s_nop 1
	v_mov_b32_dpp v76, v75 quad_perm:[1,0,3,2] row_mask:0xf bank_mask:0xf
	s_waitcnt lgkmcnt(0)
	v_add_f32_e32 v75, v75, v76
	v_mul_f32_e32 v76, 0x3a800000, v75
	v_pk_add_f32 v[78:79], v[52:53], v[76:77] op_sel_hi:[1,0] neg_lo:[0,1] neg_hi:[0,1]
	v_pk_add_f32 v[80:81], v[54:55], v[76:77] op_sel_hi:[1,0] neg_lo:[0,1] neg_hi:[0,1]
	v_pk_add_f32 v[90:91], v[32:33], v[76:77] op_sel_hi:[1,0] neg_lo:[0,1] neg_hi:[0,1]
	v_pk_mul_f32 v[32:33], v[78:79], v[78:79]
	v_pk_add_f32 v[86:87], v[36:37], v[76:77] op_sel_hi:[1,0] neg_lo:[0,1] neg_hi:[0,1]
	v_pk_mul_f32 v[36:37], v[80:81], v[80:81]
	v_add_f32_e32 v32, v32, v33
	v_pk_add_f32 v[82:83], v[44:45], v[76:77] op_sel_hi:[1,0] neg_lo:[0,1] neg_hi:[0,1]
	v_add_f32_e32 v32, v36, v32
	v_pk_add_f32 v[88:89], v[38:39], v[76:77] op_sel_hi:[1,0] neg_lo:[0,1] neg_hi:[0,1]
	v_pk_mul_f32 v[38:39], v[82:83], v[82:83]
	v_add_f32_e32 v32, v37, v32
	v_pk_add_f32 v[84:85], v[46:47], v[76:77] op_sel_hi:[1,0] neg_lo:[0,1] neg_hi:[0,1]
	v_add_f32_e32 v32, v38, v32
	v_pk_mul_f32 v[44:45], v[84:85], v[84:85]
	v_add_f32_e32 v32, v39, v32
	v_add_f32_e32 v32, v44, v32
	v_pk_mul_f32 v[46:47], v[86:87], v[86:87]
	v_add_f32_e32 v32, v45, v32
	v_add_f32_e32 v32, v46, v32
	v_pk_mul_f32 v[52:53], v[88:89], v[88:89]
	v_add_f32_e32 v32, v47, v32
	v_add_f32_e32 v32, v52, v32
	v_pk_mul_f32 v[54:55], v[90:91], v[90:91]
	v_add_f32_e32 v32, v53, v32
	v_pk_add_f32 v[34:35], v[34:35], v[76:77] op_sel_hi:[1,0] neg_lo:[0,1] neg_hi:[0,1]
	v_add_f32_e32 v32, v54, v32
	v_pk_mul_f32 v[76:77], v[34:35], v[34:35]
	v_add_f32_e32 v32, v55, v32
	v_add_f32_e32 v32, v76, v32
	v_add_f32_e32 v32, v77, v32
	v_mov_b32_e32 v33, v32
	s_nop 1
	v_permlane32_swap_b32_e32 v33, v32
	s_waitcnt vmcnt(3)
	v_mov_b64_e32 v[52:53], v[48:49]
	v_mov_b64_e32 v[54:55], v[50:51]
	s_waitcnt vmcnt(2)
	v_mov_b64_e32 v[44:45], v[56:57]
	v_mov_b64_e32 v[46:47], v[58:59]
	s_waitcnt lgkmcnt(0)
	v_add_f32_e32 v32, v32, v33
	v_mov_b32_e32 v33, v32
	s_nop 1
	v_permlane16_swap_b32_e32 v33, v32
	s_waitcnt vmcnt(1)
	v_mov_b64_e32 v[36:37], v[60:61]
	v_mov_b64_e32 v[38:39], v[62:63]
	s_waitcnt lgkmcnt(0)
	v_add_f32_e32 v32, v32, v33
	s_nop 1
	v_mov_b32_dpp v33, v32 row_ror:8 row_mask:0xf bank_mask:0xf
	s_waitcnt lgkmcnt(0)
	v_add_f32_e32 v32, v32, v33
	s_nop 1
	v_mov_b32_dpp v33, v32 row_ror:4 row_mask:0xf bank_mask:0xf
	s_waitcnt lgkmcnt(0)
	v_add_f32_e32 v32, v32, v33
	s_nop 1
	v_mov_b32_dpp v33, v32 quad_perm:[2,3,0,1] row_mask:0xf bank_mask:0xf
	s_waitcnt lgkmcnt(0)
	v_add_f32_e32 v32, v32, v33
	s_nop 1
	v_mov_b32_dpp v33, v32 quad_perm:[1,0,3,2] row_mask:0xf bank_mask:0xf
	s_waitcnt lgkmcnt(0)
	v_add_f32_e32 v32, v32, v33
	v_fmamk_f32 v32, v32, 0x3a800000, v162
	v_mul_f32_e32 v33, 0x4b800000, v32
	v_cmp_gt_f32_e32 vcc, s42, v32
	s_nop 1
	v_cndmask_b32_e32 v32, v32, v33, vcc
	v_rsq_f32_e32 v48, v32
	s_waitcnt vmcnt(0)
	v_mov_b64_e32 v[32:33], v[40:41]
	v_mul_f32_e32 v40, 0x45800000, v48
	v_cndmask_b32_e32 v40, v48, v40, vcc
	v_pk_mul_f32 v[48:49], v[78:79], v[40:41] op_sel_hi:[1,0]
	v_pk_mul_f32 v[50:51], v[80:81], v[40:41] op_sel_hi:[1,0]
	v_pk_mul_f32 v[34:35], v[34:35], v[40:41] op_sel_hi:[1,0]
	v_pk_mul_f32 v[56:57], v[82:83], v[40:41] op_sel_hi:[1,0]
	v_pk_mul_f32 v[58:59], v[84:85], v[40:41] op_sel_hi:[1,0]
	v_pk_mul_f32 v[60:61], v[86:87], v[40:41] op_sel_hi:[1,0]
	v_pk_mul_f32 v[62:63], v[88:89], v[40:41] op_sel_hi:[1,0]
	v_pk_mul_f32 v[76:77], v[90:91], v[40:41] op_sel_hi:[1,0]
	v_pk_fma_f32 v[48:49], v[0:1], v[48:49], v[8:9]
	v_pk_fma_f32 v[50:51], v[2:3], v[50:51], v[10:11]
	v_pk_fma_f32 v[78:79], v[22:23], v[34:35], v[30:31]
	v_mov_b64_e32 v[34:35], v[42:43]
	v_pk_fma_f32 v[56:57], v[4:5], v[56:57], v[12:13]
	v_pk_fma_f32 v[58:59], v[6:7], v[58:59], v[14:15]
	v_pk_fma_f32 v[60:61], v[16:17], v[60:61], v[24:25]
	v_pk_fma_f32 v[62:63], v[18:19], v[62:63], v[26:27]
	v_pk_fma_f32 v[76:77], v[20:21], v[76:77], v[28:29]
	global_store_dwordx4 v[92:93], v[48:51], off
	global_store_dwordx4 v[92:93], v[56:59], off offset:1024
	global_store_dwordx4 v[92:93], v[60:63], off offset:2048
	global_store_dwordx4 v[92:93], v[76:79], off offset:3072
	s_andn2_b64 exec, exec, s[10:11]
	s_cbranch_execz .LBB0_362

; template <class Epi>
; DI void gemm_phase(const bf16_t* A, const bf16_t* Bt, int K, int mtiles, int ntiles, const Epi& epi, char* smem) {
;     ...
;         for (int kt = 0; kt < nk; ++kt) {
;             const int cur = kt & 1;
;             const bf16_t* a_ = sA + cur * 256 * 72 + (wr * 128 + r) * 72 + 8 * h;
;             const bf16_t* b_ = sB + cur * 256 * 72 + (wc * 64 + r) * 72 + 8 * h;
;             bf16_t* wa = sA + (cur ^ 1) * 256 * 72 + srow * 72 + skc; bf16_t* wb = sB + (cur ^ 1) * 256 * 72 + srow * 72 + skc;
;     ...
;             GEMM_KS(0) GEMM_KS(1)
;             __builtin_amdgcn_sched_barrier(0);
;             if (kt + 1 < nk) {
; #pragma unroll
;                 for (int i = 0; i < 4; ++i) *(u32x4*)(wa + 64 * i * 72) = ra[i];
;             }
;             if (kt + 2 < nk) {
; #pragma unroll
;                 for (int i = 0; i < 4; ++i) ra[i] = *(const u32x4*)(Ag + (size_t)(64 * i) * K + (kt + 2) * 64);
;             }
;             GEMM_KS(2)
;             __builtin_amdgcn_sched_barrier(0);
;             if (kt + 1 < nk) {
; #pragma unroll
;                 for (int i = 0; i < 4; ++i) *(u32x4*)(wb + 64 * i * 72) = rb[i];
;             }
;             if (kt + 2 < nk) {
; #pragma unroll
;                 for (int i = 0; i < 4; ++i) rb[i] = *(const u32x4*)(Bg + (size_t)(64 * i) * K + (kt + 2) * 64);
;             }
;             GEMM_KS(3)
;     ...
;             __syncthreads();
;         }
.Lsw_kloop:
	global_load_dwordx4 v[156:159], v[138:139], off offset:128
	global_load_dwordx4 v[174:177], v[142:143], off offset:128
	global_load_dwordx4 v[182:185], v[144:145], off offset:128
	global_load_dwordx4 v[190:193], v[146:147], off offset:128
	global_load_dwordx4 v[170:173], v[132:133], off offset:128
	global_load_dwordx4 v[178:181], v[134:135], off offset:128
	global_load_dwordx4 v[186:189], v[136:137], off offset:128
	global_load_dwordx4 v[194:197], v[140:141], off offset:128
	s_waitcnt lgkmcnt(0)
	s_barrier
	ds_read_b128 v[198:201], v152
	ds_read_b128 v[244:247], v151 offset:9216
	ds_read_b128 v[202:205], v152 offset:4608
	ds_read_b128 v[248:251], v151 offset:13824
	ds_read_b128 v[206:209], v151
	ds_read_b128 v[210:213], v151 offset:4608
	s_waitcnt lgkmcnt(4)
	v_mfma_f32_32x32x16_bf16 v[32:47], v[244:247], v[198:201], 0
	ds_read_b128 v[214:217], v152 offset:32
	ds_read_b128 v[218:221], v152 offset:4640
	s_waitcnt lgkmcnt(5)
	v_mfma_f32_32x32x16_bf16 v[48:63], v[244:247], v[202:205], 0
	ds_read_b128 v[244:247], v151 offset:9248
	s_waitcnt lgkmcnt(5)
	v_mfma_f32_32x32x16_bf16 v[0:15], v[248:251], v[198:201], 0
	ds_read_b128 v[222:225], v151 offset:32
	v_mfma_f32_32x32x16_bf16 v[16:31], v[248:251], v[202:205], 0
	ds_read_b128 v[248:251], v151 offset:13856
	s_waitcnt lgkmcnt(6)
	v_mfma_f32_32x32x16_bf16 v[112:127], v[206:209], v[198:201], 0
	ds_read_b128 v[240:243], v151 offset:4640
	s_waitcnt vmcnt(7)
	ds_write_b128 v153, v[156:159] offset:36864
	global_load_dwordx4 v[156:159], v[138:139], off offset:256
	v_mfma_f32_32x32x16_bf16 v[96:111], v[206:209], v[202:205], 0
	s_waitcnt vmcnt(7)
	ds_write_b128 v153, v[174:177] offset:46080
	global_load_dwordx4 v[174:177], v[142:143], off offset:256
	s_waitcnt lgkmcnt(8)
	v_mfma_f32_32x32x16_bf16 v[64:79], v[210:213], v[198:201], 0
	s_waitcnt vmcnt(7)
	ds_write_b128 v153, v[182:185] offset:55296
	global_load_dwordx4 v[182:185], v[144:145], off offset:256
	v_mfma_f32_32x32x16_bf16 v[80:95], v[210:213], v[202:205], 0
	s_waitcnt vmcnt(7)
	ds_write_b128 v153, v[190:193] offset:64512
	global_load_dwordx4 v[190:193], v[146:147], off offset:256
	s_waitcnt lgkmcnt(7)
	v_mfma_f32_32x32x16_bf16 v[32:47], v[244:247], v[214:217], v[32:47]
	ds_read_b128 v[198:201], v152 offset:64
	ds_read_b128 v[202:205], v152 offset:4672
	v_mfma_f32_32x32x16_bf16 v[48:63], v[244:247], v[218:221], v[48:63]
	ds_read_b128 v[244:247], v151 offset:9280
	s_waitcnt lgkmcnt(8)
	v_mfma_f32_32x32x16_bf16 v[0:15], v[248:251], v[214:217], v[0:15]
	ds_read_b128 v[206:209], v151 offset:64
	v_mfma_f32_32x32x16_bf16 v[16:31], v[248:251], v[218:221], v[16:31]
	ds_read_b128 v[248:251], v151 offset:13888
	v_mfma_f32_32x32x16_bf16 v[112:127], v[222:225], v[214:217], v[112:127]
	ds_read_b128 v[210:213], v151 offset:4672
	s_waitcnt vmcnt(7)
	ds_write_b128 v154, v[170:173] offset:36864
	global_load_dwordx4 v[170:173], v[132:133], off offset:256
	v_mfma_f32_32x32x16_bf16 v[96:111], v[222:225], v[218:221], v[96:111]
	s_waitcnt vmcnt(7)
	ds_write_b128 v154, v[178:181] offset:46080
	global_load_dwordx4 v[178:181], v[134:135], off offset:256
	s_waitcnt lgkmcnt(12)
	v_mfma_f32_32x32x16_bf16 v[64:79], v[240:243], v[214:217], v[64:79]
	s_waitcnt vmcnt(7)
	ds_write_b128 v154, v[186:189] offset:55296
	global_load_dwordx4 v[186:189], v[136:137], off offset:256
	v_mfma_f32_32x32x16_bf16 v[80:95], v[240:243], v[218:221], v[80:95]
	s_waitcnt vmcnt(7)
	ds_write_b128 v154, v[194:197] offset:64512
	global_load_dwordx4 v[194:197], v[140:141], off offset:256
	s_waitcnt lgkmcnt(7)
	v_mfma_f32_32x32x16_bf16 v[32:47], v[244:247], v[198:201], v[32:47]
	ds_read_b128 v[214:217], v152 offset:96
	ds_read_b128 v[218:221], v152 offset:4704
	v_mfma_f32_32x32x16_bf16 v[48:63], v[244:247], v[202:205], v[48:63]
	ds_read_b128 v[244:247], v151 offset:9312
	s_waitcnt lgkmcnt(8)
	v_mfma_f32_32x32x16_bf16 v[0:15], v[248:251], v[198:201], v[0:15]
	ds_read_b128 v[222:225], v151 offset:96
	v_mfma_f32_32x32x16_bf16 v[16:31], v[248:251], v[202:205], v[16:31]
	ds_read_b128 v[248:251], v151 offset:13920
	v_mfma_f32_32x32x16_bf16 v[112:127], v[206:209], v[198:201], v[112:127]
	ds_read_b128 v[240:243], v151 offset:4704
	v_mfma_f32_32x32x16_bf16 v[96:111], v[206:209], v[202:205], v[96:111]
	s_waitcnt lgkmcnt(10)
	v_mfma_f32_32x32x16_bf16 v[64:79], v[210:213], v[198:201], v[64:79]
	v_mfma_f32_32x32x16_bf16 v[80:95], v[210:213], v[202:205], v[80:95]
	s_waitcnt lgkmcnt(0)
	s_barrier
; template <class Epi>
; DI void gemm_phase(const bf16_t* A, const bf16_t* Bt, int K, int mtiles, int ntiles, const Epi& epi, char* smem) {
;     ...
;         for (int kt = 0; kt < nk; ++kt) {
;             const int cur = kt & 1;
;             const bf16_t* a_ = sA + cur * 256 * 72 + (wr * 128 + r) * 72 + 8 * h;
;             const bf16_t* b_ = sB + cur * 256 * 72 + (wc * 64 + r) * 72 + 8 * h;
;             bf16_t* wa = sA + (cur ^ 1) * 256 * 72 + srow * 72 + skc; bf16_t* wb = sB + (cur ^ 1) * 256 * 72 + srow * 72 + skc;
;     ...
;             GEMM_KS(0) GEMM_KS(1)
;             __builtin_amdgcn_sched_barrier(0);
;             if (kt + 1 < nk) {
; #pragma unroll
;                 for (int i = 0; i < 4; ++i) *(u32x4*)(wa + 64 * i * 72) = ra[i];
;             }
;             if (kt + 2 < nk) {
; #pragma unroll
;                 for (int i = 0; i < 4; ++i) ra[i] = *(const u32x4*)(Ag + (size_t)(64 * i) * K + (kt + 2) * 64);
;             }
;             GEMM_KS(2)
;             __builtin_amdgcn_sched_barrier(0);
;             if (kt + 1 < nk) {
; #pragma unroll
;                 for (int i = 0; i < 4; ++i) *(u32x4*)(wb + 64 * i * 72) = rb[i];
;             }
;             if (kt + 2 < nk) {
; #pragma unroll
;                 for (int i = 0; i < 4; ++i) rb[i] = *(const u32x4*)(Bg + (size_t)(64 * i) * K + (kt + 2) * 64);
;             }
;             GEMM_KS(3)
;     ...
;             __syncthreads();
;         }
	v_mfma_f32_32x32x16_bf16 v[32:47], v[244:247], v[214:217], v[32:47]
	ds_read_b128 v[198:201], v152 offset:36864
	ds_read_b128 v[202:205], v152 offset:41472
	v_mfma_f32_32x32x16_bf16 v[48:63], v[244:247], v[218:221], v[48:63]
	ds_read_b128 v[244:247], v151 offset:46080
	v_mfma_f32_32x32x16_bf16 v[0:15], v[248:251], v[214:217], v[0:15]
	ds_read_b128 v[206:209], v151 offset:36864
	v_mfma_f32_32x32x16_bf16 v[16:31], v[248:251], v[218:221], v[16:31]
	ds_read_b128 v[248:251], v151 offset:50688
	v_mfma_f32_32x32x16_bf16 v[112:127], v[222:225], v[214:217], v[112:127]
	ds_read_b128 v[210:213], v151 offset:41472
	v_mfma_f32_32x32x16_bf16 v[96:111], v[222:225], v[218:221], v[96:111]
	v_mfma_f32_32x32x16_bf16 v[64:79], v[240:243], v[214:217], v[64:79]
	v_mfma_f32_32x32x16_bf16 v[80:95], v[240:243], v[218:221], v[80:95]
	s_waitcnt lgkmcnt(3)
	v_mfma_f32_32x32x16_bf16 v[32:47], v[244:247], v[198:201], v[32:47]
	ds_read_b128 v[214:217], v152 offset:36896
	ds_read_b128 v[218:221], v152 offset:41504
	v_mfma_f32_32x32x16_bf16 v[48:63], v[244:247], v[202:205], v[48:63]
	ds_read_b128 v[244:247], v151 offset:46112
	s_waitcnt lgkmcnt(4)
	v_mfma_f32_32x32x16_bf16 v[0:15], v[248:251], v[198:201], v[0:15]
	ds_read_b128 v[222:225], v151 offset:36896
	v_mfma_f32_32x32x16_bf16 v[16:31], v[248:251], v[202:205], v[16:31]
	ds_read_b128 v[248:251], v151 offset:50720
	v_mfma_f32_32x32x16_bf16 v[112:127], v[206:209], v[198:201], v[112:127]
	ds_read_b128 v[240:243], v151 offset:41504
	s_waitcnt vmcnt(7)
	ds_write_b128 v153, v[156:159] offset:0
	global_load_dwordx4 v[156:159], v[138:139], off offset:384
	v_mfma_f32_32x32x16_bf16 v[96:111], v[206:209], v[202:205], v[96:111]
	s_waitcnt vmcnt(7)
	ds_write_b128 v153, v[174:177] offset:9216
	global_load_dwordx4 v[174:177], v[142:143], off offset:384
	s_waitcnt lgkmcnt(8)
	v_mfma_f32_32x32x16_bf16 v[64:79], v[210:213], v[198:201], v[64:79]
	s_waitcnt vmcnt(7)
	ds_write_b128 v153, v[182:185] offset:18432
	global_load_dwordx4 v[182:185], v[144:145], off offset:384
	v_mfma_f32_32x32x16_bf16 v[80:95], v[210:213], v[202:205], v[80:95]
	s_waitcnt vmcnt(7)
	ds_write_b128 v153, v[190:193] offset:27648
	global_load_dwordx4 v[190:193], v[146:147], off offset:384
	s_waitcnt lgkmcnt(7)
	v_mfma_f32_32x32x16_bf16 v[32:47], v[244:247], v[214:217], v[32:47]
	ds_read_b128 v[198:201], v152 offset:36928
	ds_read_b128 v[202:205], v152 offset:41536
	v_mfma_f32_32x32x16_bf16 v[48:63], v[244:247], v[218:221], v[48:63]
	ds_read_b128 v[244:247], v151 offset:46144
	s_waitcnt lgkmcnt(8)
	v_mfma_f32_32x32x16_bf16 v[0:15], v[248:251], v[214:217], v[0:15]
	ds_read_b128 v[206:209], v151 offset:36928
	v_mfma_f32_32x32x16_bf16 v[16:31], v[248:251], v[218:221], v[16:31]
	ds_read_b128 v[248:251], v151 offset:50752
	v_mfma_f32_32x32x16_bf16 v[112:127], v[222:225], v[214:217], v[112:127]
	ds_read_b128 v[210:213], v151 offset:41536
	s_waitcnt vmcnt(7)
	ds_write_b128 v154, v[170:173] offset:0
	global_load_dwordx4 v[170:173], v[132:133], off offset:384
	v_mfma_f32_32x32x16_bf16 v[96:111], v[222:225], v[218:221], v[96:111]
	s_waitcnt vmcnt(7)
	ds_write_b128 v154, v[178:181] offset:9216
	global_load_dwordx4 v[178:181], v[134:135], off offset:384
	s_waitcnt lgkmcnt(12)
	v_mfma_f32_32x32x16_bf16 v[64:79], v[240:243], v[214:217], v[64:79]
	s_waitcnt vmcnt(7)
	ds_write_b128 v154, v[186:189] offset:18432
	global_load_dwordx4 v[186:189], v[136:137], off offset:384
	v_mfma_f32_32x32x16_bf16 v[80:95], v[240:243], v[218:221], v[80:95]
	s_waitcnt vmcnt(7)
	ds_write_b128 v154, v[194:197] offset:27648
	global_load_dwordx4 v[194:197], v[140:141], off offset:384
	s_waitcnt lgkmcnt(7)
	v_mfma_f32_32x32x16_bf16 v[32:47], v[244:247], v[198:201], v[32:47]
	ds_read_b128 v[214:217], v152 offset:36960
	ds_read_b128 v[218:221], v152 offset:41568
	v_mfma_f32_32x32x16_bf16 v[48:63], v[244:247], v[202:205], v[48:63]
	ds_read_b128 v[244:247], v151 offset:46176
	s_waitcnt lgkmcnt(8)
	v_mfma_f32_32x32x16_bf16 v[0:15], v[248:251], v[198:201], v[0:15]
	ds_read_b128 v[222:225], v151 offset:36960
	v_mfma_f32_32x32x16_bf16 v[16:31], v[248:251], v[202:205], v[16:31]
	ds_read_b128 v[248:251], v151 offset:50784
	v_mfma_f32_32x32x16_bf16 v[112:127], v[206:209], v[198:201], v[112:127]
	ds_read_b128 v[240:243], v151 offset:41568
	v_mfma_f32_32x32x16_bf16 v[96:111], v[206:209], v[202:205], v[96:111]
	s_waitcnt lgkmcnt(10)
	v_mfma_f32_32x32x16_bf16 v[64:79], v[210:213], v[198:201], v[64:79]
	v_mfma_f32_32x32x16_bf16 v[80:95], v[210:213], v[202:205], v[80:95]
	s_waitcnt lgkmcnt(0)
	s_barrier
; template <class Epi>
; DI void gemm_phase(const bf16_t* A, const bf16_t* Bt, int K, int mtiles, int ntiles, const Epi& epi, char* smem) {
;     ...
;         for (int kt = 0; kt < nk; ++kt) {
;             const int cur = kt & 1;
;             const bf16_t* a_ = sA + cur * 256 * 72 + (wr * 128 + r) * 72 + 8 * h;
;             const bf16_t* b_ = sB + cur * 256 * 72 + (wc * 64 + r) * 72 + 8 * h;
;             bf16_t* wa = sA + (cur ^ 1) * 256 * 72 + srow * 72 + skc; bf16_t* wb = sB + (cur ^ 1) * 256 * 72 + srow * 72 + skc;
;     ...
;             GEMM_KS(0) GEMM_KS(1)
;             __builtin_amdgcn_sched_barrier(0);
;             if (kt + 1 < nk) {
; #pragma unroll
;                 for (int i = 0; i < 4; ++i) *(u32x4*)(wa + 64 * i * 72) = ra[i];
;             }
;             if (kt + 2 < nk) {
; #pragma unroll
;                 for (int i = 0; i < 4; ++i) ra[i] = *(const u32x4*)(Ag + (size_t)(64 * i) * K + (kt + 2) * 64);
;             }
;             GEMM_KS(2)
;             __builtin_amdgcn_sched_barrier(0);
;             if (kt + 1 < nk) {
; #pragma unroll
;                 for (int i = 0; i < 4; ++i) *(u32x4*)(wb + 64 * i * 72) = rb[i];
;             }
;             if (kt + 2 < nk) {
; #pragma unroll
;                 for (int i = 0; i < 4; ++i) rb[i] = *(const u32x4*)(Bg + (size_t)(64 * i) * K + (kt + 2) * 64);
;             }
;             GEMM_KS(3)
;     ...
;             __syncthreads();
;         }
	v_mfma_f32_32x32x16_bf16 v[32:47], v[244:247], v[214:217], v[32:47]
	ds_read_b128 v[198:201], v152
	ds_read_b128 v[202:205], v152 offset:4608
	v_mfma_f32_32x32x16_bf16 v[48:63], v[244:247], v[218:221], v[48:63]
	ds_read_b128 v[244:247], v151 offset:9216
	v_mfma_f32_32x32x16_bf16 v[0:15], v[248:251], v[214:217], v[0:15]
	ds_read_b128 v[206:209], v151
	v_mfma_f32_32x32x16_bf16 v[16:31], v[248:251], v[218:221], v[16:31]
	ds_read_b128 v[248:251], v151 offset:13824
	v_mfma_f32_32x32x16_bf16 v[112:127], v[222:225], v[214:217], v[112:127]
	ds_read_b128 v[210:213], v151 offset:4608
	v_mfma_f32_32x32x16_bf16 v[96:111], v[222:225], v[218:221], v[96:111]
	v_mfma_f32_32x32x16_bf16 v[64:79], v[240:243], v[214:217], v[64:79]
	v_mfma_f32_32x32x16_bf16 v[80:95], v[240:243], v[218:221], v[80:95]
	s_waitcnt lgkmcnt(3)
	v_mfma_f32_32x32x16_bf16 v[32:47], v[244:247], v[198:201], v[32:47]
	ds_read_b128 v[214:217], v152 offset:32
	ds_read_b128 v[218:221], v152 offset:4640
	v_mfma_f32_32x32x16_bf16 v[48:63], v[244:247], v[202:205], v[48:63]
	ds_read_b128 v[244:247], v151 offset:9248
	s_waitcnt lgkmcnt(4)
	v_mfma_f32_32x32x16_bf16 v[0:15], v[248:251], v[198:201], v[0:15]
	ds_read_b128 v[222:225], v151 offset:32
	v_mfma_f32_32x32x16_bf16 v[16:31], v[248:251], v[202:205], v[16:31]
	ds_read_b128 v[248:251], v151 offset:13856
	v_mfma_f32_32x32x16_bf16 v[112:127], v[206:209], v[198:201], v[112:127]
	ds_read_b128 v[240:243], v151 offset:4640
	s_waitcnt vmcnt(7)
	ds_write_b128 v153, v[156:159] offset:36864
	global_load_dwordx4 v[156:159], v[138:139], off offset:512
	v_mfma_f32_32x32x16_bf16 v[96:111], v[206:209], v[202:205], v[96:111]
	s_waitcnt vmcnt(7)
	ds_write_b128 v153, v[174:177] offset:46080
	global_load_dwordx4 v[174:177], v[142:143], off offset:512
	s_waitcnt lgkmcnt(8)
	v_mfma_f32_32x32x16_bf16 v[64:79], v[210:213], v[198:201], v[64:79]
	s_waitcnt vmcnt(7)
	ds_write_b128 v153, v[182:185] offset:55296
	global_load_dwordx4 v[182:185], v[144:145], off offset:512
	v_mfma_f32_32x32x16_bf16 v[80:95], v[210:213], v[202:205], v[80:95]
	s_waitcnt vmcnt(7)
	ds_write_b128 v153, v[190:193] offset:64512
	global_load_dwordx4 v[190:193], v[146:147], off offset:512
	s_waitcnt lgkmcnt(7)
	v_mfma_f32_32x32x16_bf16 v[32:47], v[244:247], v[214:217], v[32:47]
	ds_read_b128 v[198:201], v152 offset:64
	ds_read_b128 v[202:205], v152 offset:4672
	v_mfma_f32_32x32x16_bf16 v[48:63], v[244:247], v[218:221], v[48:63]
	ds_read_b128 v[244:247], v151 offset:9280
	s_waitcnt lgkmcnt(8)
	v_mfma_f32_32x32x16_bf16 v[0:15], v[248:251], v[214:217], v[0:15]
	ds_read_b128 v[206:209], v151 offset:64
	v_mfma_f32_32x32x16_bf16 v[16:31], v[248:251], v[218:221], v[16:31]
	ds_read_b128 v[248:251], v151 offset:13888
	v_mfma_f32_32x32x16_bf16 v[112:127], v[222:225], v[214:217], v[112:127]
	ds_read_b128 v[210:213], v151 offset:4672
	s_waitcnt vmcnt(7)
	ds_write_b128 v154, v[170:173] offset:36864
	global_load_dwordx4 v[170:173], v[132:133], off offset:512
	v_mfma_f32_32x32x16_bf16 v[96:111], v[222:225], v[218:221], v[96:111]
	s_waitcnt vmcnt(7)
	ds_write_b128 v154, v[178:181] offset:46080
	global_load_dwordx4 v[178:181], v[134:135], off offset:512
	s_waitcnt lgkmcnt(12)
	v_mfma_f32_32x32x16_bf16 v[64:79], v[240:243], v[214:217], v[64:79]
	s_waitcnt vmcnt(7)
	ds_write_b128 v154, v[186:189] offset:55296
	global_load_dwordx4 v[186:189], v[136:137], off offset:512
	v_mfma_f32_32x32x16_bf16 v[80:95], v[240:243], v[218:221], v[80:95]
	s_waitcnt vmcnt(7)
	ds_write_b128 v154, v[194:197] offset:64512
	global_load_dwordx4 v[194:197], v[140:141], off offset:512
	s_waitcnt lgkmcnt(7)
	v_mfma_f32_32x32x16_bf16 v[32:47], v[244:247], v[198:201], v[32:47]
	ds_read_b128 v[214:217], v152 offset:96
	ds_read_b128 v[218:221], v152 offset:4704
	v_mfma_f32_32x32x16_bf16 v[48:63], v[244:247], v[202:205], v[48:63]
	ds_read_b128 v[244:247], v151 offset:9312
	s_waitcnt lgkmcnt(8)
	v_mfma_f32_32x32x16_bf16 v[0:15], v[248:251], v[198:201], v[0:15]
	ds_read_b128 v[222:225], v151 offset:96
	v_mfma_f32_32x32x16_bf16 v[16:31], v[248:251], v[202:205], v[16:31]
	ds_read_b128 v[248:251], v151 offset:13920
	v_mfma_f32_32x32x16_bf16 v[112:127], v[206:209], v[198:201], v[112:127]
	ds_read_b128 v[240:243], v151 offset:4704
	v_mfma_f32_32x32x16_bf16 v[96:111], v[206:209], v[202:205], v[96:111]
	s_waitcnt lgkmcnt(10)
	v_mfma_f32_32x32x16_bf16 v[64:79], v[210:213], v[198:201], v[64:79]
	v_mfma_f32_32x32x16_bf16 v[80:95], v[210:213], v[202:205], v[80:95]
	s_waitcnt lgkmcnt(0)
	s_barrier
; template <class Epi>
; DI void gemm_phase(const bf16_t* A, const bf16_t* Bt, int K, int mtiles, int ntiles, const Epi& epi, char* smem) {
;     ...
;         for (int kt = 0; kt < nk; ++kt) {
;             const int cur = kt & 1;
;             const bf16_t* a_ = sA + cur * 256 * 72 + (wr * 128 + r) * 72 + 8 * h;
;             const bf16_t* b_ = sB + cur * 256 * 72 + (wc * 64 + r) * 72 + 8 * h;
;             bf16_t* wa = sA + (cur ^ 1) * 256 * 72 + srow * 72 + skc; bf16_t* wb = sB + (cur ^ 1) * 256 * 72 + srow * 72 + skc;
;     ...
;             GEMM_KS(0) GEMM_KS(1)
;             __builtin_amdgcn_sched_barrier(0);
;             if (kt + 1 < nk) {
; #pragma unroll
;                 for (int i = 0; i < 4; ++i) *(u32x4*)(wa + 64 * i * 72) = ra[i];
;             }
;             if (kt + 2 < nk) {
; #pragma unroll
;                 for (int i = 0; i < 4; ++i) ra[i] = *(const u32x4*)(Ag + (size_t)(64 * i) * K + (kt + 2) * 64);
;             }
;             GEMM_KS(2)
;             __builtin_amdgcn_sched_barrier(0);
;             if (kt + 1 < nk) {
; #pragma unroll
;                 for (int i = 0; i < 4; ++i) *(u32x4*)(wb + 64 * i * 72) = rb[i];
;             }
;             if (kt + 2 < nk) {
; #pragma unroll
;                 for (int i = 0; i < 4; ++i) rb[i] = *(const u32x4*)(Bg + (size_t)(64 * i) * K + (kt + 2) * 64);
;             }
;             GEMM_KS(3)
;     ...
;             __syncthreads();
;         }
	v_mfma_f32_32x32x16_bf16 v[32:47], v[244:247], v[214:217], v[32:47]
	ds_read_b128 v[198:201], v152 offset:36864
	ds_read_b128 v[202:205], v152 offset:41472
	v_mfma_f32_32x32x16_bf16 v[48:63], v[244:247], v[218:221], v[48:63]
	ds_read_b128 v[244:247], v151 offset:46080
	v_mfma_f32_32x32x16_bf16 v[0:15], v[248:251], v[214:217], v[0:15]
	ds_read_b128 v[206:209], v151 offset:36864
	v_mfma_f32_32x32x16_bf16 v[16:31], v[248:251], v[218:221], v[16:31]
	ds_read_b128 v[248:251], v151 offset:50688
	v_mfma_f32_32x32x16_bf16 v[112:127], v[222:225], v[214:217], v[112:127]
	ds_read_b128 v[210:213], v151 offset:41472
	v_mfma_f32_32x32x16_bf16 v[96:111], v[222:225], v[218:221], v[96:111]
	v_mfma_f32_32x32x16_bf16 v[64:79], v[240:243], v[214:217], v[64:79]
	v_mfma_f32_32x32x16_bf16 v[80:95], v[240:243], v[218:221], v[80:95]
	s_waitcnt lgkmcnt(3)
	v_mfma_f32_32x32x16_bf16 v[32:47], v[244:247], v[198:201], v[32:47]
	ds_read_b128 v[214:217], v152 offset:36896
	ds_read_b128 v[218:221], v152 offset:41504
	v_mfma_f32_32x32x16_bf16 v[48:63], v[244:247], v[202:205], v[48:63]
	ds_read_b128 v[244:247], v151 offset:46112
	s_waitcnt lgkmcnt(4)
	v_mfma_f32_32x32x16_bf16 v[0:15], v[248:251], v[198:201], v[0:15]
	ds_read_b128 v[222:225], v151 offset:36896
	v_mfma_f32_32x32x16_bf16 v[16:31], v[248:251], v[202:205], v[16:31]
	ds_read_b128 v[248:251], v151 offset:50720
	v_mfma_f32_32x32x16_bf16 v[112:127], v[206:209], v[198:201], v[112:127]
	ds_read_b128 v[240:243], v151 offset:41504
	s_waitcnt vmcnt(7)
	ds_write_b128 v153, v[156:159] offset:0
	global_load_dwordx4 v[156:159], v[138:139], off offset:640
	v_mfma_f32_32x32x16_bf16 v[96:111], v[206:209], v[202:205], v[96:111]
	s_waitcnt vmcnt(7)
	ds_write_b128 v153, v[174:177] offset:9216
	global_load_dwordx4 v[174:177], v[142:143], off offset:640
	s_waitcnt lgkmcnt(8)
	v_mfma_f32_32x32x16_bf16 v[64:79], v[210:213], v[198:201], v[64:79]
	s_waitcnt vmcnt(7)
	ds_write_b128 v153, v[182:185] offset:18432
	global_load_dwordx4 v[182:185], v[144:145], off offset:640
	v_mfma_f32_32x32x16_bf16 v[80:95], v[210:213], v[202:205], v[80:95]
	s_waitcnt vmcnt(7)
	ds_write_b128 v153, v[190:193] offset:27648
	global_load_dwordx4 v[190:193], v[146:147], off offset:640
	s_waitcnt lgkmcnt(7)
	v_mfma_f32_32x32x16_bf16 v[32:47], v[244:247], v[214:217], v[32:47]
	ds_read_b128 v[198:201], v152 offset:36928
	ds_read_b128 v[202:205], v152 offset:41536
	v_mfma_f32_32x32x16_bf16 v[48:63], v[244:247], v[218:221], v[48:63]
	ds_read_b128 v[244:247], v151 offset:46144
	s_waitcnt lgkmcnt(8)
	v_mfma_f32_32x32x16_bf16 v[0:15], v[248:251], v[214:217], v[0:15]
	ds_read_b128 v[206:209], v151 offset:36928
	v_mfma_f32_32x32x16_bf16 v[16:31], v[248:251], v[218:221], v[16:31]
	ds_read_b128 v[248:251], v151 offset:50752
	v_mfma_f32_32x32x16_bf16 v[112:127], v[222:225], v[214:217], v[112:127]
	ds_read_b128 v[210:213], v151 offset:41536
	s_waitcnt vmcnt(7)
	ds_write_b128 v154, v[170:173] offset:0
	global_load_dwordx4 v[170:173], v[132:133], off offset:640
	v_mfma_f32_32x32x16_bf16 v[96:111], v[222:225], v[218:221], v[96:111]
	s_waitcnt vmcnt(7)
	ds_write_b128 v154, v[178:181] offset:9216
	global_load_dwordx4 v[178:181], v[134:135], off offset:640
	s_waitcnt lgkmcnt(12)
	v_mfma_f32_32x32x16_bf16 v[64:79], v[240:243], v[214:217], v[64:79]
	s_waitcnt vmcnt(7)
	ds_write_b128 v154, v[186:189] offset:18432
	global_load_dwordx4 v[186:189], v[136:137], off offset:640
	v_mfma_f32_32x32x16_bf16 v[80:95], v[240:243], v[218:221], v[80:95]
	s_waitcnt vmcnt(7)
	ds_write_b128 v154, v[194:197] offset:27648
	global_load_dwordx4 v[194:197], v[140:141], off offset:640
	s_waitcnt lgkmcnt(7)
	v_mfma_f32_32x32x16_bf16 v[32:47], v[244:247], v[198:201], v[32:47]
	ds_read_b128 v[214:217], v152 offset:36960
	ds_read_b128 v[218:221], v152 offset:41568
	v_mfma_f32_32x32x16_bf16 v[48:63], v[244:247], v[202:205], v[48:63]
	ds_read_b128 v[244:247], v151 offset:46176
	s_waitcnt lgkmcnt(8)
	v_mfma_f32_32x32x16_bf16 v[0:15], v[248:251], v[198:201], v[0:15]
	ds_read_b128 v[222:225], v151 offset:36960
	v_mfma_f32_32x32x16_bf16 v[16:31], v[248:251], v[202:205], v[16:31]
	ds_read_b128 v[248:251], v151 offset:50784
	v_mfma_f32_32x32x16_bf16 v[112:127], v[206:209], v[198:201], v[112:127]
	ds_read_b128 v[240:243], v151 offset:41568
	v_mfma_f32_32x32x16_bf16 v[96:111], v[206:209], v[202:205], v[96:111]
	s_waitcnt lgkmcnt(10)
	v_mfma_f32_32x32x16_bf16 v[64:79], v[210:213], v[198:201], v[64:79]
	v_mfma_f32_32x32x16_bf16 v[80:95], v[210:213], v[202:205], v[80:95]
	s_waitcnt lgkmcnt(0)
	s_barrier
; template <class Epi>
; DI void gemm_phase(const bf16_t* A, const bf16_t* Bt, int K, int mtiles, int ntiles, const Epi& epi, char* smem) {
;     ...
;         for (int kt = 0; kt < nk; ++kt) {
;             const int cur = kt & 1;
;             const bf16_t* a_ = sA + cur * 256 * 72 + (wr * 128 + r) * 72 + 8 * h;
;             const bf16_t* b_ = sB + cur * 256 * 72 + (wc * 64 + r) * 72 + 8 * h;
;             bf16_t* wa = sA + (cur ^ 1) * 256 * 72 + srow * 72 + skc; bf16_t* wb = sB + (cur ^ 1) * 256 * 72 + srow * 72 + skc;
;     ...
;             GEMM_KS(0) GEMM_KS(1)
;             __builtin_amdgcn_sched_barrier(0);
;             if (kt + 1 < nk) {
; #pragma unroll
;                 for (int i = 0; i < 4; ++i) *(u32x4*)(wa + 64 * i * 72) = ra[i];
;             }
;             if (kt + 2 < nk) {
; #pragma unroll
;                 for (int i = 0; i < 4; ++i) ra[i] = *(const u32x4*)(Ag + (size_t)(64 * i) * K + (kt + 2) * 64);
;             }
;             GEMM_KS(2)
;             __builtin_amdgcn_sched_barrier(0);
;             if (kt + 1 < nk) {
; #pragma unroll
;                 for (int i = 0; i < 4; ++i) *(u32x4*)(wb + 64 * i * 72) = rb[i];
;             }
;             if (kt + 2 < nk) {
; #pragma unroll
;                 for (int i = 0; i < 4; ++i) rb[i] = *(const u32x4*)(Bg + (size_t)(64 * i) * K + (kt + 2) * 64);
;             }
;             GEMM_KS(3)
;     ...
;             __syncthreads();
;         }
	v_mfma_f32_32x32x16_bf16 v[32:47], v[244:247], v[214:217], v[32:47]
	ds_read_b128 v[198:201], v152
	ds_read_b128 v[202:205], v152 offset:4608
	v_mfma_f32_32x32x16_bf16 v[48:63], v[244:247], v[218:221], v[48:63]
	ds_read_b128 v[244:247], v151 offset:9216
	v_mfma_f32_32x32x16_bf16 v[0:15], v[248:251], v[214:217], v[0:15]
	ds_read_b128 v[206:209], v151
	v_mfma_f32_32x32x16_bf16 v[16:31], v[248:251], v[218:221], v[16:31]
	ds_read_b128 v[248:251], v151 offset:13824
	v_mfma_f32_32x32x16_bf16 v[112:127], v[222:225], v[214:217], v[112:127]
	ds_read_b128 v[210:213], v151 offset:4608
	v_mfma_f32_32x32x16_bf16 v[96:111], v[222:225], v[218:221], v[96:111]
	v_mfma_f32_32x32x16_bf16 v[64:79], v[240:243], v[214:217], v[64:79]
	v_mfma_f32_32x32x16_bf16 v[80:95], v[240:243], v[218:221], v[80:95]
	s_waitcnt lgkmcnt(3)
	v_mfma_f32_32x32x16_bf16 v[32:47], v[244:247], v[198:201], v[32:47]
	ds_read_b128 v[214:217], v152 offset:32
	ds_read_b128 v[218:221], v152 offset:4640
	v_mfma_f32_32x32x16_bf16 v[48:63], v[244:247], v[202:205], v[48:63]
	ds_read_b128 v[244:247], v151 offset:9248
	s_waitcnt lgkmcnt(4)
	v_mfma_f32_32x32x16_bf16 v[0:15], v[248:251], v[198:201], v[0:15]
	ds_read_b128 v[222:225], v151 offset:32
	v_mfma_f32_32x32x16_bf16 v[16:31], v[248:251], v[202:205], v[16:31]
	ds_read_b128 v[248:251], v151 offset:13856
	v_mfma_f32_32x32x16_bf16 v[112:127], v[206:209], v[198:201], v[112:127]
	ds_read_b128 v[240:243], v151 offset:4640
	s_waitcnt vmcnt(7)
	ds_write_b128 v153, v[156:159] offset:36864
	global_load_dwordx4 v[156:159], v[138:139], off offset:768
	v_mfma_f32_32x32x16_bf16 v[96:111], v[206:209], v[202:205], v[96:111]
	s_waitcnt vmcnt(7)
	ds_write_b128 v153, v[174:177] offset:46080
	global_load_dwordx4 v[174:177], v[142:143], off offset:768
	s_waitcnt lgkmcnt(8)
	v_mfma_f32_32x32x16_bf16 v[64:79], v[210:213], v[198:201], v[64:79]
	s_waitcnt vmcnt(7)
	ds_write_b128 v153, v[182:185] offset:55296
	global_load_dwordx4 v[182:185], v[144:145], off offset:768
	v_mfma_f32_32x32x16_bf16 v[80:95], v[210:213], v[202:205], v[80:95]
	s_waitcnt vmcnt(7)
	ds_write_b128 v153, v[190:193] offset:64512
	global_load_dwordx4 v[190:193], v[146:147], off offset:768
	s_waitcnt lgkmcnt(7)
	v_mfma_f32_32x32x16_bf16 v[32:47], v[244:247], v[214:217], v[32:47]
	ds_read_b128 v[198:201], v152 offset:64
	ds_read_b128 v[202:205], v152 offset:4672
	v_mfma_f32_32x32x16_bf16 v[48:63], v[244:247], v[218:221], v[48:63]
	ds_read_b128 v[244:247], v151 offset:9280
	s_waitcnt lgkmcnt(8)
	v_mfma_f32_32x32x16_bf16 v[0:15], v[248:251], v[214:217], v[0:15]
	ds_read_b128 v[206:209], v151 offset:64
	v_mfma_f32_32x32x16_bf16 v[16:31], v[248:251], v[218:221], v[16:31]
	ds_read_b128 v[248:251], v151 offset:13888
	v_mfma_f32_32x32x16_bf16 v[112:127], v[222:225], v[214:217], v[112:127]
	ds_read_b128 v[210:213], v151 offset:4672
	s_waitcnt vmcnt(7)
	ds_write_b128 v154, v[170:173] offset:36864
	global_load_dwordx4 v[170:173], v[132:133], off offset:768
	v_mfma_f32_32x32x16_bf16 v[96:111], v[222:225], v[218:221], v[96:111]
	s_waitcnt vmcnt(7)
	ds_write_b128 v154, v[178:181] offset:46080
	global_load_dwordx4 v[178:181], v[134:135], off offset:768
	s_waitcnt lgkmcnt(12)
	v_mfma_f32_32x32x16_bf16 v[64:79], v[240:243], v[214:217], v[64:79]
	s_waitcnt vmcnt(7)
	ds_write_b128 v154, v[186:189] offset:55296
	global_load_dwordx4 v[186:189], v[136:137], off offset:768
	v_mfma_f32_32x32x16_bf16 v[80:95], v[240:243], v[218:221], v[80:95]
	s_waitcnt vmcnt(7)
	ds_write_b128 v154, v[194:197] offset:64512
	global_load_dwordx4 v[194:197], v[140:141], off offset:768
	s_waitcnt lgkmcnt(7)
	v_mfma_f32_32x32x16_bf16 v[32:47], v[244:247], v[198:201], v[32:47]
	ds_read_b128 v[214:217], v152 offset:96
	ds_read_b128 v[218:221], v152 offset:4704
	v_mfma_f32_32x32x16_bf16 v[48:63], v[244:247], v[202:205], v[48:63]
	ds_read_b128 v[244:247], v151 offset:9312
	s_waitcnt lgkmcnt(8)
	v_mfma_f32_32x32x16_bf16 v[0:15], v[248:251], v[198:201], v[0:15]
	ds_read_b128 v[222:225], v151 offset:96
	v_mfma_f32_32x32x16_bf16 v[16:31], v[248:251], v[202:205], v[16:31]
	ds_read_b128 v[248:251], v151 offset:13920
	v_mfma_f32_32x32x16_bf16 v[112:127], v[206:209], v[198:201], v[112:127]
	ds_read_b128 v[240:243], v151 offset:4704
	v_mfma_f32_32x32x16_bf16 v[96:111], v[206:209], v[202:205], v[96:111]
	s_waitcnt lgkmcnt(10)
	v_mfma_f32_32x32x16_bf16 v[64:79], v[210:213], v[198:201], v[64:79]
	v_mfma_f32_32x32x16_bf16 v[80:95], v[210:213], v[202:205], v[80:95]
	s_waitcnt lgkmcnt(0)
	s_barrier
; template <class Epi>
; DI void gemm_phase(const bf16_t* A, const bf16_t* Bt, int K, int mtiles, int ntiles, const Epi& epi, char* smem) {
;     ...
;         for (int kt = 0; kt < nk; ++kt) {
;             const int cur = kt & 1;
;             const bf16_t* a_ = sA + cur * 256 * 72 + (wr * 128 + r) * 72 + 8 * h;
;             const bf16_t* b_ = sB + cur * 256 * 72 + (wc * 64 + r) * 72 + 8 * h;
;             bf16_t* wa = sA + (cur ^ 1) * 256 * 72 + srow * 72 + skc; bf16_t* wb = sB + (cur ^ 1) * 256 * 72 + srow * 72 + skc;
;     ...
;             GEMM_KS(0) GEMM_KS(1)
;             __builtin_amdgcn_sched_barrier(0);
;             if (kt + 1 < nk) {
; #pragma unroll
;                 for (int i = 0; i < 4; ++i) *(u32x4*)(wa + 64 * i * 72) = ra[i];
;             }
;             if (kt + 2 < nk) {
; #pragma unroll
;                 for (int i = 0; i < 4; ++i) ra[i] = *(const u32x4*)(Ag + (size_t)(64 * i) * K + (kt + 2) * 64);
;             }
;             GEMM_KS(2)
;             __builtin_amdgcn_sched_barrier(0);
;             if (kt + 1 < nk) {
; #pragma unroll
;                 for (int i = 0; i < 4; ++i) *(u32x4*)(wb + 64 * i * 72) = rb[i];
;             }
;             if (kt + 2 < nk) {
; #pragma unroll
;                 for (int i = 0; i < 4; ++i) rb[i] = *(const u32x4*)(Bg + (size_t)(64 * i) * K + (kt + 2) * 64);
;             }
;             GEMM_KS(3)
;     ...
;             __syncthreads();
;         }
	v_mfma_f32_32x32x16_bf16 v[32:47], v[244:247], v[214:217], v[32:47]
	ds_read_b128 v[198:201], v152 offset:36864
	ds_read_b128 v[202:205], v152 offset:41472
	v_mfma_f32_32x32x16_bf16 v[48:63], v[244:247], v[218:221], v[48:63]
	ds_read_b128 v[244:247], v151 offset:46080
	v_mfma_f32_32x32x16_bf16 v[0:15], v[248:251], v[214:217], v[0:15]
	ds_read_b128 v[206:209], v151 offset:36864
	v_mfma_f32_32x32x16_bf16 v[16:31], v[248:251], v[218:221], v[16:31]
	ds_read_b128 v[248:251], v151 offset:50688
	v_mfma_f32_32x32x16_bf16 v[112:127], v[222:225], v[214:217], v[112:127]
	ds_read_b128 v[210:213], v151 offset:41472
	v_mfma_f32_32x32x16_bf16 v[96:111], v[222:225], v[218:221], v[96:111]
	v_mfma_f32_32x32x16_bf16 v[64:79], v[240:243], v[214:217], v[64:79]
	v_mfma_f32_32x32x16_bf16 v[80:95], v[240:243], v[218:221], v[80:95]
	s_waitcnt lgkmcnt(3)
	v_mfma_f32_32x32x16_bf16 v[32:47], v[244:247], v[198:201], v[32:47]
	ds_read_b128 v[214:217], v152 offset:36896
	ds_read_b128 v[218:221], v152 offset:41504
	v_mfma_f32_32x32x16_bf16 v[48:63], v[244:247], v[202:205], v[48:63]
	ds_read_b128 v[244:247], v151 offset:46112
	s_waitcnt lgkmcnt(4)
	v_mfma_f32_32x32x16_bf16 v[0:15], v[248:251], v[198:201], v[0:15]
	ds_read_b128 v[222:225], v151 offset:36896
	v_mfma_f32_32x32x16_bf16 v[16:31], v[248:251], v[202:205], v[16:31]
	ds_read_b128 v[248:251], v151 offset:50720
	v_mfma_f32_32x32x16_bf16 v[112:127], v[206:209], v[198:201], v[112:127]
	ds_read_b128 v[240:243], v151 offset:41504
	s_waitcnt vmcnt(7)
	ds_write_b128 v153, v[156:159] offset:0
	global_load_dwordx4 v[156:159], v[138:139], off offset:896
	v_mfma_f32_32x32x16_bf16 v[96:111], v[206:209], v[202:205], v[96:111]
	s_waitcnt vmcnt(7)
	ds_write_b128 v153, v[174:177] offset:9216
	global_load_dwordx4 v[174:177], v[142:143], off offset:896
	s_waitcnt lgkmcnt(8)
	v_mfma_f32_32x32x16_bf16 v[64:79], v[210:213], v[198:201], v[64:79]
	s_waitcnt vmcnt(7)
	ds_write_b128 v153, v[182:185] offset:18432
	global_load_dwordx4 v[182:185], v[144:145], off offset:896
	v_mfma_f32_32x32x16_bf16 v[80:95], v[210:213], v[202:205], v[80:95]
	s_waitcnt vmcnt(7)
	ds_write_b128 v153, v[190:193] offset:27648
	global_load_dwordx4 v[190:193], v[146:147], off offset:896
	s_waitcnt lgkmcnt(7)
	v_mfma_f32_32x32x16_bf16 v[32:47], v[244:247], v[214:217], v[32:47]
	ds_read_b128 v[198:201], v152 offset:36928
	ds_read_b128 v[202:205], v152 offset:41536
	v_mfma_f32_32x32x16_bf16 v[48:63], v[244:247], v[218:221], v[48:63]
	ds_read_b128 v[244:247], v151 offset:46144
	s_waitcnt lgkmcnt(8)
	v_mfma_f32_32x32x16_bf16 v[0:15], v[248:251], v[214:217], v[0:15]
	ds_read_b128 v[206:209], v151 offset:36928
	v_mfma_f32_32x32x16_bf16 v[16:31], v[248:251], v[218:221], v[16:31]
	ds_read_b128 v[248:251], v151 offset:50752
	v_mfma_f32_32x32x16_bf16 v[112:127], v[222:225], v[214:217], v[112:127]
	ds_read_b128 v[210:213], v151 offset:41536
	s_waitcnt vmcnt(7)
	ds_write_b128 v154, v[170:173] offset:0
	global_load_dwordx4 v[170:173], v[132:133], off offset:896
	v_mfma_f32_32x32x16_bf16 v[96:111], v[222:225], v[218:221], v[96:111]
	s_waitcnt vmcnt(7)
	ds_write_b128 v154, v[178:181] offset:9216
	global_load_dwordx4 v[178:181], v[134:135], off offset:896
	s_waitcnt lgkmcnt(12)
	v_mfma_f32_32x32x16_bf16 v[64:79], v[240:243], v[214:217], v[64:79]
	s_waitcnt vmcnt(7)
	ds_write_b128 v154, v[186:189] offset:18432
	global_load_dwordx4 v[186:189], v[136:137], off offset:896
	v_mfma_f32_32x32x16_bf16 v[80:95], v[240:243], v[218:221], v[80:95]
	s_waitcnt vmcnt(7)
	ds_write_b128 v154, v[194:197] offset:27648
	global_load_dwordx4 v[194:197], v[140:141], off offset:896
	s_waitcnt lgkmcnt(7)
	v_mfma_f32_32x32x16_bf16 v[32:47], v[244:247], v[198:201], v[32:47]
	ds_read_b128 v[214:217], v152 offset:36960
	ds_read_b128 v[218:221], v152 offset:41568
	v_mfma_f32_32x32x16_bf16 v[48:63], v[244:247], v[202:205], v[48:63]
	ds_read_b128 v[244:247], v151 offset:46176
	s_waitcnt lgkmcnt(8)
	v_mfma_f32_32x32x16_bf16 v[0:15], v[248:251], v[198:201], v[0:15]
	ds_read_b128 v[222:225], v151 offset:36960
	v_mfma_f32_32x32x16_bf16 v[16:31], v[248:251], v[202:205], v[16:31]
	ds_read_b128 v[248:251], v151 offset:50784
	v_mfma_f32_32x32x16_bf16 v[112:127], v[206:209], v[198:201], v[112:127]
	ds_read_b128 v[240:243], v151 offset:41568
	v_mfma_f32_32x32x16_bf16 v[96:111], v[206:209], v[202:205], v[96:111]
	s_waitcnt lgkmcnt(10)
	v_mfma_f32_32x32x16_bf16 v[64:79], v[210:213], v[198:201], v[64:79]
	v_mfma_f32_32x32x16_bf16 v[80:95], v[210:213], v[202:205], v[80:95]
	s_waitcnt lgkmcnt(0)
	s_barrier
; template <class Epi>
; DI void gemm_phase(const bf16_t* A, const bf16_t* Bt, int K, int mtiles, int ntiles, const Epi& epi, char* smem) {
;     ...
;         for (int kt = 0; kt < nk; ++kt) {
;             const int cur = kt & 1;
;             const bf16_t* a_ = sA + cur * 256 * 72 + (wr * 128 + r) * 72 + 8 * h;
;             const bf16_t* b_ = sB + cur * 256 * 72 + (wc * 64 + r) * 72 + 8 * h;
;             bf16_t* wa = sA + (cur ^ 1) * 256 * 72 + srow * 72 + skc; bf16_t* wb = sB + (cur ^ 1) * 256 * 72 + srow * 72 + skc;
;     ...
;             GEMM_KS(0) GEMM_KS(1)
;             __builtin_amdgcn_sched_barrier(0);
;             if (kt + 1 < nk) {
; #pragma unroll
;                 for (int i = 0; i < 4; ++i) *(u32x4*)(wa + 64 * i * 72) = ra[i];
;             }
;             if (kt + 2 < nk) {
; #pragma unroll
;                 for (int i = 0; i < 4; ++i) ra[i] = *(const u32x4*)(Ag + (size_t)(64 * i) * K + (kt + 2) * 64);
;             }
;             GEMM_KS(2)
;             __builtin_amdgcn_sched_barrier(0);
;             if (kt + 1 < nk) {
; #pragma unroll
;                 for (int i = 0; i < 4; ++i) *(u32x4*)(wb + 64 * i * 72) = rb[i];
;             }
;             if (kt + 2 < nk) {
; #pragma unroll
;                 for (int i = 0; i < 4; ++i) rb[i] = *(const u32x4*)(Bg + (size_t)(64 * i) * K + (kt + 2) * 64);
;             }
;             GEMM_KS(3)
;     ...
;             __syncthreads();
;         }
	v_mfma_f32_32x32x16_bf16 v[32:47], v[244:247], v[214:217], v[32:47]
	ds_read_b128 v[198:201], v152
	ds_read_b128 v[202:205], v152 offset:4608
	v_mfma_f32_32x32x16_bf16 v[48:63], v[244:247], v[218:221], v[48:63]
	ds_read_b128 v[244:247], v151 offset:9216
	v_mfma_f32_32x32x16_bf16 v[0:15], v[248:251], v[214:217], v[0:15]
	ds_read_b128 v[206:209], v151
	v_mfma_f32_32x32x16_bf16 v[16:31], v[248:251], v[218:221], v[16:31]
	ds_read_b128 v[248:251], v151 offset:13824
	v_mfma_f32_32x32x16_bf16 v[112:127], v[222:225], v[214:217], v[112:127]
	ds_read_b128 v[210:213], v151 offset:4608
	v_mfma_f32_32x32x16_bf16 v[96:111], v[222:225], v[218:221], v[96:111]
	v_mfma_f32_32x32x16_bf16 v[64:79], v[240:243], v[214:217], v[64:79]
	v_mfma_f32_32x32x16_bf16 v[80:95], v[240:243], v[218:221], v[80:95]
	s_waitcnt lgkmcnt(3)
	v_mfma_f32_32x32x16_bf16 v[32:47], v[244:247], v[198:201], v[32:47]
	ds_read_b128 v[214:217], v152 offset:32
	ds_read_b128 v[218:221], v152 offset:4640
	v_mfma_f32_32x32x16_bf16 v[48:63], v[244:247], v[202:205], v[48:63]
	ds_read_b128 v[244:247], v151 offset:9248
	s_waitcnt lgkmcnt(4)
	v_mfma_f32_32x32x16_bf16 v[0:15], v[248:251], v[198:201], v[0:15]
	ds_read_b128 v[222:225], v151 offset:32
	v_mfma_f32_32x32x16_bf16 v[16:31], v[248:251], v[202:205], v[16:31]
	ds_read_b128 v[248:251], v151 offset:13856
	v_mfma_f32_32x32x16_bf16 v[112:127], v[206:209], v[198:201], v[112:127]
	ds_read_b128 v[240:243], v151 offset:4640
	s_waitcnt vmcnt(7)
	ds_write_b128 v153, v[156:159] offset:36864
	global_load_dwordx4 v[156:159], v[138:139], off offset:1024
	v_mfma_f32_32x32x16_bf16 v[96:111], v[206:209], v[202:205], v[96:111]
	s_waitcnt vmcnt(7)
	ds_write_b128 v153, v[174:177] offset:46080
	global_load_dwordx4 v[174:177], v[142:143], off offset:1024
	s_waitcnt lgkmcnt(8)
	v_mfma_f32_32x32x16_bf16 v[64:79], v[210:213], v[198:201], v[64:79]
	s_waitcnt vmcnt(7)
	ds_write_b128 v153, v[182:185] offset:55296
	global_load_dwordx4 v[182:185], v[144:145], off offset:1024
	v_mfma_f32_32x32x16_bf16 v[80:95], v[210:213], v[202:205], v[80:95]
	s_waitcnt vmcnt(7)
	ds_write_b128 v153, v[190:193] offset:64512
	global_load_dwordx4 v[190:193], v[146:147], off offset:1024
	s_waitcnt lgkmcnt(7)
	v_mfma_f32_32x32x16_bf16 v[32:47], v[244:247], v[214:217], v[32:47]
	ds_read_b128 v[198:201], v152 offset:64
	ds_read_b128 v[202:205], v152 offset:4672
	v_mfma_f32_32x32x16_bf16 v[48:63], v[244:247], v[218:221], v[48:63]
	ds_read_b128 v[244:247], v151 offset:9280
	s_waitcnt lgkmcnt(8)
	v_mfma_f32_32x32x16_bf16 v[0:15], v[248:251], v[214:217], v[0:15]
	ds_read_b128 v[206:209], v151 offset:64
	v_mfma_f32_32x32x16_bf16 v[16:31], v[248:251], v[218:221], v[16:31]
	ds_read_b128 v[248:251], v151 offset:13888
	v_mfma_f32_32x32x16_bf16 v[112:127], v[222:225], v[214:217], v[112:127]
	ds_read_b128 v[210:213], v151 offset:4672
	s_waitcnt vmcnt(7)
	ds_write_b128 v154, v[170:173] offset:36864
	global_load_dwordx4 v[170:173], v[132:133], off offset:1024
	v_mfma_f32_32x32x16_bf16 v[96:111], v[222:225], v[218:221], v[96:111]
	s_waitcnt vmcnt(7)
	ds_write_b128 v154, v[178:181] offset:46080
	global_load_dwordx4 v[178:181], v[134:135], off offset:1024
	s_waitcnt lgkmcnt(12)
	v_mfma_f32_32x32x16_bf16 v[64:79], v[240:243], v[214:217], v[64:79]
	s_waitcnt vmcnt(7)
	ds_write_b128 v154, v[186:189] offset:55296
	global_load_dwordx4 v[186:189], v[136:137], off offset:1024
	v_mfma_f32_32x32x16_bf16 v[80:95], v[240:243], v[218:221], v[80:95]
	s_waitcnt vmcnt(7)
	ds_write_b128 v154, v[194:197] offset:64512
	global_load_dwordx4 v[194:197], v[140:141], off offset:1024
	s_waitcnt lgkmcnt(7)
	v_mfma_f32_32x32x16_bf16 v[32:47], v[244:247], v[198:201], v[32:47]
	ds_read_b128 v[214:217], v152 offset:96
	ds_read_b128 v[218:221], v152 offset:4704
	v_mfma_f32_32x32x16_bf16 v[48:63], v[244:247], v[202:205], v[48:63]
	ds_read_b128 v[244:247], v151 offset:9312
	s_waitcnt lgkmcnt(8)
	v_mfma_f32_32x32x16_bf16 v[0:15], v[248:251], v[198:201], v[0:15]
	ds_read_b128 v[222:225], v151 offset:96
	v_mfma_f32_32x32x16_bf16 v[16:31], v[248:251], v[202:205], v[16:31]
	ds_read_b128 v[248:251], v151 offset:13920
	v_mfma_f32_32x32x16_bf16 v[112:127], v[206:209], v[198:201], v[112:127]
	ds_read_b128 v[240:243], v151 offset:4704
	v_mfma_f32_32x32x16_bf16 v[96:111], v[206:209], v[202:205], v[96:111]
	s_waitcnt lgkmcnt(10)
	v_mfma_f32_32x32x16_bf16 v[64:79], v[210:213], v[198:201], v[64:79]
	v_mfma_f32_32x32x16_bf16 v[80:95], v[210:213], v[202:205], v[80:95]
	s_waitcnt lgkmcnt(0)
	s_barrier
; template <class Epi>
; DI void gemm_phase(const bf16_t* A, const bf16_t* Bt, int K, int mtiles, int ntiles, const Epi& epi, char* smem) {
;     ...
;         for (int kt = 0; kt < nk; ++kt) {
;             const int cur = kt & 1;
;             const bf16_t* a_ = sA + cur * 256 * 72 + (wr * 128 + r) * 72 + 8 * h;
;             const bf16_t* b_ = sB + cur * 256 * 72 + (wc * 64 + r) * 72 + 8 * h;
;             bf16_t* wa = sA + (cur ^ 1) * 256 * 72 + srow * 72 + skc; bf16_t* wb = sB + (cur ^ 1) * 256 * 72 + srow * 72 + skc;
;     ...
;             GEMM_KS(0) GEMM_KS(1)
;             __builtin_amdgcn_sched_barrier(0);
;             if (kt + 1 < nk) {
; #pragma unroll
;                 for (int i = 0; i < 4; ++i) *(u32x4*)(wa + 64 * i * 72) = ra[i];
;             }
;             if (kt + 2 < nk) {
; #pragma unroll
;                 for (int i = 0; i < 4; ++i) ra[i] = *(const u32x4*)(Ag + (size_t)(64 * i) * K + (kt + 2) * 64);
;             }
;             GEMM_KS(2)
;             __builtin_amdgcn_sched_barrier(0);
;             if (kt + 1 < nk) {
; #pragma unroll
;                 for (int i = 0; i < 4; ++i) *(u32x4*)(wb + 64 * i * 72) = rb[i];
;             }
;             if (kt + 2 < nk) {
; #pragma unroll
;                 for (int i = 0; i < 4; ++i) rb[i] = *(const u32x4*)(Bg + (size_t)(64 * i) * K + (kt + 2) * 64);
;             }
;             GEMM_KS(3)
;     ...
;             __syncthreads();
;         }
	v_mfma_f32_32x32x16_bf16 v[32:47], v[244:247], v[214:217], v[32:47]
	ds_read_b128 v[198:201], v152 offset:36864
	ds_read_b128 v[202:205], v152 offset:41472
	v_mfma_f32_32x32x16_bf16 v[48:63], v[244:247], v[218:221], v[48:63]
	ds_read_b128 v[244:247], v151 offset:46080
	v_mfma_f32_32x32x16_bf16 v[0:15], v[248:251], v[214:217], v[0:15]
	ds_read_b128 v[206:209], v151 offset:36864
	v_mfma_f32_32x32x16_bf16 v[16:31], v[248:251], v[218:221], v[16:31]
	ds_read_b128 v[248:251], v151 offset:50688
	v_mfma_f32_32x32x16_bf16 v[112:127], v[222:225], v[214:217], v[112:127]
	ds_read_b128 v[210:213], v151 offset:41472
	v_mfma_f32_32x32x16_bf16 v[96:111], v[222:225], v[218:221], v[96:111]
	v_mfma_f32_32x32x16_bf16 v[64:79], v[240:243], v[214:217], v[64:79]
	v_mfma_f32_32x32x16_bf16 v[80:95], v[240:243], v[218:221], v[80:95]
	s_waitcnt lgkmcnt(3)
	v_mfma_f32_32x32x16_bf16 v[32:47], v[244:247], v[198:201], v[32:47]
	ds_read_b128 v[214:217], v152 offset:36896
	ds_read_b128 v[218:221], v152 offset:41504
	v_mfma_f32_32x32x16_bf16 v[48:63], v[244:247], v[202:205], v[48:63]
	ds_read_b128 v[244:247], v151 offset:46112
	s_waitcnt lgkmcnt(4)
	v_mfma_f32_32x32x16_bf16 v[0:15], v[248:251], v[198:201], v[0:15]
	ds_read_b128 v[222:225], v151 offset:36896
	v_mfma_f32_32x32x16_bf16 v[16:31], v[248:251], v[202:205], v[16:31]
	ds_read_b128 v[248:251], v151 offset:50720
	v_mfma_f32_32x32x16_bf16 v[112:127], v[206:209], v[198:201], v[112:127]
	ds_read_b128 v[240:243], v151 offset:41504
	s_waitcnt vmcnt(7)
	ds_write_b128 v153, v[156:159] offset:0
	global_load_dwordx4 v[156:159], v[138:139], off offset:1152
	v_mfma_f32_32x32x16_bf16 v[96:111], v[206:209], v[202:205], v[96:111]
	s_waitcnt vmcnt(7)
	ds_write_b128 v153, v[174:177] offset:9216
	global_load_dwordx4 v[174:177], v[142:143], off offset:1152
	s_waitcnt lgkmcnt(8)
	v_mfma_f32_32x32x16_bf16 v[64:79], v[210:213], v[198:201], v[64:79]
	s_waitcnt vmcnt(7)
	ds_write_b128 v153, v[182:185] offset:18432
	global_load_dwordx4 v[182:185], v[144:145], off offset:1152
	v_mfma_f32_32x32x16_bf16 v[80:95], v[210:213], v[202:205], v[80:95]
	s_waitcnt vmcnt(7)
	ds_write_b128 v153, v[190:193] offset:27648
	global_load_dwordx4 v[190:193], v[146:147], off offset:1152
	s_waitcnt lgkmcnt(7)
	v_mfma_f32_32x32x16_bf16 v[32:47], v[244:247], v[214:217], v[32:47]
	ds_read_b128 v[198:201], v152 offset:36928
	ds_read_b128 v[202:205], v152 offset:41536
	v_mfma_f32_32x32x16_bf16 v[48:63], v[244:247], v[218:221], v[48:63]
	ds_read_b128 v[244:247], v151 offset:46144
	s_waitcnt lgkmcnt(8)
	v_mfma_f32_32x32x16_bf16 v[0:15], v[248:251], v[214:217], v[0:15]
	ds_read_b128 v[206:209], v151 offset:36928
	v_mfma_f32_32x32x16_bf16 v[16:31], v[248:251], v[218:221], v[16:31]
	ds_read_b128 v[248:251], v151 offset:50752
	v_mfma_f32_32x32x16_bf16 v[112:127], v[222:225], v[214:217], v[112:127]
	ds_read_b128 v[210:213], v151 offset:41536
	s_waitcnt vmcnt(7)
	ds_write_b128 v154, v[170:173] offset:0
	global_load_dwordx4 v[170:173], v[132:133], off offset:1152
	v_mfma_f32_32x32x16_bf16 v[96:111], v[222:225], v[218:221], v[96:111]
	s_waitcnt vmcnt(7)
	ds_write_b128 v154, v[178:181] offset:9216
	global_load_dwordx4 v[178:181], v[134:135], off offset:1152
	s_waitcnt lgkmcnt(12)
	v_mfma_f32_32x32x16_bf16 v[64:79], v[240:243], v[214:217], v[64:79]
	s_waitcnt vmcnt(7)
	ds_write_b128 v154, v[186:189] offset:18432
	global_load_dwordx4 v[186:189], v[136:137], off offset:1152
	v_mfma_f32_32x32x16_bf16 v[80:95], v[240:243], v[218:221], v[80:95]
	s_waitcnt vmcnt(7)
	ds_write_b128 v154, v[194:197] offset:27648
	global_load_dwordx4 v[194:197], v[140:141], off offset:1152
	s_waitcnt lgkmcnt(7)
	v_mfma_f32_32x32x16_bf16 v[32:47], v[244:247], v[198:201], v[32:47]
	ds_read_b128 v[214:217], v152 offset:36960
	ds_read_b128 v[218:221], v152 offset:41568
	v_mfma_f32_32x32x16_bf16 v[48:63], v[244:247], v[202:205], v[48:63]
	ds_read_b128 v[244:247], v151 offset:46176
	s_waitcnt lgkmcnt(8)
	v_mfma_f32_32x32x16_bf16 v[0:15], v[248:251], v[198:201], v[0:15]
	ds_read_b128 v[222:225], v151 offset:36960
	v_mfma_f32_32x32x16_bf16 v[16:31], v[248:251], v[202:205], v[16:31]
	ds_read_b128 v[248:251], v151 offset:50784
	v_mfma_f32_32x32x16_bf16 v[112:127], v[206:209], v[198:201], v[112:127]
	ds_read_b128 v[240:243], v151 offset:41568
	v_mfma_f32_32x32x16_bf16 v[96:111], v[206:209], v[202:205], v[96:111]
	s_waitcnt lgkmcnt(10)
	v_mfma_f32_32x32x16_bf16 v[64:79], v[210:213], v[198:201], v[64:79]
	v_mfma_f32_32x32x16_bf16 v[80:95], v[210:213], v[202:205], v[80:95]
	s_waitcnt lgkmcnt(0)
	s_barrier
; template <class Epi>
; DI void gemm_phase(const bf16_t* A, const bf16_t* Bt, int K, int mtiles, int ntiles, const Epi& epi, char* smem) {
;     ...
;         for (int kt = 0; kt < nk; ++kt) {
;             const int cur = kt & 1;
;             const bf16_t* a_ = sA + cur * 256 * 72 + (wr * 128 + r) * 72 + 8 * h;
;             const bf16_t* b_ = sB + cur * 256 * 72 + (wc * 64 + r) * 72 + 8 * h;
;             bf16_t* wa = sA + (cur ^ 1) * 256 * 72 + srow * 72 + skc; bf16_t* wb = sB + (cur ^ 1) * 256 * 72 + srow * 72 + skc;
;     ...
;             GEMM_KS(0) GEMM_KS(1)
;             __builtin_amdgcn_sched_barrier(0);
;             if (kt + 1 < nk) {
; #pragma unroll
;                 for (int i = 0; i < 4; ++i) *(u32x4*)(wa + 64 * i * 72) = ra[i];
;             }
;             if (kt + 2 < nk) {
; #pragma unroll
;                 for (int i = 0; i < 4; ++i) ra[i] = *(const u32x4*)(Ag + (size_t)(64 * i) * K + (kt + 2) * 64);
;             }
;             GEMM_KS(2)
;             __builtin_amdgcn_sched_barrier(0);
;             if (kt + 1 < nk) {
; #pragma unroll
;                 for (int i = 0; i < 4; ++i) *(u32x4*)(wb + 64 * i * 72) = rb[i];
;             }
;             if (kt + 2 < nk) {
; #pragma unroll
;                 for (int i = 0; i < 4; ++i) rb[i] = *(const u32x4*)(Bg + (size_t)(64 * i) * K + (kt + 2) * 64);
;             }
;             GEMM_KS(3)
;     ...
;             __syncthreads();
;         }
	v_mfma_f32_32x32x16_bf16 v[32:47], v[244:247], v[214:217], v[32:47]
	ds_read_b128 v[198:201], v152
	ds_read_b128 v[202:205], v152 offset:4608
	v_mfma_f32_32x32x16_bf16 v[48:63], v[244:247], v[218:221], v[48:63]
	ds_read_b128 v[244:247], v151 offset:9216
	v_mfma_f32_32x32x16_bf16 v[0:15], v[248:251], v[214:217], v[0:15]
	ds_read_b128 v[206:209], v151
	v_mfma_f32_32x32x16_bf16 v[16:31], v[248:251], v[218:221], v[16:31]
	ds_read_b128 v[248:251], v151 offset:13824
	v_mfma_f32_32x32x16_bf16 v[112:127], v[222:225], v[214:217], v[112:127]
	ds_read_b128 v[210:213], v151 offset:4608
	v_mfma_f32_32x32x16_bf16 v[96:111], v[222:225], v[218:221], v[96:111]
	v_mfma_f32_32x32x16_bf16 v[64:79], v[240:243], v[214:217], v[64:79]
	v_mfma_f32_32x32x16_bf16 v[80:95], v[240:243], v[218:221], v[80:95]
	s_waitcnt lgkmcnt(3)
	v_mfma_f32_32x32x16_bf16 v[32:47], v[244:247], v[198:201], v[32:47]
	ds_read_b128 v[214:217], v152 offset:32
	ds_read_b128 v[218:221], v152 offset:4640
	v_mfma_f32_32x32x16_bf16 v[48:63], v[244:247], v[202:205], v[48:63]
	ds_read_b128 v[244:247], v151 offset:9248
	s_waitcnt lgkmcnt(4)
	v_mfma_f32_32x32x16_bf16 v[0:15], v[248:251], v[198:201], v[0:15]
	ds_read_b128 v[222:225], v151 offset:32
	v_mfma_f32_32x32x16_bf16 v[16:31], v[248:251], v[202:205], v[16:31]
	ds_read_b128 v[248:251], v151 offset:13856
	v_mfma_f32_32x32x16_bf16 v[112:127], v[206:209], v[198:201], v[112:127]
	ds_read_b128 v[240:243], v151 offset:4640
	s_waitcnt vmcnt(7)
	ds_write_b128 v153, v[156:159] offset:36864
	global_load_dwordx4 v[156:159], v[138:139], off offset:1280
	v_mfma_f32_32x32x16_bf16 v[96:111], v[206:209], v[202:205], v[96:111]
	s_waitcnt vmcnt(7)
	ds_write_b128 v153, v[174:177] offset:46080
	global_load_dwordx4 v[174:177], v[142:143], off offset:1280
	s_waitcnt lgkmcnt(8)
	v_mfma_f32_32x32x16_bf16 v[64:79], v[210:213], v[198:201], v[64:79]
	s_waitcnt vmcnt(7)
	ds_write_b128 v153, v[182:185] offset:55296
	global_load_dwordx4 v[182:185], v[144:145], off offset:1280
	v_mfma_f32_32x32x16_bf16 v[80:95], v[210:213], v[202:205], v[80:95]
	s_waitcnt vmcnt(7)
	ds_write_b128 v153, v[190:193] offset:64512
	global_load_dwordx4 v[190:193], v[146:147], off offset:1280
	s_waitcnt lgkmcnt(7)
	v_mfma_f32_32x32x16_bf16 v[32:47], v[244:247], v[214:217], v[32:47]
	ds_read_b128 v[198:201], v152 offset:64
	ds_read_b128 v[202:205], v152 offset:4672
	v_mfma_f32_32x32x16_bf16 v[48:63], v[244:247], v[218:221], v[48:63]
	ds_read_b128 v[244:247], v151 offset:9280
	s_waitcnt lgkmcnt(8)
	v_mfma_f32_32x32x16_bf16 v[0:15], v[248:251], v[214:217], v[0:15]
	ds_read_b128 v[206:209], v151 offset:64
	v_mfma_f32_32x32x16_bf16 v[16:31], v[248:251], v[218:221], v[16:31]
	ds_read_b128 v[248:251], v151 offset:13888
	v_mfma_f32_32x32x16_bf16 v[112:127], v[222:225], v[214:217], v[112:127]
	ds_read_b128 v[210:213], v151 offset:4672
	s_waitcnt vmcnt(7)
	ds_write_b128 v154, v[170:173] offset:36864
	global_load_dwordx4 v[170:173], v[132:133], off offset:1280
	v_mfma_f32_32x32x16_bf16 v[96:111], v[222:225], v[218:221], v[96:111]
	s_waitcnt vmcnt(7)
	ds_write_b128 v154, v[178:181] offset:46080
	global_load_dwordx4 v[178:181], v[134:135], off offset:1280
	s_waitcnt lgkmcnt(12)
	v_mfma_f32_32x32x16_bf16 v[64:79], v[240:243], v[214:217], v[64:79]
	s_waitcnt vmcnt(7)
	ds_write_b128 v154, v[186:189] offset:55296
	global_load_dwordx4 v[186:189], v[136:137], off offset:1280
	v_mfma_f32_32x32x16_bf16 v[80:95], v[240:243], v[218:221], v[80:95]
	s_waitcnt vmcnt(7)
	ds_write_b128 v154, v[194:197] offset:64512
	global_load_dwordx4 v[194:197], v[140:141], off offset:1280
	s_waitcnt lgkmcnt(7)
	v_mfma_f32_32x32x16_bf16 v[32:47], v[244:247], v[198:201], v[32:47]
	ds_read_b128 v[214:217], v152 offset:96
	ds_read_b128 v[218:221], v152 offset:4704
	v_mfma_f32_32x32x16_bf16 v[48:63], v[244:247], v[202:205], v[48:63]
	ds_read_b128 v[244:247], v151 offset:9312
	s_waitcnt lgkmcnt(8)
	v_mfma_f32_32x32x16_bf16 v[0:15], v[248:251], v[198:201], v[0:15]
	ds_read_b128 v[222:225], v151 offset:96
	v_mfma_f32_32x32x16_bf16 v[16:31], v[248:251], v[202:205], v[16:31]
	ds_read_b128 v[248:251], v151 offset:13920
	v_mfma_f32_32x32x16_bf16 v[112:127], v[206:209], v[198:201], v[112:127]
	ds_read_b128 v[240:243], v151 offset:4704
	v_mfma_f32_32x32x16_bf16 v[96:111], v[206:209], v[202:205], v[96:111]
	s_waitcnt lgkmcnt(10)
	v_mfma_f32_32x32x16_bf16 v[64:79], v[210:213], v[198:201], v[64:79]
	v_mfma_f32_32x32x16_bf16 v[80:95], v[210:213], v[202:205], v[80:95]
	s_waitcnt lgkmcnt(0)
	s_barrier
; template <class Epi>
; DI void gemm_phase(const bf16_t* A, const bf16_t* Bt, int K, int mtiles, int ntiles, const Epi& epi, char* smem) {
;     ...
;         for (int kt = 0; kt < nk; ++kt) {
;             const int cur = kt & 1;
;             const bf16_t* a_ = sA + cur * 256 * 72 + (wr * 128 + r) * 72 + 8 * h;
;             const bf16_t* b_ = sB + cur * 256 * 72 + (wc * 64 + r) * 72 + 8 * h;
;             bf16_t* wa = sA + (cur ^ 1) * 256 * 72 + srow * 72 + skc; bf16_t* wb = sB + (cur ^ 1) * 256 * 72 + srow * 72 + skc;
;     ...
;             GEMM_KS(0) GEMM_KS(1)
;             __builtin_amdgcn_sched_barrier(0);
;             if (kt + 1 < nk) {
; #pragma unroll
;                 for (int i = 0; i < 4; ++i) *(u32x4*)(wa + 64 * i * 72) = ra[i];
;             }
;             if (kt + 2 < nk) {
; #pragma unroll
;                 for (int i = 0; i < 4; ++i) ra[i] = *(const u32x4*)(Ag + (size_t)(64 * i) * K + (kt + 2) * 64);
;             }
;             GEMM_KS(2)
;             __builtin_amdgcn_sched_barrier(0);
;             if (kt + 1 < nk) {
; #pragma unroll
;                 for (int i = 0; i < 4; ++i) *(u32x4*)(wb + 64 * i * 72) = rb[i];
;             }
;             if (kt + 2 < nk) {
; #pragma unroll
;                 for (int i = 0; i < 4; ++i) rb[i] = *(const u32x4*)(Bg + (size_t)(64 * i) * K + (kt + 2) * 64);
;             }
;             GEMM_KS(3)
;     ...
;             __syncthreads();
;         }
	v_mfma_f32_32x32x16_bf16 v[32:47], v[244:247], v[214:217], v[32:47]
	ds_read_b128 v[198:201], v152 offset:36864
	ds_read_b128 v[202:205], v152 offset:41472
	v_mfma_f32_32x32x16_bf16 v[48:63], v[244:247], v[218:221], v[48:63]
	ds_read_b128 v[244:247], v151 offset:46080
	v_mfma_f32_32x32x16_bf16 v[0:15], v[248:251], v[214:217], v[0:15]
	ds_read_b128 v[206:209], v151 offset:36864
	v_mfma_f32_32x32x16_bf16 v[16:31], v[248:251], v[218:221], v[16:31]
	ds_read_b128 v[248:251], v151 offset:50688
	v_mfma_f32_32x32x16_bf16 v[112:127], v[222:225], v[214:217], v[112:127]
	ds_read_b128 v[210:213], v151 offset:41472
	v_mfma_f32_32x32x16_bf16 v[96:111], v[222:225], v[218:221], v[96:111]
	v_mfma_f32_32x32x16_bf16 v[64:79], v[240:243], v[214:217], v[64:79]
	v_mfma_f32_32x32x16_bf16 v[80:95], v[240:243], v[218:221], v[80:95]
	s_waitcnt lgkmcnt(3)
	v_mfma_f32_32x32x16_bf16 v[32:47], v[244:247], v[198:201], v[32:47]
	ds_read_b128 v[214:217], v152 offset:36896
	ds_read_b128 v[218:221], v152 offset:41504
	v_mfma_f32_32x32x16_bf16 v[48:63], v[244:247], v[202:205], v[48:63]
	ds_read_b128 v[244:247], v151 offset:46112
	s_waitcnt lgkmcnt(4)
	v_mfma_f32_32x32x16_bf16 v[0:15], v[248:251], v[198:201], v[0:15]
	ds_read_b128 v[222:225], v151 offset:36896
	v_mfma_f32_32x32x16_bf16 v[16:31], v[248:251], v[202:205], v[16:31]
	ds_read_b128 v[248:251], v151 offset:50720
	v_mfma_f32_32x32x16_bf16 v[112:127], v[206:209], v[198:201], v[112:127]
	ds_read_b128 v[240:243], v151 offset:41504
	s_waitcnt vmcnt(7)
	ds_write_b128 v153, v[156:159] offset:0
	global_load_dwordx4 v[156:159], v[138:139], off offset:1408
	v_mfma_f32_32x32x16_bf16 v[96:111], v[206:209], v[202:205], v[96:111]
	s_waitcnt vmcnt(7)
	ds_write_b128 v153, v[174:177] offset:9216
	global_load_dwordx4 v[174:177], v[142:143], off offset:1408
	s_waitcnt lgkmcnt(8)
	v_mfma_f32_32x32x16_bf16 v[64:79], v[210:213], v[198:201], v[64:79]
	s_waitcnt vmcnt(7)
	ds_write_b128 v153, v[182:185] offset:18432
	global_load_dwordx4 v[182:185], v[144:145], off offset:1408
	v_mfma_f32_32x32x16_bf16 v[80:95], v[210:213], v[202:205], v[80:95]
	s_waitcnt vmcnt(7)
	ds_write_b128 v153, v[190:193] offset:27648
	global_load_dwordx4 v[190:193], v[146:147], off offset:1408
	s_waitcnt lgkmcnt(7)
	v_mfma_f32_32x32x16_bf16 v[32:47], v[244:247], v[214:217], v[32:47]
	ds_read_b128 v[198:201], v152 offset:36928
	ds_read_b128 v[202:205], v152 offset:41536
	v_mfma_f32_32x32x16_bf16 v[48:63], v[244:247], v[218:221], v[48:63]
	ds_read_b128 v[244:247], v151 offset:46144
	s_waitcnt lgkmcnt(8)
	v_mfma_f32_32x32x16_bf16 v[0:15], v[248:251], v[214:217], v[0:15]
	ds_read_b128 v[206:209], v151 offset:36928
	v_mfma_f32_32x32x16_bf16 v[16:31], v[248:251], v[218:221], v[16:31]
	ds_read_b128 v[248:251], v151 offset:50752
	v_mfma_f32_32x32x16_bf16 v[112:127], v[222:225], v[214:217], v[112:127]
	ds_read_b128 v[210:213], v151 offset:41536
	s_waitcnt vmcnt(7)
	ds_write_b128 v154, v[170:173] offset:0
	global_load_dwordx4 v[170:173], v[132:133], off offset:1408
	v_mfma_f32_32x32x16_bf16 v[96:111], v[222:225], v[218:221], v[96:111]
	s_waitcnt vmcnt(7)
	ds_write_b128 v154, v[178:181] offset:9216
	global_load_dwordx4 v[178:181], v[134:135], off offset:1408
	s_waitcnt lgkmcnt(12)
	v_mfma_f32_32x32x16_bf16 v[64:79], v[240:243], v[214:217], v[64:79]
	s_waitcnt vmcnt(7)
	ds_write_b128 v154, v[186:189] offset:18432
	global_load_dwordx4 v[186:189], v[136:137], off offset:1408
	v_mfma_f32_32x32x16_bf16 v[80:95], v[240:243], v[218:221], v[80:95]
	s_waitcnt vmcnt(7)
	ds_write_b128 v154, v[194:197] offset:27648
	global_load_dwordx4 v[194:197], v[140:141], off offset:1408
	s_waitcnt lgkmcnt(7)
	v_mfma_f32_32x32x16_bf16 v[32:47], v[244:247], v[198:201], v[32:47]
	ds_read_b128 v[214:217], v152 offset:36960
	ds_read_b128 v[218:221], v152 offset:41568
	v_mfma_f32_32x32x16_bf16 v[48:63], v[244:247], v[202:205], v[48:63]
	ds_read_b128 v[244:247], v151 offset:46176
	s_waitcnt lgkmcnt(8)
	v_mfma_f32_32x32x16_bf16 v[0:15], v[248:251], v[198:201], v[0:15]
	ds_read_b128 v[222:225], v151 offset:36960
	v_mfma_f32_32x32x16_bf16 v[16:31], v[248:251], v[202:205], v[16:31]
	ds_read_b128 v[248:251], v151 offset:50784
	v_mfma_f32_32x32x16_bf16 v[112:127], v[206:209], v[198:201], v[112:127]
	ds_read_b128 v[240:243], v151 offset:41568
	v_mfma_f32_32x32x16_bf16 v[96:111], v[206:209], v[202:205], v[96:111]
	s_waitcnt lgkmcnt(10)
	v_mfma_f32_32x32x16_bf16 v[64:79], v[210:213], v[198:201], v[64:79]
	v_mfma_f32_32x32x16_bf16 v[80:95], v[210:213], v[202:205], v[80:95]
	s_waitcnt lgkmcnt(0)
	s_barrier
; template <class Epi>
; DI void gemm_phase(const bf16_t* A, const bf16_t* Bt, int K, int mtiles, int ntiles, const Epi& epi, char* smem) {
;     ...
;         for (int kt = 0; kt < nk; ++kt) {
;             const int cur = kt & 1;
;             const bf16_t* a_ = sA + cur * 256 * 72 + (wr * 128 + r) * 72 + 8 * h;
;             const bf16_t* b_ = sB + cur * 256 * 72 + (wc * 64 + r) * 72 + 8 * h;
;             bf16_t* wa = sA + (cur ^ 1) * 256 * 72 + srow * 72 + skc; bf16_t* wb = sB + (cur ^ 1) * 256 * 72 + srow * 72 + skc;
;     ...
;             GEMM_KS(0) GEMM_KS(1)
;             __builtin_amdgcn_sched_barrier(0);
;             if (kt + 1 < nk) {
; #pragma unroll
;                 for (int i = 0; i < 4; ++i) *(u32x4*)(wa + 64 * i * 72) = ra[i];
;             }
;             if (kt + 2 < nk) {
; #pragma unroll
;                 for (int i = 0; i < 4; ++i) ra[i] = *(const u32x4*)(Ag + (size_t)(64 * i) * K + (kt + 2) * 64);
;             }
;             GEMM_KS(2)
;             __builtin_amdgcn_sched_barrier(0);
;             if (kt + 1 < nk) {
; #pragma unroll
;                 for (int i = 0; i < 4; ++i) *(u32x4*)(wb + 64 * i * 72) = rb[i];
;             }
;             if (kt + 2 < nk) {
; #pragma unroll
;                 for (int i = 0; i < 4; ++i) rb[i] = *(const u32x4*)(Bg + (size_t)(64 * i) * K + (kt + 2) * 64);
;             }
;             GEMM_KS(3)
;     ...
;             __syncthreads();
;         }
	v_mfma_f32_32x32x16_bf16 v[32:47], v[244:247], v[214:217], v[32:47]
	ds_read_b128 v[198:201], v152
	ds_read_b128 v[202:205], v152 offset:4608
	v_mfma_f32_32x32x16_bf16 v[48:63], v[244:247], v[218:221], v[48:63]
	ds_read_b128 v[244:247], v151 offset:9216
	v_mfma_f32_32x32x16_bf16 v[0:15], v[248:251], v[214:217], v[0:15]
	ds_read_b128 v[206:209], v151
	v_mfma_f32_32x32x16_bf16 v[16:31], v[248:251], v[218:221], v[16:31]
	ds_read_b128 v[248:251], v151 offset:13824
	v_mfma_f32_32x32x16_bf16 v[112:127], v[222:225], v[214:217], v[112:127]
	ds_read_b128 v[210:213], v151 offset:4608
	v_mfma_f32_32x32x16_bf16 v[96:111], v[222:225], v[218:221], v[96:111]
	v_mfma_f32_32x32x16_bf16 v[64:79], v[240:243], v[214:217], v[64:79]
	v_mfma_f32_32x32x16_bf16 v[80:95], v[240:243], v[218:221], v[80:95]
	s_waitcnt lgkmcnt(3)
	v_mfma_f32_32x32x16_bf16 v[32:47], v[244:247], v[198:201], v[32:47]
	ds_read_b128 v[214:217], v152 offset:32
	ds_read_b128 v[218:221], v152 offset:4640
	v_mfma_f32_32x32x16_bf16 v[48:63], v[244:247], v[202:205], v[48:63]
	ds_read_b128 v[244:247], v151 offset:9248
	s_waitcnt lgkmcnt(4)
	v_mfma_f32_32x32x16_bf16 v[0:15], v[248:251], v[198:201], v[0:15]
	ds_read_b128 v[222:225], v151 offset:32
	v_mfma_f32_32x32x16_bf16 v[16:31], v[248:251], v[202:205], v[16:31]
	ds_read_b128 v[248:251], v151 offset:13856
	v_mfma_f32_32x32x16_bf16 v[112:127], v[206:209], v[198:201], v[112:127]
	ds_read_b128 v[240:243], v151 offset:4640
	s_waitcnt vmcnt(7)
	ds_write_b128 v153, v[156:159] offset:36864
	global_load_dwordx4 v[156:159], v[138:139], off offset:1536
	v_mfma_f32_32x32x16_bf16 v[96:111], v[206:209], v[202:205], v[96:111]
	s_waitcnt vmcnt(7)
	ds_write_b128 v153, v[174:177] offset:46080
	global_load_dwordx4 v[174:177], v[142:143], off offset:1536
	s_waitcnt lgkmcnt(8)
	v_mfma_f32_32x32x16_bf16 v[64:79], v[210:213], v[198:201], v[64:79]
	s_waitcnt vmcnt(7)
	ds_write_b128 v153, v[182:185] offset:55296
	global_load_dwordx4 v[182:185], v[144:145], off offset:1536
	v_mfma_f32_32x32x16_bf16 v[80:95], v[210:213], v[202:205], v[80:95]
	s_waitcnt vmcnt(7)
	ds_write_b128 v153, v[190:193] offset:64512
	global_load_dwordx4 v[190:193], v[146:147], off offset:1536
	s_waitcnt lgkmcnt(7)
	v_mfma_f32_32x32x16_bf16 v[32:47], v[244:247], v[214:217], v[32:47]
	ds_read_b128 v[198:201], v152 offset:64
	ds_read_b128 v[202:205], v152 offset:4672
	v_mfma_f32_32x32x16_bf16 v[48:63], v[244:247], v[218:221], v[48:63]
	ds_read_b128 v[244:247], v151 offset:9280
	s_waitcnt lgkmcnt(8)
	v_mfma_f32_32x32x16_bf16 v[0:15], v[248:251], v[214:217], v[0:15]
	ds_read_b128 v[206:209], v151 offset:64
	v_mfma_f32_32x32x16_bf16 v[16:31], v[248:251], v[218:221], v[16:31]
	ds_read_b128 v[248:251], v151 offset:13888
	v_mfma_f32_32x32x16_bf16 v[112:127], v[222:225], v[214:217], v[112:127]
	ds_read_b128 v[210:213], v151 offset:4672
	s_waitcnt vmcnt(7)
	ds_write_b128 v154, v[170:173] offset:36864
	global_load_dwordx4 v[170:173], v[132:133], off offset:1536
	v_mfma_f32_32x32x16_bf16 v[96:111], v[222:225], v[218:221], v[96:111]
	s_waitcnt vmcnt(7)
	ds_write_b128 v154, v[178:181] offset:46080
	global_load_dwordx4 v[178:181], v[134:135], off offset:1536
	s_waitcnt lgkmcnt(12)
	v_mfma_f32_32x32x16_bf16 v[64:79], v[240:243], v[214:217], v[64:79]
	s_waitcnt vmcnt(7)
	ds_write_b128 v154, v[186:189] offset:55296
	global_load_dwordx4 v[186:189], v[136:137], off offset:1536
	v_mfma_f32_32x32x16_bf16 v[80:95], v[240:243], v[218:221], v[80:95]
	s_waitcnt vmcnt(7)
	ds_write_b128 v154, v[194:197] offset:64512
	global_load_dwordx4 v[194:197], v[140:141], off offset:1536
	s_waitcnt lgkmcnt(7)
	v_mfma_f32_32x32x16_bf16 v[32:47], v[244:247], v[198:201], v[32:47]
	ds_read_b128 v[214:217], v152 offset:96
	ds_read_b128 v[218:221], v152 offset:4704
	v_mfma_f32_32x32x16_bf16 v[48:63], v[244:247], v[202:205], v[48:63]
	ds_read_b128 v[244:247], v151 offset:9312
	s_waitcnt lgkmcnt(8)
	v_mfma_f32_32x32x16_bf16 v[0:15], v[248:251], v[198:201], v[0:15]
	ds_read_b128 v[222:225], v151 offset:96
	v_mfma_f32_32x32x16_bf16 v[16:31], v[248:251], v[202:205], v[16:31]
	ds_read_b128 v[248:251], v151 offset:13920
	v_mfma_f32_32x32x16_bf16 v[112:127], v[206:209], v[198:201], v[112:127]
	ds_read_b128 v[240:243], v151 offset:4704
	v_mfma_f32_32x32x16_bf16 v[96:111], v[206:209], v[202:205], v[96:111]
	s_waitcnt lgkmcnt(10)
	v_mfma_f32_32x32x16_bf16 v[64:79], v[210:213], v[198:201], v[64:79]
	v_mfma_f32_32x32x16_bf16 v[80:95], v[210:213], v[202:205], v[80:95]
	s_waitcnt lgkmcnt(0)
	s_barrier
; template <class Epi>
; DI void gemm_phase(const bf16_t* A, const bf16_t* Bt, int K, int mtiles, int ntiles, const Epi& epi, char* smem) {
;     ...
;         for (int kt = 0; kt < nk; ++kt) {
;             const int cur = kt & 1;
;             const bf16_t* a_ = sA + cur * 256 * 72 + (wr * 128 + r) * 72 + 8 * h;
;             const bf16_t* b_ = sB + cur * 256 * 72 + (wc * 64 + r) * 72 + 8 * h;
;             bf16_t* wa = sA + (cur ^ 1) * 256 * 72 + srow * 72 + skc; bf16_t* wb = sB + (cur ^ 1) * 256 * 72 + srow * 72 + skc;
;     ...
;             GEMM_KS(0) GEMM_KS(1)
;             __builtin_amdgcn_sched_barrier(0);
;             if (kt + 1 < nk) {
; #pragma unroll
;                 for (int i = 0; i < 4; ++i) *(u32x4*)(wa + 64 * i * 72) = ra[i];
;             }
;             if (kt + 2 < nk) {
; #pragma unroll
;                 for (int i = 0; i < 4; ++i) ra[i] = *(const u32x4*)(Ag + (size_t)(64 * i) * K + (kt + 2) * 64);
;             }
;             GEMM_KS(2)
;             __builtin_amdgcn_sched_barrier(0);
;             if (kt + 1 < nk) {
; #pragma unroll
;                 for (int i = 0; i < 4; ++i) *(u32x4*)(wb + 64 * i * 72) = rb[i];
;             }
;             if (kt + 2 < nk) {
; #pragma unroll
;                 for (int i = 0; i < 4; ++i) rb[i] = *(const u32x4*)(Bg + (size_t)(64 * i) * K + (kt + 2) * 64);
;             }
;             GEMM_KS(3)
;     ...
;             __syncthreads();
;         }
	v_mfma_f32_32x32x16_bf16 v[32:47], v[244:247], v[214:217], v[32:47]
	ds_read_b128 v[198:201], v152 offset:36864
	ds_read_b128 v[202:205], v152 offset:41472
	v_mfma_f32_32x32x16_bf16 v[48:63], v[244:247], v[218:221], v[48:63]
	ds_read_b128 v[244:247], v151 offset:46080
	v_mfma_f32_32x32x16_bf16 v[0:15], v[248:251], v[214:217], v[0:15]
	ds_read_b128 v[206:209], v151 offset:36864
	v_mfma_f32_32x32x16_bf16 v[16:31], v[248:251], v[218:221], v[16:31]
	ds_read_b128 v[248:251], v151 offset:50688
	v_mfma_f32_32x32x16_bf16 v[112:127], v[222:225], v[214:217], v[112:127]
	ds_read_b128 v[210:213], v151 offset:41472
	v_mfma_f32_32x32x16_bf16 v[96:111], v[222:225], v[218:221], v[96:111]
	v_mfma_f32_32x32x16_bf16 v[64:79], v[240:243], v[214:217], v[64:79]
	v_mfma_f32_32x32x16_bf16 v[80:95], v[240:243], v[218:221], v[80:95]
	s_waitcnt lgkmcnt(3)
	v_mfma_f32_32x32x16_bf16 v[32:47], v[244:247], v[198:201], v[32:47]
	ds_read_b128 v[214:217], v152 offset:36896
	ds_read_b128 v[218:221], v152 offset:41504
	v_mfma_f32_32x32x16_bf16 v[48:63], v[244:247], v[202:205], v[48:63]
	ds_read_b128 v[244:247], v151 offset:46112
	s_waitcnt lgkmcnt(4)
	v_mfma_f32_32x32x16_bf16 v[0:15], v[248:251], v[198:201], v[0:15]
	ds_read_b128 v[222:225], v151 offset:36896
	v_mfma_f32_32x32x16_bf16 v[16:31], v[248:251], v[202:205], v[16:31]
	ds_read_b128 v[248:251], v151 offset:50720
	v_mfma_f32_32x32x16_bf16 v[112:127], v[206:209], v[198:201], v[112:127]
	ds_read_b128 v[240:243], v151 offset:41504
	s_waitcnt vmcnt(7)
	ds_write_b128 v153, v[156:159] offset:0
	global_load_dwordx4 v[156:159], v[138:139], off offset:1664
	v_mfma_f32_32x32x16_bf16 v[96:111], v[206:209], v[202:205], v[96:111]
	s_waitcnt vmcnt(7)
	ds_write_b128 v153, v[174:177] offset:9216
	global_load_dwordx4 v[174:177], v[142:143], off offset:1664
	s_waitcnt lgkmcnt(8)
	v_mfma_f32_32x32x16_bf16 v[64:79], v[210:213], v[198:201], v[64:79]
	s_waitcnt vmcnt(7)
	ds_write_b128 v153, v[182:185] offset:18432
	global_load_dwordx4 v[182:185], v[144:145], off offset:1664
	v_mfma_f32_32x32x16_bf16 v[80:95], v[210:213], v[202:205], v[80:95]
	s_waitcnt vmcnt(7)
	ds_write_b128 v153, v[190:193] offset:27648
	global_load_dwordx4 v[190:193], v[146:147], off offset:1664
	s_waitcnt lgkmcnt(7)
	v_mfma_f32_32x32x16_bf16 v[32:47], v[244:247], v[214:217], v[32:47]
	ds_read_b128 v[198:201], v152 offset:36928
	ds_read_b128 v[202:205], v152 offset:41536
	v_mfma_f32_32x32x16_bf16 v[48:63], v[244:247], v[218:221], v[48:63]
	ds_read_b128 v[244:247], v151 offset:46144
	s_waitcnt lgkmcnt(8)
	v_mfma_f32_32x32x16_bf16 v[0:15], v[248:251], v[214:217], v[0:15]
	ds_read_b128 v[206:209], v151 offset:36928
	v_mfma_f32_32x32x16_bf16 v[16:31], v[248:251], v[218:221], v[16:31]
	ds_read_b128 v[248:251], v151 offset:50752
	v_mfma_f32_32x32x16_bf16 v[112:127], v[222:225], v[214:217], v[112:127]
	ds_read_b128 v[210:213], v151 offset:41536
	s_waitcnt vmcnt(7)
	ds_write_b128 v154, v[170:173] offset:0
	global_load_dwordx4 v[170:173], v[132:133], off offset:1664
	v_mfma_f32_32x32x16_bf16 v[96:111], v[222:225], v[218:221], v[96:111]
	s_waitcnt vmcnt(7)
	ds_write_b128 v154, v[178:181] offset:9216
	global_load_dwordx4 v[178:181], v[134:135], off offset:1664
	s_waitcnt lgkmcnt(12)
	v_mfma_f32_32x32x16_bf16 v[64:79], v[240:243], v[214:217], v[64:79]
	s_waitcnt vmcnt(7)
	ds_write_b128 v154, v[186:189] offset:18432
	global_load_dwordx4 v[186:189], v[136:137], off offset:1664
	v_mfma_f32_32x32x16_bf16 v[80:95], v[240:243], v[218:221], v[80:95]
	s_waitcnt vmcnt(7)
	ds_write_b128 v154, v[194:197] offset:27648
	global_load_dwordx4 v[194:197], v[140:141], off offset:1664
	s_waitcnt lgkmcnt(7)
	v_mfma_f32_32x32x16_bf16 v[32:47], v[244:247], v[198:201], v[32:47]
	ds_read_b128 v[214:217], v152 offset:36960
	ds_read_b128 v[218:221], v152 offset:41568
	v_mfma_f32_32x32x16_bf16 v[48:63], v[244:247], v[202:205], v[48:63]
	ds_read_b128 v[244:247], v151 offset:46176
	s_waitcnt lgkmcnt(8)
	v_mfma_f32_32x32x16_bf16 v[0:15], v[248:251], v[198:201], v[0:15]
	ds_read_b128 v[222:225], v151 offset:36960
	v_mfma_f32_32x32x16_bf16 v[16:31], v[248:251], v[202:205], v[16:31]
	ds_read_b128 v[248:251], v151 offset:50784
	v_mfma_f32_32x32x16_bf16 v[112:127], v[206:209], v[198:201], v[112:127]
	ds_read_b128 v[240:243], v151 offset:41568
	v_mfma_f32_32x32x16_bf16 v[96:111], v[206:209], v[202:205], v[96:111]
	s_waitcnt lgkmcnt(10)
	v_mfma_f32_32x32x16_bf16 v[64:79], v[210:213], v[198:201], v[64:79]
	v_mfma_f32_32x32x16_bf16 v[80:95], v[210:213], v[202:205], v[80:95]
	s_waitcnt lgkmcnt(0)
	s_barrier
; template <class Epi>
; DI void gemm_phase(const bf16_t* A, const bf16_t* Bt, int K, int mtiles, int ntiles, const Epi& epi, char* smem) {
;     ...
;         for (int kt = 0; kt < nk; ++kt) {
;             const int cur = kt & 1;
;             const bf16_t* a_ = sA + cur * 256 * 72 + (wr * 128 + r) * 72 + 8 * h;
;             const bf16_t* b_ = sB + cur * 256 * 72 + (wc * 64 + r) * 72 + 8 * h;
;             bf16_t* wa = sA + (cur ^ 1) * 256 * 72 + srow * 72 + skc; bf16_t* wb = sB + (cur ^ 1) * 256 * 72 + srow * 72 + skc;
;     ...
;             GEMM_KS(0) GEMM_KS(1)
;             __builtin_amdgcn_sched_barrier(0);
;             if (kt + 1 < nk) {
; #pragma unroll
;                 for (int i = 0; i < 4; ++i) *(u32x4*)(wa + 64 * i * 72) = ra[i];
;             }
;             if (kt + 2 < nk) {
; #pragma unroll
;                 for (int i = 0; i < 4; ++i) ra[i] = *(const u32x4*)(Ag + (size_t)(64 * i) * K + (kt + 2) * 64);
;             }
;             GEMM_KS(2)
;             __builtin_amdgcn_sched_barrier(0);
;             if (kt + 1 < nk) {
; #pragma unroll
;                 for (int i = 0; i < 4; ++i) *(u32x4*)(wb + 64 * i * 72) = rb[i];
;             }
;             if (kt + 2 < nk) {
; #pragma unroll
;                 for (int i = 0; i < 4; ++i) rb[i] = *(const u32x4*)(Bg + (size_t)(64 * i) * K + (kt + 2) * 64);
;             }
;             GEMM_KS(3)
;     ...
;             __syncthreads();
;         }
	v_mfma_f32_32x32x16_bf16 v[32:47], v[244:247], v[214:217], v[32:47]
	ds_read_b128 v[198:201], v152
	ds_read_b128 v[202:205], v152 offset:4608
	v_mfma_f32_32x32x16_bf16 v[48:63], v[244:247], v[218:221], v[48:63]
	ds_read_b128 v[244:247], v151 offset:9216
	v_mfma_f32_32x32x16_bf16 v[0:15], v[248:251], v[214:217], v[0:15]
	ds_read_b128 v[206:209], v151
	v_mfma_f32_32x32x16_bf16 v[16:31], v[248:251], v[218:221], v[16:31]
	ds_read_b128 v[248:251], v151 offset:13824
	v_mfma_f32_32x32x16_bf16 v[112:127], v[222:225], v[214:217], v[112:127]
	ds_read_b128 v[210:213], v151 offset:4608
	v_mfma_f32_32x32x16_bf16 v[96:111], v[222:225], v[218:221], v[96:111]
	v_mfma_f32_32x32x16_bf16 v[64:79], v[240:243], v[214:217], v[64:79]
	v_mfma_f32_32x32x16_bf16 v[80:95], v[240:243], v[218:221], v[80:95]
	s_waitcnt lgkmcnt(3)
	v_mfma_f32_32x32x16_bf16 v[32:47], v[244:247], v[198:201], v[32:47]
	ds_read_b128 v[214:217], v152 offset:32
	ds_read_b128 v[218:221], v152 offset:4640
	v_mfma_f32_32x32x16_bf16 v[48:63], v[244:247], v[202:205], v[48:63]
	ds_read_b128 v[244:247], v151 offset:9248
	s_waitcnt lgkmcnt(4)
	v_mfma_f32_32x32x16_bf16 v[0:15], v[248:251], v[198:201], v[0:15]
	ds_read_b128 v[222:225], v151 offset:32
	v_mfma_f32_32x32x16_bf16 v[16:31], v[248:251], v[202:205], v[16:31]
	ds_read_b128 v[248:251], v151 offset:13856
	v_mfma_f32_32x32x16_bf16 v[112:127], v[206:209], v[198:201], v[112:127]
	ds_read_b128 v[240:243], v151 offset:4640
	s_waitcnt vmcnt(7)
	ds_write_b128 v153, v[156:159] offset:36864
	global_load_dwordx4 v[156:159], v[138:139], off offset:1792
	v_mfma_f32_32x32x16_bf16 v[96:111], v[206:209], v[202:205], v[96:111]
	s_waitcnt vmcnt(7)
	ds_write_b128 v153, v[174:177] offset:46080
	global_load_dwordx4 v[174:177], v[142:143], off offset:1792
	s_waitcnt lgkmcnt(8)
	v_mfma_f32_32x32x16_bf16 v[64:79], v[210:213], v[198:201], v[64:79]
	s_waitcnt vmcnt(7)
	ds_write_b128 v153, v[182:185] offset:55296
	global_load_dwordx4 v[182:185], v[144:145], off offset:1792
	v_mfma_f32_32x32x16_bf16 v[80:95], v[210:213], v[202:205], v[80:95]
	s_waitcnt vmcnt(7)
	ds_write_b128 v153, v[190:193] offset:64512
	global_load_dwordx4 v[190:193], v[146:147], off offset:1792
	s_waitcnt lgkmcnt(7)
	v_mfma_f32_32x32x16_bf16 v[32:47], v[244:247], v[214:217], v[32:47]
	ds_read_b128 v[198:201], v152 offset:64
	ds_read_b128 v[202:205], v152 offset:4672
	v_mfma_f32_32x32x16_bf16 v[48:63], v[244:247], v[218:221], v[48:63]
	ds_read_b128 v[244:247], v151 offset:9280
	s_waitcnt lgkmcnt(8)
	v_mfma_f32_32x32x16_bf16 v[0:15], v[248:251], v[214:217], v[0:15]
	ds_read_b128 v[206:209], v151 offset:64
	v_mfma_f32_32x32x16_bf16 v[16:31], v[248:251], v[218:221], v[16:31]
	ds_read_b128 v[248:251], v151 offset:13888
	v_mfma_f32_32x32x16_bf16 v[112:127], v[222:225], v[214:217], v[112:127]
	ds_read_b128 v[210:213], v151 offset:4672
	s_waitcnt vmcnt(7)
	ds_write_b128 v154, v[170:173] offset:36864
	global_load_dwordx4 v[170:173], v[132:133], off offset:1792
	v_mfma_f32_32x32x16_bf16 v[96:111], v[222:225], v[218:221], v[96:111]
	s_waitcnt vmcnt(7)
	ds_write_b128 v154, v[178:181] offset:46080
	global_load_dwordx4 v[178:181], v[134:135], off offset:1792
	s_waitcnt lgkmcnt(12)
	v_mfma_f32_32x32x16_bf16 v[64:79], v[240:243], v[214:217], v[64:79]
	s_waitcnt vmcnt(7)
	ds_write_b128 v154, v[186:189] offset:55296
	global_load_dwordx4 v[186:189], v[136:137], off offset:1792
	v_mfma_f32_32x32x16_bf16 v[80:95], v[240:243], v[218:221], v[80:95]
	s_waitcnt vmcnt(7)
	ds_write_b128 v154, v[194:197] offset:64512
	global_load_dwordx4 v[194:197], v[140:141], off offset:1792
	s_waitcnt lgkmcnt(7)
	v_mfma_f32_32x32x16_bf16 v[32:47], v[244:247], v[198:201], v[32:47]
	ds_read_b128 v[214:217], v152 offset:96
	ds_read_b128 v[218:221], v152 offset:4704
	v_mfma_f32_32x32x16_bf16 v[48:63], v[244:247], v[202:205], v[48:63]
	ds_read_b128 v[244:247], v151 offset:9312
	s_waitcnt lgkmcnt(8)
	v_mfma_f32_32x32x16_bf16 v[0:15], v[248:251], v[198:201], v[0:15]
	ds_read_b128 v[222:225], v151 offset:96
	v_mfma_f32_32x32x16_bf16 v[16:31], v[248:251], v[202:205], v[16:31]
	ds_read_b128 v[248:251], v151 offset:13920
	v_mfma_f32_32x32x16_bf16 v[112:127], v[206:209], v[198:201], v[112:127]
	ds_read_b128 v[240:243], v151 offset:4704
	v_mfma_f32_32x32x16_bf16 v[96:111], v[206:209], v[202:205], v[96:111]
	s_waitcnt lgkmcnt(10)
	v_mfma_f32_32x32x16_bf16 v[64:79], v[210:213], v[198:201], v[64:79]
	v_mfma_f32_32x32x16_bf16 v[80:95], v[210:213], v[202:205], v[80:95]
	s_waitcnt lgkmcnt(0)
	s_barrier
; template <class Epi>
; DI void gemm_phase(const bf16_t* A, const bf16_t* Bt, int K, int mtiles, int ntiles, const Epi& epi, char* smem) {
;     ...
;         for (int kt = 0; kt < nk; ++kt) {
;             const int cur = kt & 1;
;             const bf16_t* a_ = sA + cur * 256 * 72 + (wr * 128 + r) * 72 + 8 * h;
;             const bf16_t* b_ = sB + cur * 256 * 72 + (wc * 64 + r) * 72 + 8 * h;
;             bf16_t* wa = sA + (cur ^ 1) * 256 * 72 + srow * 72 + skc; bf16_t* wb = sB + (cur ^ 1) * 256 * 72 + srow * 72 + skc;
;     ...
;             GEMM_KS(0) GEMM_KS(1)
;             __builtin_amdgcn_sched_barrier(0);
;             if (kt + 1 < nk) {
; #pragma unroll
;                 for (int i = 0; i < 4; ++i) *(u32x4*)(wa + 64 * i * 72) = ra[i];
;             }
;             if (kt + 2 < nk) {
; #pragma unroll
;                 for (int i = 0; i < 4; ++i) ra[i] = *(const u32x4*)(Ag + (size_t)(64 * i) * K + (kt + 2) * 64);
;             }
;             GEMM_KS(2)
;             __builtin_amdgcn_sched_barrier(0);
;             if (kt + 1 < nk) {
; #pragma unroll
;                 for (int i = 0; i < 4; ++i) *(u32x4*)(wb + 64 * i * 72) = rb[i];
;             }
;             if (kt + 2 < nk) {
; #pragma unroll
;                 for (int i = 0; i < 4; ++i) rb[i] = *(const u32x4*)(Bg + (size_t)(64 * i) * K + (kt + 2) * 64);
;             }
;             GEMM_KS(3)
;     ...
;             __syncthreads();
;         }
	v_mfma_f32_32x32x16_bf16 v[32:47], v[244:247], v[214:217], v[32:47]
	ds_read_b128 v[198:201], v152 offset:36864
	ds_read_b128 v[202:205], v152 offset:41472
	v_mfma_f32_32x32x16_bf16 v[48:63], v[244:247], v[218:221], v[48:63]
	ds_read_b128 v[244:247], v151 offset:46080
	v_mfma_f32_32x32x16_bf16 v[0:15], v[248:251], v[214:217], v[0:15]
	ds_read_b128 v[206:209], v151 offset:36864
	v_mfma_f32_32x32x16_bf16 v[16:31], v[248:251], v[218:221], v[16:31]
	ds_read_b128 v[248:251], v151 offset:50688
	v_mfma_f32_32x32x16_bf16 v[112:127], v[222:225], v[214:217], v[112:127]
	ds_read_b128 v[210:213], v151 offset:41472
	v_mfma_f32_32x32x16_bf16 v[96:111], v[222:225], v[218:221], v[96:111]
	v_mfma_f32_32x32x16_bf16 v[64:79], v[240:243], v[214:217], v[64:79]
	v_mfma_f32_32x32x16_bf16 v[80:95], v[240:243], v[218:221], v[80:95]
	s_waitcnt lgkmcnt(3)
	v_mfma_f32_32x32x16_bf16 v[32:47], v[244:247], v[198:201], v[32:47]
	ds_read_b128 v[214:217], v152 offset:36896
	ds_read_b128 v[218:221], v152 offset:41504
	v_mfma_f32_32x32x16_bf16 v[48:63], v[244:247], v[202:205], v[48:63]
	ds_read_b128 v[244:247], v151 offset:46112
	s_waitcnt lgkmcnt(4)
	v_mfma_f32_32x32x16_bf16 v[0:15], v[248:251], v[198:201], v[0:15]
	ds_read_b128 v[222:225], v151 offset:36896
	v_mfma_f32_32x32x16_bf16 v[16:31], v[248:251], v[202:205], v[16:31]
	ds_read_b128 v[248:251], v151 offset:50720
	v_mfma_f32_32x32x16_bf16 v[112:127], v[206:209], v[198:201], v[112:127]
	ds_read_b128 v[240:243], v151 offset:41504
	s_waitcnt vmcnt(7)
	ds_write_b128 v153, v[156:159] offset:0
	global_load_dwordx4 v[156:159], v[138:139], off offset:1920
	v_mfma_f32_32x32x16_bf16 v[96:111], v[206:209], v[202:205], v[96:111]
	s_waitcnt vmcnt(7)
	ds_write_b128 v153, v[174:177] offset:9216
	global_load_dwordx4 v[174:177], v[142:143], off offset:1920
	s_waitcnt lgkmcnt(8)
	v_mfma_f32_32x32x16_bf16 v[64:79], v[210:213], v[198:201], v[64:79]
	s_waitcnt vmcnt(7)
	ds_write_b128 v153, v[182:185] offset:18432
	global_load_dwordx4 v[182:185], v[144:145], off offset:1920
	v_mfma_f32_32x32x16_bf16 v[80:95], v[210:213], v[202:205], v[80:95]
	s_waitcnt vmcnt(7)
	ds_write_b128 v153, v[190:193] offset:27648
	global_load_dwordx4 v[190:193], v[146:147], off offset:1920
	s_waitcnt lgkmcnt(7)
	v_mfma_f32_32x32x16_bf16 v[32:47], v[244:247], v[214:217], v[32:47]
	ds_read_b128 v[198:201], v152 offset:36928
	ds_read_b128 v[202:205], v152 offset:41536
	v_mfma_f32_32x32x16_bf16 v[48:63], v[244:247], v[218:221], v[48:63]
	ds_read_b128 v[244:247], v151 offset:46144
	s_waitcnt lgkmcnt(8)
	v_mfma_f32_32x32x16_bf16 v[0:15], v[248:251], v[214:217], v[0:15]
	ds_read_b128 v[206:209], v151 offset:36928
	v_mfma_f32_32x32x16_bf16 v[16:31], v[248:251], v[218:221], v[16:31]
	ds_read_b128 v[248:251], v151 offset:50752
	v_mfma_f32_32x32x16_bf16 v[112:127], v[222:225], v[214:217], v[112:127]
	ds_read_b128 v[210:213], v151 offset:41536
	s_waitcnt vmcnt(7)
	ds_write_b128 v154, v[170:173] offset:0
	global_load_dwordx4 v[170:173], v[132:133], off offset:1920
	v_mfma_f32_32x32x16_bf16 v[96:111], v[222:225], v[218:221], v[96:111]
	s_waitcnt vmcnt(7)
	ds_write_b128 v154, v[178:181] offset:9216
	global_load_dwordx4 v[178:181], v[134:135], off offset:1920
	s_waitcnt lgkmcnt(12)
	v_mfma_f32_32x32x16_bf16 v[64:79], v[240:243], v[214:217], v[64:79]
	s_waitcnt vmcnt(7)
	ds_write_b128 v154, v[186:189] offset:18432
	global_load_dwordx4 v[186:189], v[136:137], off offset:1920
	v_mfma_f32_32x32x16_bf16 v[80:95], v[240:243], v[218:221], v[80:95]
	s_waitcnt vmcnt(7)
	ds_write_b128 v154, v[194:197] offset:27648
	global_load_dwordx4 v[194:197], v[140:141], off offset:1920
	s_waitcnt lgkmcnt(7)
	v_mfma_f32_32x32x16_bf16 v[32:47], v[244:247], v[198:201], v[32:47]
	ds_read_b128 v[214:217], v152 offset:36960
	ds_read_b128 v[218:221], v152 offset:41568
	v_mfma_f32_32x32x16_bf16 v[48:63], v[244:247], v[202:205], v[48:63]
	ds_read_b128 v[244:247], v151 offset:46176
	s_waitcnt lgkmcnt(8)
	v_mfma_f32_32x32x16_bf16 v[0:15], v[248:251], v[198:201], v[0:15]
	ds_read_b128 v[222:225], v151 offset:36960
	v_mfma_f32_32x32x16_bf16 v[16:31], v[248:251], v[202:205], v[16:31]
	ds_read_b128 v[248:251], v151 offset:50784
	v_mfma_f32_32x32x16_bf16 v[112:127], v[206:209], v[198:201], v[112:127]
	ds_read_b128 v[240:243], v151 offset:41568
	v_mfma_f32_32x32x16_bf16 v[96:111], v[206:209], v[202:205], v[96:111]
	s_waitcnt lgkmcnt(10)
	v_mfma_f32_32x32x16_bf16 v[64:79], v[210:213], v[198:201], v[64:79]
	v_mfma_f32_32x32x16_bf16 v[80:95], v[210:213], v[202:205], v[80:95]
	s_waitcnt lgkmcnt(0)
	s_barrier
; template <class Epi>
; DI void gemm_phase(const bf16_t* A, const bf16_t* Bt, int K, int mtiles, int ntiles, const Epi& epi, char* smem) {
;     ...
;         for (int kt = 0; kt < nk; ++kt) {
;             const int cur = kt & 1;
;             const bf16_t* a_ = sA + cur * 256 * 72 + (wr * 128 + r) * 72 + 8 * h;
;             const bf16_t* b_ = sB + cur * 256 * 72 + (wc * 64 + r) * 72 + 8 * h;
;             bf16_t* wa = sA + (cur ^ 1) * 256 * 72 + srow * 72 + skc; bf16_t* wb = sB + (cur ^ 1) * 256 * 72 + srow * 72 + skc;
;     ...
;             GEMM_KS(0) GEMM_KS(1)
;             __builtin_amdgcn_sched_barrier(0);
;             if (kt + 1 < nk) {
; #pragma unroll
;                 for (int i = 0; i < 4; ++i) *(u32x4*)(wa + 64 * i * 72) = ra[i];
;             }
;             if (kt + 2 < nk) {
; #pragma unroll
;                 for (int i = 0; i < 4; ++i) ra[i] = *(const u32x4*)(Ag + (size_t)(64 * i) * K + (kt + 2) * 64);
;             }
;             GEMM_KS(2)
;             __builtin_amdgcn_sched_barrier(0);
;             if (kt + 1 < nk) {
; #pragma unroll
;                 for (int i = 0; i < 4; ++i) *(u32x4*)(wb + 64 * i * 72) = rb[i];
;             }
;             if (kt + 2 < nk) {
; #pragma unroll
;                 for (int i = 0; i < 4; ++i) rb[i] = *(const u32x4*)(Bg + (size_t)(64 * i) * K + (kt + 2) * 64);
;             }
;             GEMM_KS(3)
;     ...
;             __syncthreads();
;         }
	v_mfma_f32_32x32x16_bf16 v[32:47], v[244:247], v[214:217], v[32:47]
	ds_read_b128 v[198:201], v152
	ds_read_b128 v[202:205], v152 offset:4608
	v_mfma_f32_32x32x16_bf16 v[48:63], v[244:247], v[218:221], v[48:63]
	ds_read_b128 v[244:247], v151 offset:9216
	v_mfma_f32_32x32x16_bf16 v[0:15], v[248:251], v[214:217], v[0:15]
	ds_read_b128 v[206:209], v151
	v_mfma_f32_32x32x16_bf16 v[16:31], v[248:251], v[218:221], v[16:31]
	ds_read_b128 v[248:251], v151 offset:13824
	v_mfma_f32_32x32x16_bf16 v[112:127], v[222:225], v[214:217], v[112:127]
	ds_read_b128 v[210:213], v151 offset:4608
	v_mfma_f32_32x32x16_bf16 v[96:111], v[222:225], v[218:221], v[96:111]
	v_mfma_f32_32x32x16_bf16 v[64:79], v[240:243], v[214:217], v[64:79]
	v_mfma_f32_32x32x16_bf16 v[80:95], v[240:243], v[218:221], v[80:95]
	s_waitcnt lgkmcnt(3)
	v_mfma_f32_32x32x16_bf16 v[32:47], v[244:247], v[198:201], v[32:47]
	ds_read_b128 v[214:217], v152 offset:32
	ds_read_b128 v[218:221], v152 offset:4640
	v_mfma_f32_32x32x16_bf16 v[48:63], v[244:247], v[202:205], v[48:63]
	ds_read_b128 v[244:247], v151 offset:9248
	s_waitcnt lgkmcnt(4)
	v_mfma_f32_32x32x16_bf16 v[0:15], v[248:251], v[198:201], v[0:15]
	ds_read_b128 v[222:225], v151 offset:32
	v_mfma_f32_32x32x16_bf16 v[16:31], v[248:251], v[202:205], v[16:31]
	ds_read_b128 v[248:251], v151 offset:13856
	v_mfma_f32_32x32x16_bf16 v[112:127], v[206:209], v[198:201], v[112:127]
	ds_read_b128 v[240:243], v151 offset:4640
	s_waitcnt vmcnt(7)
	ds_write_b128 v153, v[156:159] offset:36864
	v_mfma_f32_32x32x16_bf16 v[96:111], v[206:209], v[202:205], v[96:111]
	s_waitcnt vmcnt(6)
	ds_write_b128 v153, v[174:177] offset:46080
	s_waitcnt lgkmcnt(8)
	v_mfma_f32_32x32x16_bf16 v[64:79], v[210:213], v[198:201], v[64:79]
	s_waitcnt vmcnt(5)
	ds_write_b128 v153, v[182:185] offset:55296
	v_mfma_f32_32x32x16_bf16 v[80:95], v[210:213], v[202:205], v[80:95]
	s_waitcnt vmcnt(4)
	ds_write_b128 v153, v[190:193] offset:64512
	s_waitcnt lgkmcnt(7)
	v_mfma_f32_32x32x16_bf16 v[32:47], v[244:247], v[214:217], v[32:47]
	ds_read_b128 v[198:201], v152 offset:64
	ds_read_b128 v[202:205], v152 offset:4672
	v_mfma_f32_32x32x16_bf16 v[48:63], v[244:247], v[218:221], v[48:63]
	ds_read_b128 v[244:247], v151 offset:9280
	s_waitcnt lgkmcnt(8)
	v_mfma_f32_32x32x16_bf16 v[0:15], v[248:251], v[214:217], v[0:15]
	ds_read_b128 v[206:209], v151 offset:64
	v_mfma_f32_32x32x16_bf16 v[16:31], v[248:251], v[218:221], v[16:31]
	ds_read_b128 v[248:251], v151 offset:13888
	v_mfma_f32_32x32x16_bf16 v[112:127], v[222:225], v[214:217], v[112:127]
	ds_read_b128 v[210:213], v151 offset:4672
	s_waitcnt vmcnt(3)
	ds_write_b128 v154, v[170:173] offset:36864
	v_mfma_f32_32x32x16_bf16 v[96:111], v[222:225], v[218:221], v[96:111]
	s_waitcnt vmcnt(2)
	ds_write_b128 v154, v[178:181] offset:46080
	s_waitcnt lgkmcnt(12)
	v_mfma_f32_32x32x16_bf16 v[64:79], v[240:243], v[214:217], v[64:79]
	s_waitcnt vmcnt(1)
	ds_write_b128 v154, v[186:189] offset:55296
	v_mfma_f32_32x32x16_bf16 v[80:95], v[240:243], v[218:221], v[80:95]
	s_waitcnt vmcnt(0)
	ds_write_b128 v154, v[194:197] offset:64512
	s_waitcnt lgkmcnt(7)
	v_mfma_f32_32x32x16_bf16 v[32:47], v[244:247], v[198:201], v[32:47]
	ds_read_b128 v[214:217], v152 offset:96
	ds_read_b128 v[218:221], v152 offset:4704
	v_mfma_f32_32x32x16_bf16 v[48:63], v[244:247], v[202:205], v[48:63]
	ds_read_b128 v[244:247], v151 offset:9312
	s_waitcnt lgkmcnt(8)
	v_mfma_f32_32x32x16_bf16 v[0:15], v[248:251], v[198:201], v[0:15]
	ds_read_b128 v[222:225], v151 offset:96
	v_mfma_f32_32x32x16_bf16 v[16:31], v[248:251], v[202:205], v[16:31]
	ds_read_b128 v[248:251], v151 offset:13920
	v_mfma_f32_32x32x16_bf16 v[112:127], v[206:209], v[198:201], v[112:127]
	ds_read_b128 v[240:243], v151 offset:4704
	v_mfma_f32_32x32x16_bf16 v[96:111], v[206:209], v[202:205], v[96:111]
	s_waitcnt lgkmcnt(10)
	v_mfma_f32_32x32x16_bf16 v[64:79], v[210:213], v[198:201], v[64:79]
	v_mfma_f32_32x32x16_bf16 v[80:95], v[210:213], v[202:205], v[80:95]
	s_waitcnt lgkmcnt(0)
	s_barrier
	v_mfma_f32_32x32x16_bf16 v[32:47], v[244:247], v[214:217], v[32:47]
	ds_read_b128 v[198:201], v152 offset:36864
	ds_read_b128 v[202:205], v152 offset:41472
	v_mfma_f32_32x32x16_bf16 v[48:63], v[244:247], v[218:221], v[48:63]
	ds_read_b128 v[244:247], v151 offset:46080
	v_mfma_f32_32x32x16_bf16 v[0:15], v[248:251], v[214:217], v[0:15]
	ds_read_b128 v[206:209], v151 offset:36864
	v_mfma_f32_32x32x16_bf16 v[16:31], v[248:251], v[218:221], v[16:31]
	ds_read_b128 v[248:251], v151 offset:50688
	v_mfma_f32_32x32x16_bf16 v[112:127], v[222:225], v[214:217], v[112:127]
	ds_read_b128 v[210:213], v151 offset:41472
	v_mfma_f32_32x32x16_bf16 v[96:111], v[222:225], v[218:221], v[96:111]
	v_mfma_f32_32x32x16_bf16 v[64:79], v[240:243], v[214:217], v[64:79]
	v_mfma_f32_32x32x16_bf16 v[80:95], v[240:243], v[218:221], v[80:95]
	s_waitcnt lgkmcnt(3)
	v_mfma_f32_32x32x16_bf16 v[32:47], v[244:247], v[198:201], v[32:47]
	ds_read_b128 v[214:217], v152 offset:36896
	ds_read_b128 v[218:221], v152 offset:41504
	v_mfma_f32_32x32x16_bf16 v[48:63], v[244:247], v[202:205], v[48:63]
	ds_read_b128 v[244:247], v151 offset:46112
	s_waitcnt lgkmcnt(4)
	v_mfma_f32_32x32x16_bf16 v[0:15], v[248:251], v[198:201], v[0:15]
	ds_read_b128 v[222:225], v151 offset:36896
	v_mfma_f32_32x32x16_bf16 v[16:31], v[248:251], v[202:205], v[16:31]
	ds_read_b128 v[248:251], v151 offset:50720
	v_mfma_f32_32x32x16_bf16 v[112:127], v[206:209], v[198:201], v[112:127]
	ds_read_b128 v[240:243], v151 offset:41504
	v_mfma_f32_32x32x16_bf16 v[96:111], v[206:209], v[202:205], v[96:111]
	s_waitcnt lgkmcnt(6)
	v_mfma_f32_32x32x16_bf16 v[64:79], v[210:213], v[198:201], v[64:79]
	v_mfma_f32_32x32x16_bf16 v[80:95], v[210:213], v[202:205], v[80:95]
	s_waitcnt lgkmcnt(3)
; DI bf16_t to_bf16(float a) { return (bf16_t)(pk_bf16(a, 0.f) & 0xffffu); }
; DI int crow(int i, int h) { return (i & 3) + 8 * (i >> 2) + 4 * h; }
;     DI void operator()(const f32x16 (&acc)[2][2], int row0, int col0, int r, int h, const float*) const {
;         const int hc = (col0 >> 1) + r;
; #pragma unroll
;         for (int mi = 0; mi < 2; ++mi)
; #pragma unroll
;             for (int i = 0; i < 16; ++i) {
;                 const int row = row0 + mi * 32 + crow(i, h);
;                 const float gt = acc[mi][0][i], up = acc[mi][1][i];
;                 ACT[(size_t)row * DFF + hc] = to_bf16(gt * __builtin_amdgcn_rcpf(1.f + __expf(-gt)) * up);
; template <class Epi>
; DI void gemm_phase(const bf16_t* A, const bf16_t* Bt, int K, int mtiles, int ntiles, const Epi& epi, char* smem) {
;     ...
;     for (int it = local; it < main_total; it += nloc) {
;         const int grp = it / pg, rem = it - grp * pg;
;         const int gl = mcnt - grp * 4, gsz = gl < 4 ? gl : 4;
;         const int mt = mbeg + grp * 4 + rem % gsz, nt = rem / gsz;
;         const bf16_t* Ag = A + (size_t)(mt * 256 + srow) * K + skc;
;         const bf16_t* Bg = Bt + (size_t)(nt * 256 + srow) * K + skc;
;         float* sst = (float*)(smem + 2 * HALF_LDS) + (tcount & 1) * 512; ++tcount;
;         epi.prefetch(mt * 256, tid, sst);
;         u32x4 ra[4], rb[4];
; #pragma unroll
;         for (int i = 0; i < 4; ++i) { ra[i] = *(const u32x4*)(Ag + (size_t)(64 * i) * K); rb[i] = *(const u32x4*)(Bg + (size_t)(64 * i) * K); }
	v_mfma_f32_32x32x16_bf16 v[32:47], v[244:247], v[214:217], v[32:47]
	ds_read_b128 v[198:201], v152 offset:36928
	ds_read_b128 v[202:205], v152 offset:41536
	v_mfma_f32_32x32x16_bf16 v[48:63], v[244:247], v[218:221], v[48:63]
	ds_read_b128 v[244:247], v151 offset:46144
	s_waitcnt lgkmcnt(4)
	v_mfma_f32_32x32x16_bf16 v[0:15], v[248:251], v[214:217], v[0:15]
	ds_read_b128 v[206:209], v151 offset:36928
	v_mfma_f32_32x32x16_bf16 v[16:31], v[248:251], v[218:221], v[16:31]
	ds_read_b128 v[248:251], v151 offset:50752
	v_mfma_f32_32x32x16_bf16 v[112:127], v[222:225], v[214:217], v[112:127]
	ds_read_b128 v[210:213], v151 offset:41536
	v_mfma_f32_32x32x16_bf16 v[96:111], v[222:225], v[218:221], v[96:111]
	s_waitcnt lgkmcnt(6)
	v_mfma_f32_32x32x16_bf16 v[64:79], v[240:243], v[214:217], v[64:79]
	v_mfma_f32_32x32x16_bf16 v[80:95], v[240:243], v[218:221], v[80:95]
	s_waitcnt lgkmcnt(3)
	v_mfma_f32_32x32x16_bf16 v[32:47], v[244:247], v[198:201], v[32:47]
	ds_read_b128 v[214:217], v152 offset:36960
	ds_read_b128 v[218:221], v152 offset:41568
	v_mfma_f32_32x32x16_bf16 v[48:63], v[244:247], v[202:205], v[48:63]
	ds_read_b128 v[244:247], v151 offset:46176
	s_waitcnt lgkmcnt(4)
	v_mfma_f32_32x32x16_bf16 v[0:15], v[248:251], v[198:201], v[0:15]
	ds_read_b128 v[222:225], v151 offset:36960
	v_mfma_f32_32x32x16_bf16 v[16:31], v[248:251], v[202:205], v[16:31]
	ds_read_b128 v[248:251], v151 offset:50784
	v_mfma_f32_32x32x16_bf16 v[112:127], v[206:209], v[198:201], v[112:127]
	ds_read_b128 v[240:243], v151 offset:41568
	v_mfma_f32_32x32x16_bf16 v[96:111], v[206:209], v[202:205], v[96:111]
	s_waitcnt lgkmcnt(6)
	v_mfma_f32_32x32x16_bf16 v[64:79], v[210:213], v[198:201], v[64:79]
	v_mfma_f32_32x32x16_bf16 v[80:95], v[210:213], v[202:205], v[80:95]
	s_waitcnt lgkmcnt(3)
	v_mfma_f32_32x32x16_bf16 v[32:47], v[244:247], v[214:217], v[32:47]
	v_mfma_f32_32x32x16_bf16 v[48:63], v[244:247], v[218:221], v[48:63]
	s_waitcnt lgkmcnt(1)
	v_mfma_f32_32x32x16_bf16 v[0:15], v[248:251], v[214:217], v[0:15]
	v_mfma_f32_32x32x16_bf16 v[16:31], v[248:251], v[218:221], v[16:31]
	v_mfma_f32_32x32x16_bf16 v[112:127], v[222:225], v[214:217], v[112:127]
	v_mfma_f32_32x32x16_bf16 v[96:111], v[222:225], v[218:221], v[96:111]
	s_waitcnt lgkmcnt(0)
	v_mfma_f32_32x32x16_bf16 v[64:79], v[240:243], v[214:217], v[64:79]
	v_mfma_f32_32x32x16_bf16 v[80:95], v[240:243], v[218:221], v[80:95]
	s_nop 7
	s_nop 7
	v_or_b32_e32 v205, s1, v150
	v_ashrrev_i32_e32 v205, 1, v205
	v_or_b32_e32 v205, v205, v148
	v_lshlrev_b32_e32 v205, 1, v205
	v_mad_u32_u24 v204, v155, s24, v205
	s_mul_i32 s12, s0, s24
	v_add_u32_e32 v204, s12, v204
	v_add_u32_e32 v210, 0x15fe, v204
	s_add_i32 s4, s4, s7
	s_cmp_ge_i32 s4, s6
	s_cbranch_scc1 .Lsw_last
	s_mul_hi_i32 s0, s4, 0x2e8ba2e9
	s_lshr_b32 s1, s0, 31
	s_ashr_i32 s0, s0, 4
	s_add_i32 s0, s0, s1
	s_mul_i32 s1, s0, 0xffffffa8
	s_lshl_b32 s0, s0, 2
	s_sub_i32 s9, s5, s0
	s_min_u32 s9, s9, 4
	v_cvt_f32_ubyte0_e32 v212, s9
	v_rcp_iflag_f32_e32 v212, v212
	s_sub_i32 s12, 0, s9
	s_add_i32 s1, s4, s1
	s_abs_i32 s11, s1
	v_mul_f32_e32 v212, 0x4f7ffffe, v212
	v_cvt_u32_f32_e32 v212, v212
	s_ashr_i32 s10, s1, 31
	v_readfirstlane_b32 s13, v212
	s_mul_i32 s12, s12, s13
	s_mul_hi_u32 s12, s13, s12
	s_add_i32 s13, s13, s12
	s_mul_hi_u32 s12, s11, s13
	s_mul_i32 s13, s12, s9
	s_sub_i32 s11, s11, s13
	s_add_i32 s13, s12, 1
	s_sub_i32 s14, s11, s9
	s_cmp_ge_u32 s11, s9
	s_cselect_b32 s12, s13, s12
	s_cselect_b32 s11, s14, s11
	s_add_i32 s13, s12, 1
	s_cmp_ge_u32 s11, s9
	s_cselect_b32 s11, s13, s12
	s_xor_b32 s11, s11, s10
	s_sub_i32 s10, s11, s10
	s_mul_i32 s9, s10, s9
	s_sub_i32 s1, s1, s9
	s_add_i32 s1, s1, s8
	s_add_i32 s1, s1, s0
	s_lshl_b32 s0, s1, 8
	v_add_u32_e32 v212, s0, v149
	v_ashrrev_i32_e32 v213, 31, v212
	v_lshlrev_b64 v[212:213], 11, v[212:213]
	s_lshl_b32 s1, s10, 8
	v_lshl_add_u64 v[138:139], v[128:129], 0, v[212:213]
	v_add_u32_e32 v212, s1, v149
	v_ashrrev_i32_e32 v213, 31, v212
	v_lshlrev_b64 v[212:213], 11, v[212:213]
	v_add_co_u32_e32 v142, vcc, s15, v138
	v_lshl_add_u64 v[132:133], v[130:131], 0, v[212:213]
	s_nop 0
	v_addc_co_u32_e32 v143, vcc, 0, v139, vcc
	v_add_co_u32_e32 v134, vcc, s15, v132
	global_load_dwordx4 v[156:159], v[138:139], off
	global_load_dwordx4 v[170:173], v[132:133], off
	v_addc_co_u32_e32 v135, vcc, 0, v133, vcc
	v_add_co_u32_e32 v144, vcc, s16, v138
	global_load_dwordx4 v[174:177], v[142:143], off
	s_nop 0
	v_addc_co_u32_e32 v145, vcc, 0, v139, vcc
	v_add_co_u32_e32 v136, vcc, s16, v132
	global_load_dwordx4 v[178:181], v[134:135], off
	s_nop 0
	v_addc_co_u32_e32 v137, vcc, 0, v133, vcc
	v_add_co_u32_e32 v146, vcc, s17, v138
	global_load_dwordx4 v[182:185], v[144:145], off
	s_nop 0
	v_addc_co_u32_e32 v147, vcc, 0, v139, vcc
	global_load_dwordx4 v[186:189], v[136:137], off
	v_add_co_u32_e32 v140, vcc, s17, v132
	global_load_dwordx4 v[190:193], v[146:147], off
	s_nop 0
	v_addc_co_u32_e32 v141, vcc, 0, v133, vcc
	global_load_dwordx4 v[194:197], v[140:141], off
	v_and_b32_e32 v205, 1, v148
	v_cmp_eq_u32_e32 vcc, 1, v205
	s_nop 1
	v_cndmask_b32_e32 v204, v204, v210, vcc
	v_mul_f32_e32 v198, 0xbfb8aa3b, v112
	v_mul_f32_e32 v199, 0xbfb8aa3b, v113
	v_mul_f32_e32 v200, 0xbfb8aa3b, v114
	v_mul_f32_e32 v201, 0xbfb8aa3b, v115
	v_exp_f32_e32 v198, v198
	v_exp_f32_e32 v199, v199
	v_exp_f32_e32 v200, v200
	v_exp_f32_e32 v201, v201
	v_add_f32_e32 v198, 1.0, v198
	v_add_f32_e32 v199, 1.0, v199
	v_add_f32_e32 v200, 1.0, v200
	v_add_f32_e32 v201, 1.0, v201
	v_rcp_f32_e32 v198, v198
	v_rcp_f32_e32 v199, v199
	v_rcp_f32_e32 v200, v200
	v_rcp_f32_e32 v201, v201
	v_mul_f32_e32 v198, v112, v198
	v_mul_f32_e32 v199, v113, v199
	v_mul_f32_e32 v200, v114, v200
; DI bf16_t to_bf16(float a) { return (bf16_t)(pk_bf16(a, 0.f) & 0xffffu); }
; DI int crow(int i, int h) { return (i & 3) + 8 * (i >> 2) + 4 * h; }
;     DI void operator()(const f32x16 (&acc)[2][2], int row0, int col0, int r, int h, const float*) const {
;         const int hc = (col0 >> 1) + r;
; #pragma unroll
;         for (int mi = 0; mi < 2; ++mi)
; #pragma unroll
;             for (int i = 0; i < 16; ++i) {
;                 const int row = row0 + mi * 32 + crow(i, h);
;                 const float gt = acc[mi][0][i], up = acc[mi][1][i];
;                 ACT[(size_t)row * DFF + hc] = to_bf16(gt * __builtin_amdgcn_rcpf(1.f + __expf(-gt)) * up);
	v_mul_f32_e32 v201, v115, v201
	v_mul_f32_e32 v198, v96, v198
	v_mul_f32_e32 v199, v97, v199
	v_mul_f32_e32 v200, v98, v200
	v_mul_f32_e32 v201, v99, v201
	v_mov_b32_dpp v206, v198 quad_perm:[1,0,3,2] row_mask:0xf bank_mask:0xf
	v_mov_b32_dpp v207, v199 quad_perm:[1,0,3,2] row_mask:0xf bank_mask:0xf
	v_cndmask_b32_e32 v208, v198, v207, vcc
	v_cndmask_b32_e32 v209, v206, v199, vcc
	v_cvt_pk_bf16_f32 v202, v208, v209
	global_store_dword v204, v202, s[64:65]
	v_mov_b32_dpp v206, v200 quad_perm:[1,0,3,2] row_mask:0xf bank_mask:0xf
	v_mov_b32_dpp v207, v201 quad_perm:[1,0,3,2] row_mask:0xf bank_mask:0xf
	v_add_u32_e32 v204, 0x2c00, v204
	v_cndmask_b32_e32 v208, v200, v207, vcc
	v_cndmask_b32_e32 v209, v206, v201, vcc
	v_cvt_pk_bf16_f32 v203, v208, v209
	global_store_dword v204, v203, s[64:65]
	v_mul_f32_e32 v198, 0xbfb8aa3b, v116
	v_mul_f32_e32 v199, 0xbfb8aa3b, v117
	v_mul_f32_e32 v200, 0xbfb8aa3b, v118
	v_mul_f32_e32 v201, 0xbfb8aa3b, v119
	v_exp_f32_e32 v198, v198
	v_exp_f32_e32 v199, v199
	v_exp_f32_e32 v200, v200
	v_exp_f32_e32 v201, v201
	v_add_f32_e32 v198, 1.0, v198
	v_add_f32_e32 v199, 1.0, v199
	v_add_f32_e32 v200, 1.0, v200
	v_add_f32_e32 v201, 1.0, v201
	v_rcp_f32_e32 v198, v198
	v_rcp_f32_e32 v199, v199
	v_rcp_f32_e32 v200, v200
	v_rcp_f32_e32 v201, v201
	v_mul_f32_e32 v198, v116, v198
	v_mul_f32_e32 v199, v117, v199
	v_mul_f32_e32 v200, v118, v200
	v_mul_f32_e32 v201, v119, v201
	v_mul_f32_e32 v198, v100, v198
	v_mul_f32_e32 v199, v101, v199
	v_mul_f32_e32 v200, v102, v200
	v_mul_f32_e32 v201, v103, v201
	v_mov_b32_dpp v206, v198 quad_perm:[1,0,3,2] row_mask:0xf bank_mask:0xf
	v_mov_b32_dpp v207, v199 quad_perm:[1,0,3,2] row_mask:0xf bank_mask:0xf
	v_add_u32_e32 v204, 0x8400, v204
	v_cndmask_b32_e32 v208, v198, v207, vcc
	v_cndmask_b32_e32 v209, v206, v199, vcc
	v_cvt_pk_bf16_f32 v202, v208, v209
	global_store_dword v204, v202, s[64:65]
	v_mov_b32_dpp v206, v200 quad_perm:[1,0,3,2] row_mask:0xf bank_mask:0xf
	v_mov_b32_dpp v207, v201 quad_perm:[1,0,3,2] row_mask:0xf bank_mask:0xf
	v_add_u32_e32 v204, 0x2c00, v204
	v_cndmask_b32_e32 v208, v200, v207, vcc
	v_cndmask_b32_e32 v209, v206, v201, vcc
	v_cvt_pk_bf16_f32 v203, v208, v209
	global_store_dword v204, v203, s[64:65]
	v_mul_f32_e32 v198, 0xbfb8aa3b, v120
	v_mul_f32_e32 v199, 0xbfb8aa3b, v121
	v_mul_f32_e32 v200, 0xbfb8aa3b, v122
	v_mul_f32_e32 v201, 0xbfb8aa3b, v123
	v_exp_f32_e32 v198, v198
	v_exp_f32_e32 v199, v199
	v_exp_f32_e32 v200, v200
	v_exp_f32_e32 v201, v201
	v_add_f32_e32 v198, 1.0, v198
	v_add_f32_e32 v199, 1.0, v199
	v_add_f32_e32 v200, 1.0, v200
	v_add_f32_e32 v201, 1.0, v201
	v_rcp_f32_e32 v198, v198
	v_rcp_f32_e32 v199, v199
	v_rcp_f32_e32 v200, v200
	v_rcp_f32_e32 v201, v201
	v_mul_f32_e32 v198, v120, v198
	v_mul_f32_e32 v199, v121, v199
	v_mul_f32_e32 v200, v122, v200
	v_mul_f32_e32 v201, v123, v201
	v_mul_f32_e32 v198, v104, v198
	v_mul_f32_e32 v199, v105, v199
	v_mul_f32_e32 v200, v106, v200
	v_mul_f32_e32 v201, v107, v201
	v_mov_b32_dpp v206, v198 quad_perm:[1,0,3,2] row_mask:0xf bank_mask:0xf
	v_mov_b32_dpp v207, v199 quad_perm:[1,0,3,2] row_mask:0xf bank_mask:0xf
	v_add_u32_e32 v204, 0x8400, v204
	v_cndmask_b32_e32 v208, v198, v207, vcc
	v_cndmask_b32_e32 v209, v206, v199, vcc
	v_cvt_pk_bf16_f32 v202, v208, v209
	global_store_dword v204, v202, s[64:65]
	v_mov_b32_dpp v206, v200 quad_perm:[1,0,3,2] row_mask:0xf bank_mask:0xf
	v_mov_b32_dpp v207, v201 quad_perm:[1,0,3,2] row_mask:0xf bank_mask:0xf
	v_add_u32_e32 v204, 0x2c00, v204
	v_cndmask_b32_e32 v208, v200, v207, vcc
	v_cndmask_b32_e32 v209, v206, v201, vcc
	v_cvt_pk_bf16_f32 v203, v208, v209
	global_store_dword v204, v203, s[64:65]
	v_mul_f32_e32 v198, 0xbfb8aa3b, v124
	v_mul_f32_e32 v199, 0xbfb8aa3b, v125
	v_mul_f32_e32 v200, 0xbfb8aa3b, v126
	v_mul_f32_e32 v201, 0xbfb8aa3b, v127
	v_exp_f32_e32 v198, v198
	v_exp_f32_e32 v199, v199
	v_exp_f32_e32 v200, v200
	v_exp_f32_e32 v201, v201
	v_add_f32_e32 v198, 1.0, v198
	v_add_f32_e32 v199, 1.0, v199
	v_add_f32_e32 v200, 1.0, v200
	v_add_f32_e32 v201, 1.0, v201
	v_rcp_f32_e32 v198, v198
	v_rcp_f32_e32 v199, v199
	v_rcp_f32_e32 v200, v200
	v_rcp_f32_e32 v201, v201
	v_mul_f32_e32 v198, v124, v198
	v_mul_f32_e32 v199, v125, v199
	v_mul_f32_e32 v200, v126, v200
	v_mul_f32_e32 v201, v127, v201
	v_mul_f32_e32 v198, v108, v198
	v_mul_f32_e32 v199, v109, v199
	v_mul_f32_e32 v200, v110, v200
	v_mul_f32_e32 v201, v111, v201
	v_mov_b32_dpp v206, v198 quad_perm:[1,0,3,2] row_mask:0xf bank_mask:0xf
	v_mov_b32_dpp v207, v199 quad_perm:[1,0,3,2] row_mask:0xf bank_mask:0xf
	v_add_u32_e32 v204, 0x8400, v204
	v_cndmask_b32_e32 v208, v198, v207, vcc
	v_cndmask_b32_e32 v209, v206, v199, vcc
	v_cvt_pk_bf16_f32 v202, v208, v209
	global_store_dword v204, v202, s[64:65]
	v_mov_b32_dpp v206, v200 quad_perm:[1,0,3,2] row_mask:0xf bank_mask:0xf
	v_mov_b32_dpp v207, v201 quad_perm:[1,0,3,2] row_mask:0xf bank_mask:0xf
	v_add_u32_e32 v204, 0x2c00, v204
	v_cndmask_b32_e32 v208, v200, v207, vcc
	v_cndmask_b32_e32 v209, v206, v201, vcc
	v_cvt_pk_bf16_f32 v203, v208, v209
	global_store_dword v204, v203, s[64:65]
	v_mul_f32_e32 v198, 0xbfb8aa3b, v64
	v_mul_f32_e32 v199, 0xbfb8aa3b, v65
	v_mul_f32_e32 v200, 0xbfb8aa3b, v66
	v_mul_f32_e32 v201, 0xbfb8aa3b, v67
	v_exp_f32_e32 v198, v198
	v_exp_f32_e32 v199, v199
	v_exp_f32_e32 v200, v200
	v_exp_f32_e32 v201, v201
	v_add_f32_e32 v198, 1.0, v198
	v_add_f32_e32 v199, 1.0, v199
	v_add_f32_e32 v200, 1.0, v200
	v_add_f32_e32 v201, 1.0, v201
	v_rcp_f32_e32 v198, v198
	v_rcp_f32_e32 v199, v199
	v_rcp_f32_e32 v200, v200
	v_rcp_f32_e32 v201, v201
	v_mul_f32_e32 v198, v64, v198
	v_mul_f32_e32 v199, v65, v199
	v_mul_f32_e32 v200, v66, v200
; DI bf16_t to_bf16(float a) { return (bf16_t)(pk_bf16(a, 0.f) & 0xffffu); }
; DI int crow(int i, int h) { return (i & 3) + 8 * (i >> 2) + 4 * h; }
;     DI void operator()(const f32x16 (&acc)[2][2], int row0, int col0, int r, int h, const float*) const {
;         const int hc = (col0 >> 1) + r;
; #pragma unroll
;         for (int mi = 0; mi < 2; ++mi)
; #pragma unroll
;             for (int i = 0; i < 16; ++i) {
;                 const int row = row0 + mi * 32 + crow(i, h);
;                 const float gt = acc[mi][0][i], up = acc[mi][1][i];
;                 ACT[(size_t)row * DFF + hc] = to_bf16(gt * __builtin_amdgcn_rcpf(1.f + __expf(-gt)) * up);
	v_mul_f32_e32 v201, v67, v201
	v_mul_f32_e32 v198, v80, v198
	v_mul_f32_e32 v199, v81, v199
	v_mul_f32_e32 v200, v82, v200
	v_mul_f32_e32 v201, v83, v201
	v_mov_b32_dpp v206, v198 quad_perm:[1,0,3,2] row_mask:0xf bank_mask:0xf
	v_mov_b32_dpp v207, v199 quad_perm:[1,0,3,2] row_mask:0xf bank_mask:0xf
	v_add_u32_e32 v204, 0x8400, v204
	v_cndmask_b32_e32 v208, v198, v207, vcc
	v_cndmask_b32_e32 v209, v206, v199, vcc
	v_cvt_pk_bf16_f32 v202, v208, v209
	global_store_dword v204, v202, s[64:65]
	v_mov_b32_dpp v206, v200 quad_perm:[1,0,3,2] row_mask:0xf bank_mask:0xf
	v_mov_b32_dpp v207, v201 quad_perm:[1,0,3,2] row_mask:0xf bank_mask:0xf
	v_add_u32_e32 v204, 0x2c00, v204
	v_cndmask_b32_e32 v208, v200, v207, vcc
	v_cndmask_b32_e32 v209, v206, v201, vcc
	v_cvt_pk_bf16_f32 v203, v208, v209
	global_store_dword v204, v203, s[64:65]
	v_mul_f32_e32 v198, 0xbfb8aa3b, v68
	v_mul_f32_e32 v199, 0xbfb8aa3b, v69
	v_mul_f32_e32 v200, 0xbfb8aa3b, v70
	v_mul_f32_e32 v201, 0xbfb8aa3b, v71
	v_exp_f32_e32 v198, v198
	v_exp_f32_e32 v199, v199
	v_exp_f32_e32 v200, v200
	v_exp_f32_e32 v201, v201
	v_add_f32_e32 v198, 1.0, v198
	v_add_f32_e32 v199, 1.0, v199
	v_add_f32_e32 v200, 1.0, v200
	v_add_f32_e32 v201, 1.0, v201
	v_rcp_f32_e32 v198, v198
	v_rcp_f32_e32 v199, v199
	v_rcp_f32_e32 v200, v200
	v_rcp_f32_e32 v201, v201
	v_mul_f32_e32 v198, v68, v198
	v_mul_f32_e32 v199, v69, v199
	v_mul_f32_e32 v200, v70, v200
	v_mul_f32_e32 v201, v71, v201
	v_mul_f32_e32 v198, v84, v198
	v_mul_f32_e32 v199, v85, v199
	v_mul_f32_e32 v200, v86, v200
	v_mul_f32_e32 v201, v87, v201
	v_mov_b32_dpp v206, v198 quad_perm:[1,0,3,2] row_mask:0xf bank_mask:0xf
	v_mov_b32_dpp v207, v199 quad_perm:[1,0,3,2] row_mask:0xf bank_mask:0xf
	v_add_u32_e32 v204, 0x8400, v204
	v_cndmask_b32_e32 v208, v198, v207, vcc
	v_cndmask_b32_e32 v209, v206, v199, vcc
	v_cvt_pk_bf16_f32 v202, v208, v209
	global_store_dword v204, v202, s[64:65]
	v_mov_b32_dpp v206, v200 quad_perm:[1,0,3,2] row_mask:0xf bank_mask:0xf
	v_mov_b32_dpp v207, v201 quad_perm:[1,0,3,2] row_mask:0xf bank_mask:0xf
	v_add_u32_e32 v204, 0x2c00, v204
	v_cndmask_b32_e32 v208, v200, v207, vcc
	v_cndmask_b32_e32 v209, v206, v201, vcc
	v_cvt_pk_bf16_f32 v203, v208, v209
	global_store_dword v204, v203, s[64:65]
	v_mul_f32_e32 v198, 0xbfb8aa3b, v72
	v_mul_f32_e32 v199, 0xbfb8aa3b, v73
	v_mul_f32_e32 v200, 0xbfb8aa3b, v74
	v_mul_f32_e32 v201, 0xbfb8aa3b, v75
	v_exp_f32_e32 v198, v198
	v_exp_f32_e32 v199, v199
	v_exp_f32_e32 v200, v200
	v_exp_f32_e32 v201, v201
	v_add_f32_e32 v198, 1.0, v198
	v_add_f32_e32 v199, 1.0, v199
	v_add_f32_e32 v200, 1.0, v200
	v_add_f32_e32 v201, 1.0, v201
	v_rcp_f32_e32 v198, v198
	v_rcp_f32_e32 v199, v199
	v_rcp_f32_e32 v200, v200
	v_rcp_f32_e32 v201, v201
	v_mul_f32_e32 v198, v72, v198
	v_mul_f32_e32 v199, v73, v199
	v_mul_f32_e32 v200, v74, v200
	v_mul_f32_e32 v201, v75, v201
	v_mul_f32_e32 v198, v88, v198
	v_mul_f32_e32 v199, v89, v199
	v_mul_f32_e32 v200, v90, v200
	v_mul_f32_e32 v201, v91, v201
	v_mov_b32_dpp v206, v198 quad_perm:[1,0,3,2] row_mask:0xf bank_mask:0xf
	v_mov_b32_dpp v207, v199 quad_perm:[1,0,3,2] row_mask:0xf bank_mask:0xf
	v_add_u32_e32 v204, 0x8400, v204
	v_cndmask_b32_e32 v208, v198, v207, vcc
	v_cndmask_b32_e32 v209, v206, v199, vcc
	v_cvt_pk_bf16_f32 v202, v208, v209
	global_store_dword v204, v202, s[64:65]
	v_mov_b32_dpp v206, v200 quad_perm:[1,0,3,2] row_mask:0xf bank_mask:0xf
	v_mov_b32_dpp v207, v201 quad_perm:[1,0,3,2] row_mask:0xf bank_mask:0xf
	v_add_u32_e32 v204, 0x2c00, v204
	v_cndmask_b32_e32 v208, v200, v207, vcc
	v_cndmask_b32_e32 v209, v206, v201, vcc
	v_cvt_pk_bf16_f32 v203, v208, v209
	global_store_dword v204, v203, s[64:65]
	v_mul_f32_e32 v198, 0xbfb8aa3b, v76
	v_mul_f32_e32 v199, 0xbfb8aa3b, v77
	v_mul_f32_e32 v200, 0xbfb8aa3b, v78
	v_mul_f32_e32 v201, 0xbfb8aa3b, v79
	v_exp_f32_e32 v198, v198
	v_exp_f32_e32 v199, v199
	v_exp_f32_e32 v200, v200
	v_exp_f32_e32 v201, v201
	v_add_f32_e32 v198, 1.0, v198
	v_add_f32_e32 v199, 1.0, v199
	v_add_f32_e32 v200, 1.0, v200
	v_add_f32_e32 v201, 1.0, v201
	v_rcp_f32_e32 v198, v198
	v_rcp_f32_e32 v199, v199
	v_rcp_f32_e32 v200, v200
	v_rcp_f32_e32 v201, v201
	v_mul_f32_e32 v198, v76, v198
	v_mul_f32_e32 v199, v77, v199
	v_mul_f32_e32 v200, v78, v200
	v_mul_f32_e32 v201, v79, v201
	v_mul_f32_e32 v198, v92, v198
	v_mul_f32_e32 v199, v93, v199
	v_mul_f32_e32 v200, v94, v200
	v_mul_f32_e32 v201, v95, v201
	v_mov_b32_dpp v206, v198 quad_perm:[1,0,3,2] row_mask:0xf bank_mask:0xf
	v_mov_b32_dpp v207, v199 quad_perm:[1,0,3,2] row_mask:0xf bank_mask:0xf
	v_add_u32_e32 v204, 0x8400, v204
	v_cndmask_b32_e32 v208, v198, v207, vcc
	v_cndmask_b32_e32 v209, v206, v199, vcc
	v_cvt_pk_bf16_f32 v202, v208, v209
	global_store_dword v204, v202, s[64:65]
	v_mov_b32_dpp v206, v200 quad_perm:[1,0,3,2] row_mask:0xf bank_mask:0xf
	v_mov_b32_dpp v207, v201 quad_perm:[1,0,3,2] row_mask:0xf bank_mask:0xf
	v_add_u32_e32 v204, 0x2c00, v204
	v_cndmask_b32_e32 v208, v200, v207, vcc
	v_cndmask_b32_e32 v209, v206, v201, vcc
	v_cvt_pk_bf16_f32 v203, v208, v209
	global_store_dword v204, v203, s[64:65]
	v_mul_f32_e32 v198, 0xbfb8aa3b, v32
	v_mul_f32_e32 v199, 0xbfb8aa3b, v33
	v_mul_f32_e32 v200, 0xbfb8aa3b, v34
	v_mul_f32_e32 v201, 0xbfb8aa3b, v35
	v_exp_f32_e32 v198, v198
	v_exp_f32_e32 v199, v199
	v_exp_f32_e32 v200, v200
	v_exp_f32_e32 v201, v201
	v_add_f32_e32 v198, 1.0, v198
	v_add_f32_e32 v199, 1.0, v199
	v_add_f32_e32 v200, 1.0, v200
	v_add_f32_e32 v201, 1.0, v201
	v_rcp_f32_e32 v198, v198
	v_rcp_f32_e32 v199, v199
	v_rcp_f32_e32 v200, v200
	v_rcp_f32_e32 v201, v201
	v_mul_f32_e32 v198, v32, v198
	v_mul_f32_e32 v199, v33, v199
	v_mul_f32_e32 v200, v34, v200
	v_mul_f32_e32 v201, v35, v201
; DI bf16_t to_bf16(float a) { return (bf16_t)(pk_bf16(a, 0.f) & 0xffffu); }
; DI int crow(int i, int h) { return (i & 3) + 8 * (i >> 2) + 4 * h; }
;     DI void operator()(const f32x16 (&acc)[2][2], int row0, int col0, int r, int h, const float*) const {
;         const int hc = (col0 >> 1) + r;
; #pragma unroll
;         for (int mi = 0; mi < 2; ++mi)
; #pragma unroll
;             for (int i = 0; i < 16; ++i) {
;                 const int row = row0 + mi * 32 + crow(i, h);
;                 const float gt = acc[mi][0][i], up = acc[mi][1][i];
;                 ACT[(size_t)row * DFF + hc] = to_bf16(gt * __builtin_amdgcn_rcpf(1.f + __expf(-gt)) * up);
;             }
	v_mul_f32_e32 v198, v48, v198
	v_mul_f32_e32 v199, v49, v199
	v_mul_f32_e32 v200, v50, v200
	v_mul_f32_e32 v201, v51, v201
	v_mov_b32_dpp v206, v198 quad_perm:[1,0,3,2] row_mask:0xf bank_mask:0xf
	v_mov_b32_dpp v207, v199 quad_perm:[1,0,3,2] row_mask:0xf bank_mask:0xf
	v_add_u32_e32 v204, 0x8400, v204
	v_cndmask_b32_e32 v208, v198, v207, vcc
	v_cndmask_b32_e32 v209, v206, v199, vcc
	v_cvt_pk_bf16_f32 v202, v208, v209
	global_store_dword v204, v202, s[64:65]
	v_mov_b32_dpp v206, v200 quad_perm:[1,0,3,2] row_mask:0xf bank_mask:0xf
	v_mov_b32_dpp v207, v201 quad_perm:[1,0,3,2] row_mask:0xf bank_mask:0xf
	v_add_u32_e32 v204, 0x2c00, v204
	v_cndmask_b32_e32 v208, v200, v207, vcc
	v_cndmask_b32_e32 v209, v206, v201, vcc
	v_cvt_pk_bf16_f32 v203, v208, v209
	global_store_dword v204, v203, s[64:65]
	v_mul_f32_e32 v198, 0xbfb8aa3b, v36
	v_mul_f32_e32 v199, 0xbfb8aa3b, v37
	v_mul_f32_e32 v200, 0xbfb8aa3b, v38
	v_mul_f32_e32 v201, 0xbfb8aa3b, v39
	v_exp_f32_e32 v198, v198
	v_exp_f32_e32 v199, v199
	v_exp_f32_e32 v200, v200
	v_exp_f32_e32 v201, v201
	v_add_f32_e32 v198, 1.0, v198
	v_add_f32_e32 v199, 1.0, v199
	v_add_f32_e32 v200, 1.0, v200
	v_add_f32_e32 v201, 1.0, v201
	v_rcp_f32_e32 v198, v198
	v_rcp_f32_e32 v199, v199
	v_rcp_f32_e32 v200, v200
	v_rcp_f32_e32 v201, v201
	v_mul_f32_e32 v198, v36, v198
	v_mul_f32_e32 v199, v37, v199
	v_mul_f32_e32 v200, v38, v200
	v_mul_f32_e32 v201, v39, v201
	v_mul_f32_e32 v198, v52, v198
	v_mul_f32_e32 v199, v53, v199
	v_mul_f32_e32 v200, v54, v200
	v_mul_f32_e32 v201, v55, v201
	v_mov_b32_dpp v206, v198 quad_perm:[1,0,3,2] row_mask:0xf bank_mask:0xf
	v_mov_b32_dpp v207, v199 quad_perm:[1,0,3,2] row_mask:0xf bank_mask:0xf
	v_add_u32_e32 v204, 0x8400, v204
	v_cndmask_b32_e32 v208, v198, v207, vcc
	v_cndmask_b32_e32 v209, v206, v199, vcc
	v_cvt_pk_bf16_f32 v202, v208, v209
	global_store_dword v204, v202, s[64:65]
	v_mov_b32_dpp v206, v200 quad_perm:[1,0,3,2] row_mask:0xf bank_mask:0xf
	v_mov_b32_dpp v207, v201 quad_perm:[1,0,3,2] row_mask:0xf bank_mask:0xf
	v_add_u32_e32 v204, 0x2c00, v204
	v_cndmask_b32_e32 v208, v200, v207, vcc
	v_cndmask_b32_e32 v209, v206, v201, vcc
	v_cvt_pk_bf16_f32 v203, v208, v209
	global_store_dword v204, v203, s[64:65]
	v_mul_f32_e32 v198, 0xbfb8aa3b, v40
	v_mul_f32_e32 v199, 0xbfb8aa3b, v41
	v_mul_f32_e32 v200, 0xbfb8aa3b, v42
	v_mul_f32_e32 v201, 0xbfb8aa3b, v43
	v_exp_f32_e32 v198, v198
	v_exp_f32_e32 v199, v199
	v_exp_f32_e32 v200, v200
	v_exp_f32_e32 v201, v201
	v_add_f32_e32 v198, 1.0, v198
	v_add_f32_e32 v199, 1.0, v199
	v_add_f32_e32 v200, 1.0, v200
	v_add_f32_e32 v201, 1.0, v201
	v_rcp_f32_e32 v198, v198
	v_rcp_f32_e32 v199, v199
	v_rcp_f32_e32 v200, v200
	v_rcp_f32_e32 v201, v201
	v_mul_f32_e32 v198, v40, v198
	v_mul_f32_e32 v199, v41, v199
	v_mul_f32_e32 v200, v42, v200
	v_mul_f32_e32 v201, v43, v201
	v_mul_f32_e32 v198, v56, v198
	v_mul_f32_e32 v199, v57, v199
	v_mul_f32_e32 v200, v58, v200
	v_mul_f32_e32 v201, v59, v201
	v_mov_b32_dpp v206, v198 quad_perm:[1,0,3,2] row_mask:0xf bank_mask:0xf
	v_mov_b32_dpp v207, v199 quad_perm:[1,0,3,2] row_mask:0xf bank_mask:0xf
	v_add_u32_e32 v204, 0x8400, v204
	v_cndmask_b32_e32 v208, v198, v207, vcc
	v_cndmask_b32_e32 v209, v206, v199, vcc
	v_cvt_pk_bf16_f32 v202, v208, v209
	global_store_dword v204, v202, s[64:65]
	v_mov_b32_dpp v206, v200 quad_perm:[1,0,3,2] row_mask:0xf bank_mask:0xf
	v_mov_b32_dpp v207, v201 quad_perm:[1,0,3,2] row_mask:0xf bank_mask:0xf
	v_add_u32_e32 v204, 0x2c00, v204
	v_cndmask_b32_e32 v208, v200, v207, vcc
	v_cndmask_b32_e32 v209, v206, v201, vcc
	v_cvt_pk_bf16_f32 v203, v208, v209
	global_store_dword v204, v203, s[64:65]
	v_mul_f32_e32 v198, 0xbfb8aa3b, v44
	v_mul_f32_e32 v199, 0xbfb8aa3b, v45
	v_mul_f32_e32 v200, 0xbfb8aa3b, v46
	v_mul_f32_e32 v201, 0xbfb8aa3b, v47
	v_exp_f32_e32 v198, v198
	v_exp_f32_e32 v199, v199
	v_exp_f32_e32 v200, v200
	v_exp_f32_e32 v201, v201
	v_add_f32_e32 v198, 1.0, v198
	v_add_f32_e32 v199, 1.0, v199
	v_add_f32_e32 v200, 1.0, v200
	v_add_f32_e32 v201, 1.0, v201
	v_rcp_f32_e32 v198, v198
	v_rcp_f32_e32 v199, v199
	v_rcp_f32_e32 v200, v200
	v_rcp_f32_e32 v201, v201
	v_mul_f32_e32 v198, v44, v198
	v_mul_f32_e32 v199, v45, v199
	v_mul_f32_e32 v200, v46, v200
	v_mul_f32_e32 v201, v47, v201
	v_mul_f32_e32 v198, v60, v198
	v_mul_f32_e32 v199, v61, v199
	v_mul_f32_e32 v200, v62, v200
	v_mul_f32_e32 v201, v63, v201
	v_mov_b32_dpp v206, v198 quad_perm:[1,0,3,2] row_mask:0xf bank_mask:0xf
	v_mov_b32_dpp v207, v199 quad_perm:[1,0,3,2] row_mask:0xf bank_mask:0xf
	v_add_u32_e32 v204, 0x8400, v204
	v_cndmask_b32_e32 v208, v198, v207, vcc
	v_cndmask_b32_e32 v209, v206, v199, vcc
	v_cvt_pk_bf16_f32 v202, v208, v209
	global_store_dword v204, v202, s[64:65]
	v_mov_b32_dpp v206, v200 quad_perm:[1,0,3,2] row_mask:0xf bank_mask:0xf
	v_mov_b32_dpp v207, v201 quad_perm:[1,0,3,2] row_mask:0xf bank_mask:0xf
	v_add_u32_e32 v204, 0x2c00, v204
	v_cndmask_b32_e32 v208, v200, v207, vcc
	v_cndmask_b32_e32 v209, v206, v201, vcc
	v_cvt_pk_bf16_f32 v203, v208, v209
	global_store_dword v204, v203, s[64:65]
	v_mul_f32_e32 v198, 0xbfb8aa3b, v0
	v_mul_f32_e32 v199, 0xbfb8aa3b, v1
	v_mul_f32_e32 v200, 0xbfb8aa3b, v2
	v_mul_f32_e32 v201, 0xbfb8aa3b, v3
	v_exp_f32_e32 v198, v198
	v_exp_f32_e32 v199, v199
	v_exp_f32_e32 v200, v200
	v_exp_f32_e32 v201, v201
	v_add_f32_e32 v198, 1.0, v198
	v_add_f32_e32 v199, 1.0, v199
	v_add_f32_e32 v200, 1.0, v200
	v_add_f32_e32 v201, 1.0, v201
	v_rcp_f32_e32 v198, v198
	v_rcp_f32_e32 v199, v199
	v_rcp_f32_e32 v200, v200
	v_rcp_f32_e32 v201, v201
	v_mul_f32_e32 v198, v0, v198
	v_mul_f32_e32 v199, v1, v199
	v_mul_f32_e32 v200, v2, v200
	v_mul_f32_e32 v201, v3, v201
	v_mul_f32_e32 v198, v16, v198
; DI bf16_t to_bf16(float a) { return (bf16_t)(pk_bf16(a, 0.f) & 0xffffu); }
; DI int crow(int i, int h) { return (i & 3) + 8 * (i >> 2) + 4 * h; }
;     DI void operator()(const f32x16 (&acc)[2][2], int row0, int col0, int r, int h, const float*) const {
;         const int hc = (col0 >> 1) + r;
; #pragma unroll
;         for (int mi = 0; mi < 2; ++mi)
; #pragma unroll
;             for (int i = 0; i < 16; ++i) {
;                 const int row = row0 + mi * 32 + crow(i, h);
;                 const float gt = acc[mi][0][i], up = acc[mi][1][i];
;                 ACT[(size_t)row * DFF + hc] = to_bf16(gt * __builtin_amdgcn_rcpf(1.f + __expf(-gt)) * up);
;             }
; template <class Epi>
; DI void gemm_phase(const bf16_t* A, const bf16_t* Bt, int K, int mtiles, int ntiles, const Epi& epi, char* smem) {
;     ...
;         for (int i = 0; i < 4; ++i) { ra[i] = *(const u32x4*)(Ag + (size_t)(64 * i) * K); rb[i] = *(const u32x4*)(Bg + (size_t)(64 * i) * K); }
; #pragma unroll
;         for (int i = 0; i < 4; ++i) { *(u32x4*)(sA + (srow + 64 * i) * 72 + skc) = ra[i]; *(u32x4*)(sB + (srow + 64 * i) * 72 + skc) = rb[i]; }
	v_mul_f32_e32 v199, v17, v199
	v_mul_f32_e32 v200, v18, v200
	v_mul_f32_e32 v201, v19, v201
	v_mov_b32_dpp v206, v198 quad_perm:[1,0,3,2] row_mask:0xf bank_mask:0xf
	v_mov_b32_dpp v207, v199 quad_perm:[1,0,3,2] row_mask:0xf bank_mask:0xf
	v_add_u32_e32 v204, 0x8400, v204
	v_cndmask_b32_e32 v208, v198, v207, vcc
	v_cndmask_b32_e32 v209, v206, v199, vcc
	v_cvt_pk_bf16_f32 v202, v208, v209
	global_store_dword v204, v202, s[64:65]
	v_mov_b32_dpp v206, v200 quad_perm:[1,0,3,2] row_mask:0xf bank_mask:0xf
	v_mov_b32_dpp v207, v201 quad_perm:[1,0,3,2] row_mask:0xf bank_mask:0xf
	v_add_u32_e32 v204, 0x2c00, v204
	v_cndmask_b32_e32 v208, v200, v207, vcc
	v_cndmask_b32_e32 v209, v206, v201, vcc
	v_cvt_pk_bf16_f32 v203, v208, v209
	global_store_dword v204, v203, s[64:65]
	v_mul_f32_e32 v198, 0xbfb8aa3b, v4
	v_mul_f32_e32 v199, 0xbfb8aa3b, v5
	v_mul_f32_e32 v200, 0xbfb8aa3b, v6
	v_mul_f32_e32 v201, 0xbfb8aa3b, v7
	v_exp_f32_e32 v198, v198
	v_exp_f32_e32 v199, v199
	v_exp_f32_e32 v200, v200
	v_exp_f32_e32 v201, v201
	v_add_f32_e32 v198, 1.0, v198
	v_add_f32_e32 v199, 1.0, v199
	v_add_f32_e32 v200, 1.0, v200
	v_add_f32_e32 v201, 1.0, v201
	v_rcp_f32_e32 v198, v198
	v_rcp_f32_e32 v199, v199
	v_rcp_f32_e32 v200, v200
	v_rcp_f32_e32 v201, v201
	v_mul_f32_e32 v198, v4, v198
	v_mul_f32_e32 v199, v5, v199
	v_mul_f32_e32 v200, v6, v200
	v_mul_f32_e32 v201, v7, v201
	v_mul_f32_e32 v198, v20, v198
	v_mul_f32_e32 v199, v21, v199
	v_mul_f32_e32 v200, v22, v200
	v_mul_f32_e32 v201, v23, v201
	v_mov_b32_dpp v206, v198 quad_perm:[1,0,3,2] row_mask:0xf bank_mask:0xf
	v_mov_b32_dpp v207, v199 quad_perm:[1,0,3,2] row_mask:0xf bank_mask:0xf
	v_add_u32_e32 v204, 0x8400, v204
	v_cndmask_b32_e32 v208, v198, v207, vcc
	v_cndmask_b32_e32 v209, v206, v199, vcc
	v_cvt_pk_bf16_f32 v202, v208, v209
	global_store_dword v204, v202, s[64:65]
	v_mov_b32_dpp v206, v200 quad_perm:[1,0,3,2] row_mask:0xf bank_mask:0xf
	v_mov_b32_dpp v207, v201 quad_perm:[1,0,3,2] row_mask:0xf bank_mask:0xf
	v_add_u32_e32 v204, 0x2c00, v204
	v_cndmask_b32_e32 v208, v200, v207, vcc
	v_cndmask_b32_e32 v209, v206, v201, vcc
	v_cvt_pk_bf16_f32 v203, v208, v209
	global_store_dword v204, v203, s[64:65]
	v_mul_f32_e32 v198, 0xbfb8aa3b, v8
	v_mul_f32_e32 v199, 0xbfb8aa3b, v9
	v_mul_f32_e32 v200, 0xbfb8aa3b, v10
	v_mul_f32_e32 v201, 0xbfb8aa3b, v11
	v_exp_f32_e32 v198, v198
	v_exp_f32_e32 v199, v199
	v_exp_f32_e32 v200, v200
	v_exp_f32_e32 v201, v201
	v_add_f32_e32 v198, 1.0, v198
	v_add_f32_e32 v199, 1.0, v199
	v_add_f32_e32 v200, 1.0, v200
	v_add_f32_e32 v201, 1.0, v201
	v_rcp_f32_e32 v198, v198
	v_rcp_f32_e32 v199, v199
	v_rcp_f32_e32 v200, v200
	v_rcp_f32_e32 v201, v201
	v_mul_f32_e32 v198, v8, v198
	v_mul_f32_e32 v199, v9, v199
	v_mul_f32_e32 v200, v10, v200
	v_mul_f32_e32 v201, v11, v201
	v_mul_f32_e32 v198, v24, v198
	v_mul_f32_e32 v199, v25, v199
	v_mul_f32_e32 v200, v26, v200
	v_mul_f32_e32 v201, v27, v201
	v_mov_b32_dpp v206, v198 quad_perm:[1,0,3,2] row_mask:0xf bank_mask:0xf
	v_mov_b32_dpp v207, v199 quad_perm:[1,0,3,2] row_mask:0xf bank_mask:0xf
	v_add_u32_e32 v204, 0x8400, v204
	v_cndmask_b32_e32 v208, v198, v207, vcc
	v_cndmask_b32_e32 v209, v206, v199, vcc
	v_cvt_pk_bf16_f32 v202, v208, v209
	global_store_dword v204, v202, s[64:65]
	v_mov_b32_dpp v206, v200 quad_perm:[1,0,3,2] row_mask:0xf bank_mask:0xf
	v_mov_b32_dpp v207, v201 quad_perm:[1,0,3,2] row_mask:0xf bank_mask:0xf
	v_add_u32_e32 v204, 0x2c00, v204
	v_cndmask_b32_e32 v208, v200, v207, vcc
	v_cndmask_b32_e32 v209, v206, v201, vcc
	v_cvt_pk_bf16_f32 v203, v208, v209
	global_store_dword v204, v203, s[64:65]
	v_mul_f32_e32 v198, 0xbfb8aa3b, v12
	v_mul_f32_e32 v199, 0xbfb8aa3b, v13
	v_mul_f32_e32 v200, 0xbfb8aa3b, v14
	v_mul_f32_e32 v201, 0xbfb8aa3b, v15
	v_exp_f32_e32 v198, v198
	v_exp_f32_e32 v199, v199
	v_exp_f32_e32 v200, v200
	v_exp_f32_e32 v201, v201
	v_add_f32_e32 v198, 1.0, v198
	v_add_f32_e32 v199, 1.0, v199
	v_add_f32_e32 v200, 1.0, v200
	v_add_f32_e32 v201, 1.0, v201
	v_rcp_f32_e32 v198, v198
	v_rcp_f32_e32 v199, v199
	v_rcp_f32_e32 v200, v200
	v_rcp_f32_e32 v201, v201
	v_mul_f32_e32 v198, v12, v198
	v_mul_f32_e32 v199, v13, v199
	v_mul_f32_e32 v200, v14, v200
	v_mul_f32_e32 v201, v15, v201
	v_mul_f32_e32 v198, v28, v198
	v_mul_f32_e32 v199, v29, v199
	v_mul_f32_e32 v200, v30, v200
	v_mul_f32_e32 v201, v31, v201
	v_mov_b32_dpp v206, v198 quad_perm:[1,0,3,2] row_mask:0xf bank_mask:0xf
	v_mov_b32_dpp v207, v199 quad_perm:[1,0,3,2] row_mask:0xf bank_mask:0xf
	v_add_u32_e32 v204, 0x8400, v204
	v_cndmask_b32_e32 v208, v198, v207, vcc
	v_cndmask_b32_e32 v209, v206, v199, vcc
	v_cvt_pk_bf16_f32 v202, v208, v209
	global_store_dword v204, v202, s[64:65]
	v_mov_b32_dpp v206, v200 quad_perm:[1,0,3,2] row_mask:0xf bank_mask:0xf
	v_mov_b32_dpp v207, v201 quad_perm:[1,0,3,2] row_mask:0xf bank_mask:0xf
	v_add_u32_e32 v204, 0x2c00, v204
	v_cndmask_b32_e32 v208, v200, v207, vcc
	v_cndmask_b32_e32 v209, v206, v201, vcc
	v_cvt_pk_bf16_f32 v203, v208, v209
	global_store_dword v204, v203, s[64:65]
	s_waitcnt vmcnt(32)
	ds_write_b128 v153, v[156:159]
	ds_write_b128 v154, v[170:173]
	ds_write_b128 v153, v[174:177] offset:9216
	ds_write_b128 v154, v[178:181] offset:9216
	ds_write_b128 v153, v[182:185] offset:18432
	ds_write_b128 v154, v[186:189] offset:18432
	ds_write_b128 v153, v[190:193] offset:27648
	ds_write_b128 v154, v[194:197] offset:27648
	s_branch .Lsw_kloop
; DI bf16_t to_bf16(float a) { return (bf16_t)(pk_bf16(a, 0.f) & 0xffffu); }
; DI int crow(int i, int h) { return (i & 3) + 8 * (i >> 2) + 4 * h; }
;     DI void operator()(const f32x16 (&acc)[2][2], int row0, int col0, int r, int h, const float*) const {
;         const int hc = (col0 >> 1) + r;
; #pragma unroll
;         for (int mi = 0; mi < 2; ++mi)
; #pragma unroll
;             for (int i = 0; i < 16; ++i) {
;                 const int row = row0 + mi * 32 + crow(i, h);
;                 const float gt = acc[mi][0][i], up = acc[mi][1][i];
;                 ACT[(size_t)row * DFF + hc] = to_bf16(gt * __builtin_amdgcn_rcpf(1.f + __expf(-gt)) * up);
;             }
.Lsw_last:
	v_and_b32_e32 v205, 1, v148
	v_cmp_eq_u32_e32 vcc, 1, v205
	s_nop 1
	v_cndmask_b32_e32 v204, v204, v210, vcc
	v_mul_f32_e32 v198, 0xbfb8aa3b, v112
	v_mul_f32_e32 v199, 0xbfb8aa3b, v113
	v_mul_f32_e32 v200, 0xbfb8aa3b, v114
	v_mul_f32_e32 v201, 0xbfb8aa3b, v115
	v_exp_f32_e32 v198, v198
	v_exp_f32_e32 v199, v199
	v_exp_f32_e32 v200, v200
	v_exp_f32_e32 v201, v201
	v_add_f32_e32 v198, 1.0, v198
	v_add_f32_e32 v199, 1.0, v199
	v_add_f32_e32 v200, 1.0, v200
	v_add_f32_e32 v201, 1.0, v201
	v_rcp_f32_e32 v198, v198
	v_rcp_f32_e32 v199, v199
	v_rcp_f32_e32 v200, v200
	v_rcp_f32_e32 v201, v201
	v_mul_f32_e32 v198, v112, v198
	v_mul_f32_e32 v199, v113, v199
	v_mul_f32_e32 v200, v114, v200
	v_mul_f32_e32 v201, v115, v201
	v_mul_f32_e32 v198, v96, v198
	v_mul_f32_e32 v199, v97, v199
	v_mul_f32_e32 v200, v98, v200
	v_mul_f32_e32 v201, v99, v201
	v_mov_b32_dpp v206, v198 quad_perm:[1,0,3,2] row_mask:0xf bank_mask:0xf
	v_mov_b32_dpp v207, v199 quad_perm:[1,0,3,2] row_mask:0xf bank_mask:0xf
	v_cndmask_b32_e32 v208, v198, v207, vcc
	v_cndmask_b32_e32 v209, v206, v199, vcc
	v_cvt_pk_bf16_f32 v202, v208, v209
	global_store_dword v204, v202, s[64:65]
	v_mov_b32_dpp v206, v200 quad_perm:[1,0,3,2] row_mask:0xf bank_mask:0xf
	v_mov_b32_dpp v207, v201 quad_perm:[1,0,3,2] row_mask:0xf bank_mask:0xf
	v_add_u32_e32 v204, 0x2c00, v204
	v_cndmask_b32_e32 v208, v200, v207, vcc
	v_cndmask_b32_e32 v209, v206, v201, vcc
	v_cvt_pk_bf16_f32 v203, v208, v209
	global_store_dword v204, v203, s[64:65]
	v_mul_f32_e32 v198, 0xbfb8aa3b, v116
	v_mul_f32_e32 v199, 0xbfb8aa3b, v117
	v_mul_f32_e32 v200, 0xbfb8aa3b, v118
	v_mul_f32_e32 v201, 0xbfb8aa3b, v119
	v_exp_f32_e32 v198, v198
	v_exp_f32_e32 v199, v199
	v_exp_f32_e32 v200, v200
	v_exp_f32_e32 v201, v201
	v_add_f32_e32 v198, 1.0, v198
	v_add_f32_e32 v199, 1.0, v199
	v_add_f32_e32 v200, 1.0, v200
	v_add_f32_e32 v201, 1.0, v201
	v_rcp_f32_e32 v198, v198
	v_rcp_f32_e32 v199, v199
	v_rcp_f32_e32 v200, v200
	v_rcp_f32_e32 v201, v201
	v_mul_f32_e32 v198, v116, v198
	v_mul_f32_e32 v199, v117, v199
	v_mul_f32_e32 v200, v118, v200
	v_mul_f32_e32 v201, v119, v201
	v_mul_f32_e32 v198, v100, v198
	v_mul_f32_e32 v199, v101, v199
	v_mul_f32_e32 v200, v102, v200
	v_mul_f32_e32 v201, v103, v201
	v_mov_b32_dpp v206, v198 quad_perm:[1,0,3,2] row_mask:0xf bank_mask:0xf
	v_mov_b32_dpp v207, v199 quad_perm:[1,0,3,2] row_mask:0xf bank_mask:0xf
	v_add_u32_e32 v204, 0x8400, v204
	v_cndmask_b32_e32 v208, v198, v207, vcc
	v_cndmask_b32_e32 v209, v206, v199, vcc
	v_cvt_pk_bf16_f32 v202, v208, v209
	global_store_dword v204, v202, s[64:65]
	v_mov_b32_dpp v206, v200 quad_perm:[1,0,3,2] row_mask:0xf bank_mask:0xf
	v_mov_b32_dpp v207, v201 quad_perm:[1,0,3,2] row_mask:0xf bank_mask:0xf
	v_add_u32_e32 v204, 0x2c00, v204
	v_cndmask_b32_e32 v208, v200, v207, vcc
	v_cndmask_b32_e32 v209, v206, v201, vcc
	v_cvt_pk_bf16_f32 v203, v208, v209
	global_store_dword v204, v203, s[64:65]
	v_mul_f32_e32 v198, 0xbfb8aa3b, v120
	v_mul_f32_e32 v199, 0xbfb8aa3b, v121
	v_mul_f32_e32 v200, 0xbfb8aa3b, v122
	v_mul_f32_e32 v201, 0xbfb8aa3b, v123
	v_exp_f32_e32 v198, v198
	v_exp_f32_e32 v199, v199
	v_exp_f32_e32 v200, v200
	v_exp_f32_e32 v201, v201
	v_add_f32_e32 v198, 1.0, v198
	v_add_f32_e32 v199, 1.0, v199
	v_add_f32_e32 v200, 1.0, v200
	v_add_f32_e32 v201, 1.0, v201
	v_rcp_f32_e32 v198, v198
	v_rcp_f32_e32 v199, v199
	v_rcp_f32_e32 v200, v200
	v_rcp_f32_e32 v201, v201
	v_mul_f32_e32 v198, v120, v198
	v_mul_f32_e32 v199, v121, v199
	v_mul_f32_e32 v200, v122, v200
	v_mul_f32_e32 v201, v123, v201
	v_mul_f32_e32 v198, v104, v198
	v_mul_f32_e32 v199, v105, v199
	v_mul_f32_e32 v200, v106, v200
	v_mul_f32_e32 v201, v107, v201
	v_mov_b32_dpp v206, v198 quad_perm:[1,0,3,2] row_mask:0xf bank_mask:0xf
	v_mov_b32_dpp v207, v199 quad_perm:[1,0,3,2] row_mask:0xf bank_mask:0xf
	v_add_u32_e32 v204, 0x8400, v204
	v_cndmask_b32_e32 v208, v198, v207, vcc
	v_cndmask_b32_e32 v209, v206, v199, vcc
	v_cvt_pk_bf16_f32 v202, v208, v209
	global_store_dword v204, v202, s[64:65]
	v_mov_b32_dpp v206, v200 quad_perm:[1,0,3,2] row_mask:0xf bank_mask:0xf
	v_mov_b32_dpp v207, v201 quad_perm:[1,0,3,2] row_mask:0xf bank_mask:0xf
	v_add_u32_e32 v204, 0x2c00, v204
	v_cndmask_b32_e32 v208, v200, v207, vcc
	v_cndmask_b32_e32 v209, v206, v201, vcc
	v_cvt_pk_bf16_f32 v203, v208, v209
	global_store_dword v204, v203, s[64:65]
	v_mul_f32_e32 v198, 0xbfb8aa3b, v124
	v_mul_f32_e32 v199, 0xbfb8aa3b, v125
	v_mul_f32_e32 v200, 0xbfb8aa3b, v126
	v_mul_f32_e32 v201, 0xbfb8aa3b, v127
	v_exp_f32_e32 v198, v198
	v_exp_f32_e32 v199, v199
	v_exp_f32_e32 v200, v200
	v_exp_f32_e32 v201, v201
	v_add_f32_e32 v198, 1.0, v198
	v_add_f32_e32 v199, 1.0, v199
	v_add_f32_e32 v200, 1.0, v200
	v_add_f32_e32 v201, 1.0, v201
	v_rcp_f32_e32 v198, v198
	v_rcp_f32_e32 v199, v199
	v_rcp_f32_e32 v200, v200
	v_rcp_f32_e32 v201, v201
	v_mul_f32_e32 v198, v124, v198
	v_mul_f32_e32 v199, v125, v199
	v_mul_f32_e32 v200, v126, v200
	v_mul_f32_e32 v201, v127, v201
	v_mul_f32_e32 v198, v108, v198
	v_mul_f32_e32 v199, v109, v199
	v_mul_f32_e32 v200, v110, v200
	v_mul_f32_e32 v201, v111, v201
	v_mov_b32_dpp v206, v198 quad_perm:[1,0,3,2] row_mask:0xf bank_mask:0xf
	v_mov_b32_dpp v207, v199 quad_perm:[1,0,3,2] row_mask:0xf bank_mask:0xf
	v_add_u32_e32 v204, 0x8400, v204
	v_cndmask_b32_e32 v208, v198, v207, vcc
	v_cndmask_b32_e32 v209, v206, v199, vcc
	v_cvt_pk_bf16_f32 v202, v208, v209
	global_store_dword v204, v202, s[64:65]
	v_mov_b32_dpp v206, v200 quad_perm:[1,0,3,2] row_mask:0xf bank_mask:0xf
	v_mov_b32_dpp v207, v201 quad_perm:[1,0,3,2] row_mask:0xf bank_mask:0xf
	v_add_u32_e32 v204, 0x2c00, v204
	v_cndmask_b32_e32 v208, v200, v207, vcc
; DI bf16_t to_bf16(float a) { return (bf16_t)(pk_bf16(a, 0.f) & 0xffffu); }
; DI int crow(int i, int h) { return (i & 3) + 8 * (i >> 2) + 4 * h; }
;     DI void operator()(const f32x16 (&acc)[2][2], int row0, int col0, int r, int h, const float*) const {
;         const int hc = (col0 >> 1) + r;
; #pragma unroll
;         for (int mi = 0; mi < 2; ++mi)
; #pragma unroll
;             for (int i = 0; i < 16; ++i) {
;                 const int row = row0 + mi * 32 + crow(i, h);
;                 const float gt = acc[mi][0][i], up = acc[mi][1][i];
;                 ACT[(size_t)row * DFF + hc] = to_bf16(gt * __builtin_amdgcn_rcpf(1.f + __expf(-gt)) * up);
;             }
	v_cndmask_b32_e32 v209, v206, v201, vcc
	v_cvt_pk_bf16_f32 v203, v208, v209
	global_store_dword v204, v203, s[64:65]
	v_mul_f32_e32 v198, 0xbfb8aa3b, v64
	v_mul_f32_e32 v199, 0xbfb8aa3b, v65
	v_mul_f32_e32 v200, 0xbfb8aa3b, v66
	v_mul_f32_e32 v201, 0xbfb8aa3b, v67
	v_exp_f32_e32 v198, v198
	v_exp_f32_e32 v199, v199
	v_exp_f32_e32 v200, v200
	v_exp_f32_e32 v201, v201
	v_add_f32_e32 v198, 1.0, v198
	v_add_f32_e32 v199, 1.0, v199
	v_add_f32_e32 v200, 1.0, v200
	v_add_f32_e32 v201, 1.0, v201
	v_rcp_f32_e32 v198, v198
	v_rcp_f32_e32 v199, v199
	v_rcp_f32_e32 v200, v200
	v_rcp_f32_e32 v201, v201
	v_mul_f32_e32 v198, v64, v198
	v_mul_f32_e32 v199, v65, v199
	v_mul_f32_e32 v200, v66, v200
	v_mul_f32_e32 v201, v67, v201
	v_mul_f32_e32 v198, v80, v198
	v_mul_f32_e32 v199, v81, v199
	v_mul_f32_e32 v200, v82, v200
	v_mul_f32_e32 v201, v83, v201
	v_mov_b32_dpp v206, v198 quad_perm:[1,0,3,2] row_mask:0xf bank_mask:0xf
	v_mov_b32_dpp v207, v199 quad_perm:[1,0,3,2] row_mask:0xf bank_mask:0xf
	v_add_u32_e32 v204, 0x8400, v204
	v_cndmask_b32_e32 v208, v198, v207, vcc
	v_cndmask_b32_e32 v209, v206, v199, vcc
	v_cvt_pk_bf16_f32 v202, v208, v209
	global_store_dword v204, v202, s[64:65]
	v_mov_b32_dpp v206, v200 quad_perm:[1,0,3,2] row_mask:0xf bank_mask:0xf
	v_mov_b32_dpp v207, v201 quad_perm:[1,0,3,2] row_mask:0xf bank_mask:0xf
	v_add_u32_e32 v204, 0x2c00, v204
	v_cndmask_b32_e32 v208, v200, v207, vcc
	v_cndmask_b32_e32 v209, v206, v201, vcc
	v_cvt_pk_bf16_f32 v203, v208, v209
	global_store_dword v204, v203, s[64:65]
	v_mul_f32_e32 v198, 0xbfb8aa3b, v68
	v_mul_f32_e32 v199, 0xbfb8aa3b, v69
	v_mul_f32_e32 v200, 0xbfb8aa3b, v70
	v_mul_f32_e32 v201, 0xbfb8aa3b, v71
	v_exp_f32_e32 v198, v198
	v_exp_f32_e32 v199, v199
	v_exp_f32_e32 v200, v200
	v_exp_f32_e32 v201, v201
	v_add_f32_e32 v198, 1.0, v198
	v_add_f32_e32 v199, 1.0, v199
	v_add_f32_e32 v200, 1.0, v200
	v_add_f32_e32 v201, 1.0, v201
	v_rcp_f32_e32 v198, v198
	v_rcp_f32_e32 v199, v199
	v_rcp_f32_e32 v200, v200
	v_rcp_f32_e32 v201, v201
	v_mul_f32_e32 v198, v68, v198
	v_mul_f32_e32 v199, v69, v199
	v_mul_f32_e32 v200, v70, v200
	v_mul_f32_e32 v201, v71, v201
	v_mul_f32_e32 v198, v84, v198
	v_mul_f32_e32 v199, v85, v199
	v_mul_f32_e32 v200, v86, v200
	v_mul_f32_e32 v201, v87, v201
	v_mov_b32_dpp v206, v198 quad_perm:[1,0,3,2] row_mask:0xf bank_mask:0xf
	v_mov_b32_dpp v207, v199 quad_perm:[1,0,3,2] row_mask:0xf bank_mask:0xf
	v_add_u32_e32 v204, 0x8400, v204
	v_cndmask_b32_e32 v208, v198, v207, vcc
	v_cndmask_b32_e32 v209, v206, v199, vcc
	v_cvt_pk_bf16_f32 v202, v208, v209
	global_store_dword v204, v202, s[64:65]
	v_mov_b32_dpp v206, v200 quad_perm:[1,0,3,2] row_mask:0xf bank_mask:0xf
	v_mov_b32_dpp v207, v201 quad_perm:[1,0,3,2] row_mask:0xf bank_mask:0xf
	v_add_u32_e32 v204, 0x2c00, v204
	v_cndmask_b32_e32 v208, v200, v207, vcc
	v_cndmask_b32_e32 v209, v206, v201, vcc
	v_cvt_pk_bf16_f32 v203, v208, v209
	global_store_dword v204, v203, s[64:65]
	v_mul_f32_e32 v198, 0xbfb8aa3b, v72
	v_mul_f32_e32 v199, 0xbfb8aa3b, v73
	v_mul_f32_e32 v200, 0xbfb8aa3b, v74
	v_mul_f32_e32 v201, 0xbfb8aa3b, v75
	v_exp_f32_e32 v198, v198
	v_exp_f32_e32 v199, v199
	v_exp_f32_e32 v200, v200
	v_exp_f32_e32 v201, v201
	v_add_f32_e32 v198, 1.0, v198
	v_add_f32_e32 v199, 1.0, v199
	v_add_f32_e32 v200, 1.0, v200
	v_add_f32_e32 v201, 1.0, v201
	v_rcp_f32_e32 v198, v198
	v_rcp_f32_e32 v199, v199
	v_rcp_f32_e32 v200, v200
	v_rcp_f32_e32 v201, v201
	v_mul_f32_e32 v198, v72, v198
	v_mul_f32_e32 v199, v73, v199
	v_mul_f32_e32 v200, v74, v200
	v_mul_f32_e32 v201, v75, v201
	v_mul_f32_e32 v198, v88, v198
	v_mul_f32_e32 v199, v89, v199
	v_mul_f32_e32 v200, v90, v200
	v_mul_f32_e32 v201, v91, v201
	v_mov_b32_dpp v206, v198 quad_perm:[1,0,3,2] row_mask:0xf bank_mask:0xf
	v_mov_b32_dpp v207, v199 quad_perm:[1,0,3,2] row_mask:0xf bank_mask:0xf
	v_add_u32_e32 v204, 0x8400, v204
	v_cndmask_b32_e32 v208, v198, v207, vcc
	v_cndmask_b32_e32 v209, v206, v199, vcc
	v_cvt_pk_bf16_f32 v202, v208, v209
	global_store_dword v204, v202, s[64:65]
	v_mov_b32_dpp v206, v200 quad_perm:[1,0,3,2] row_mask:0xf bank_mask:0xf
	v_mov_b32_dpp v207, v201 quad_perm:[1,0,3,2] row_mask:0xf bank_mask:0xf
	v_add_u32_e32 v204, 0x2c00, v204
	v_cndmask_b32_e32 v208, v200, v207, vcc
	v_cndmask_b32_e32 v209, v206, v201, vcc
	v_cvt_pk_bf16_f32 v203, v208, v209
	global_store_dword v204, v203, s[64:65]
	v_mul_f32_e32 v198, 0xbfb8aa3b, v76
	v_mul_f32_e32 v199, 0xbfb8aa3b, v77
	v_mul_f32_e32 v200, 0xbfb8aa3b, v78
	v_mul_f32_e32 v201, 0xbfb8aa3b, v79
	v_exp_f32_e32 v198, v198
	v_exp_f32_e32 v199, v199
	v_exp_f32_e32 v200, v200
	v_exp_f32_e32 v201, v201
	v_add_f32_e32 v198, 1.0, v198
	v_add_f32_e32 v199, 1.0, v199
	v_add_f32_e32 v200, 1.0, v200
	v_add_f32_e32 v201, 1.0, v201
	v_rcp_f32_e32 v198, v198
	v_rcp_f32_e32 v199, v199
	v_rcp_f32_e32 v200, v200
	v_rcp_f32_e32 v201, v201
	v_mul_f32_e32 v198, v76, v198
	v_mul_f32_e32 v199, v77, v199
	v_mul_f32_e32 v200, v78, v200
	v_mul_f32_e32 v201, v79, v201
	v_mul_f32_e32 v198, v92, v198
	v_mul_f32_e32 v199, v93, v199
	v_mul_f32_e32 v200, v94, v200
	v_mul_f32_e32 v201, v95, v201
	v_mov_b32_dpp v206, v198 quad_perm:[1,0,3,2] row_mask:0xf bank_mask:0xf
	v_mov_b32_dpp v207, v199 quad_perm:[1,0,3,2] row_mask:0xf bank_mask:0xf
	v_add_u32_e32 v204, 0x8400, v204
	v_cndmask_b32_e32 v208, v198, v207, vcc
	v_cndmask_b32_e32 v209, v206, v199, vcc
	v_cvt_pk_bf16_f32 v202, v208, v209
	global_store_dword v204, v202, s[64:65]
	v_mov_b32_dpp v206, v200 quad_perm:[1,0,3,2] row_mask:0xf bank_mask:0xf
	v_mov_b32_dpp v207, v201 quad_perm:[1,0,3,2] row_mask:0xf bank_mask:0xf
	v_add_u32_e32 v204, 0x2c00, v204
	v_cndmask_b32_e32 v208, v200, v207, vcc
; DI bf16_t to_bf16(float a) { return (bf16_t)(pk_bf16(a, 0.f) & 0xffffu); }
; DI int crow(int i, int h) { return (i & 3) + 8 * (i >> 2) + 4 * h; }
;     DI void operator()(const f32x16 (&acc)[2][2], int row0, int col0, int r, int h, const float*) const {
;         const int hc = (col0 >> 1) + r;
; #pragma unroll
;         for (int mi = 0; mi < 2; ++mi)
; #pragma unroll
;             for (int i = 0; i < 16; ++i) {
;                 const int row = row0 + mi * 32 + crow(i, h);
;                 const float gt = acc[mi][0][i], up = acc[mi][1][i];
;                 ACT[(size_t)row * DFF + hc] = to_bf16(gt * __builtin_amdgcn_rcpf(1.f + __expf(-gt)) * up);
;             }
	v_cndmask_b32_e32 v209, v206, v201, vcc
	v_cvt_pk_bf16_f32 v203, v208, v209
	global_store_dword v204, v203, s[64:65]
	v_mul_f32_e32 v198, 0xbfb8aa3b, v32
	v_mul_f32_e32 v199, 0xbfb8aa3b, v33
	v_mul_f32_e32 v200, 0xbfb8aa3b, v34
	v_mul_f32_e32 v201, 0xbfb8aa3b, v35
	v_exp_f32_e32 v198, v198
	v_exp_f32_e32 v199, v199
	v_exp_f32_e32 v200, v200
	v_exp_f32_e32 v201, v201
	v_add_f32_e32 v198, 1.0, v198
	v_add_f32_e32 v199, 1.0, v199
	v_add_f32_e32 v200, 1.0, v200
	v_add_f32_e32 v201, 1.0, v201
	v_rcp_f32_e32 v198, v198
	v_rcp_f32_e32 v199, v199
	v_rcp_f32_e32 v200, v200
	v_rcp_f32_e32 v201, v201
	v_mul_f32_e32 v198, v32, v198
	v_mul_f32_e32 v199, v33, v199
	v_mul_f32_e32 v200, v34, v200
	v_mul_f32_e32 v201, v35, v201
	v_mul_f32_e32 v198, v48, v198
	v_mul_f32_e32 v199, v49, v199
	v_mul_f32_e32 v200, v50, v200
	v_mul_f32_e32 v201, v51, v201
	v_mov_b32_dpp v206, v198 quad_perm:[1,0,3,2] row_mask:0xf bank_mask:0xf
	v_mov_b32_dpp v207, v199 quad_perm:[1,0,3,2] row_mask:0xf bank_mask:0xf
	v_add_u32_e32 v204, 0x8400, v204
	v_cndmask_b32_e32 v208, v198, v207, vcc
	v_cndmask_b32_e32 v209, v206, v199, vcc
	v_cvt_pk_bf16_f32 v202, v208, v209
	global_store_dword v204, v202, s[64:65]
	v_mov_b32_dpp v206, v200 quad_perm:[1,0,3,2] row_mask:0xf bank_mask:0xf
	v_mov_b32_dpp v207, v201 quad_perm:[1,0,3,2] row_mask:0xf bank_mask:0xf
	v_add_u32_e32 v204, 0x2c00, v204
	v_cndmask_b32_e32 v208, v200, v207, vcc
	v_cndmask_b32_e32 v209, v206, v201, vcc
	v_cvt_pk_bf16_f32 v203, v208, v209
	global_store_dword v204, v203, s[64:65]
	v_mul_f32_e32 v198, 0xbfb8aa3b, v36
	v_mul_f32_e32 v199, 0xbfb8aa3b, v37
	v_mul_f32_e32 v200, 0xbfb8aa3b, v38
	v_mul_f32_e32 v201, 0xbfb8aa3b, v39
	v_exp_f32_e32 v198, v198
	v_exp_f32_e32 v199, v199
	v_exp_f32_e32 v200, v200
	v_exp_f32_e32 v201, v201
	v_add_f32_e32 v198, 1.0, v198
	v_add_f32_e32 v199, 1.0, v199
	v_add_f32_e32 v200, 1.0, v200
	v_add_f32_e32 v201, 1.0, v201
	v_rcp_f32_e32 v198, v198
	v_rcp_f32_e32 v199, v199
	v_rcp_f32_e32 v200, v200
	v_rcp_f32_e32 v201, v201
	v_mul_f32_e32 v198, v36, v198
	v_mul_f32_e32 v199, v37, v199
	v_mul_f32_e32 v200, v38, v200
	v_mul_f32_e32 v201, v39, v201
	v_mul_f32_e32 v198, v52, v198
	v_mul_f32_e32 v199, v53, v199
	v_mul_f32_e32 v200, v54, v200
	v_mul_f32_e32 v201, v55, v201
	v_mov_b32_dpp v206, v198 quad_perm:[1,0,3,2] row_mask:0xf bank_mask:0xf
	v_mov_b32_dpp v207, v199 quad_perm:[1,0,3,2] row_mask:0xf bank_mask:0xf
	v_add_u32_e32 v204, 0x8400, v204
	v_cndmask_b32_e32 v208, v198, v207, vcc
	v_cndmask_b32_e32 v209, v206, v199, vcc
	v_cvt_pk_bf16_f32 v202, v208, v209
	global_store_dword v204, v202, s[64:65]
	v_mov_b32_dpp v206, v200 quad_perm:[1,0,3,2] row_mask:0xf bank_mask:0xf
	v_mov_b32_dpp v207, v201 quad_perm:[1,0,3,2] row_mask:0xf bank_mask:0xf
	v_add_u32_e32 v204, 0x2c00, v204
	v_cndmask_b32_e32 v208, v200, v207, vcc
	v_cndmask_b32_e32 v209, v206, v201, vcc
	v_cvt_pk_bf16_f32 v203, v208, v209
	global_store_dword v204, v203, s[64:65]
	v_mul_f32_e32 v198, 0xbfb8aa3b, v40
	v_mul_f32_e32 v199, 0xbfb8aa3b, v41
	v_mul_f32_e32 v200, 0xbfb8aa3b, v42
	v_mul_f32_e32 v201, 0xbfb8aa3b, v43
	v_exp_f32_e32 v198, v198
	v_exp_f32_e32 v199, v199
	v_exp_f32_e32 v200, v200
	v_exp_f32_e32 v201, v201
	v_add_f32_e32 v198, 1.0, v198
	v_add_f32_e32 v199, 1.0, v199
	v_add_f32_e32 v200, 1.0, v200
	v_add_f32_e32 v201, 1.0, v201
	v_rcp_f32_e32 v198, v198
	v_rcp_f32_e32 v199, v199
	v_rcp_f32_e32 v200, v200
	v_rcp_f32_e32 v201, v201
	v_mul_f32_e32 v198, v40, v198
	v_mul_f32_e32 v199, v41, v199
	v_mul_f32_e32 v200, v42, v200
	v_mul_f32_e32 v201, v43, v201
	v_mul_f32_e32 v198, v56, v198
	v_mul_f32_e32 v199, v57, v199
	v_mul_f32_e32 v200, v58, v200
	v_mul_f32_e32 v201, v59, v201
	v_mov_b32_dpp v206, v198 quad_perm:[1,0,3,2] row_mask:0xf bank_mask:0xf
	v_mov_b32_dpp v207, v199 quad_perm:[1,0,3,2] row_mask:0xf bank_mask:0xf
	v_add_u32_e32 v204, 0x8400, v204
	v_cndmask_b32_e32 v208, v198, v207, vcc
	v_cndmask_b32_e32 v209, v206, v199, vcc
	v_cvt_pk_bf16_f32 v202, v208, v209
	global_store_dword v204, v202, s[64:65]
	v_mov_b32_dpp v206, v200 quad_perm:[1,0,3,2] row_mask:0xf bank_mask:0xf
	v_mov_b32_dpp v207, v201 quad_perm:[1,0,3,2] row_mask:0xf bank_mask:0xf
	v_add_u32_e32 v204, 0x2c00, v204
	v_cndmask_b32_e32 v208, v200, v207, vcc
	v_cndmask_b32_e32 v209, v206, v201, vcc
	v_cvt_pk_bf16_f32 v203, v208, v209
	global_store_dword v204, v203, s[64:65]
	v_mul_f32_e32 v198, 0xbfb8aa3b, v44
	v_mul_f32_e32 v199, 0xbfb8aa3b, v45
	v_mul_f32_e32 v200, 0xbfb8aa3b, v46
	v_mul_f32_e32 v201, 0xbfb8aa3b, v47
	v_exp_f32_e32 v198, v198
	v_exp_f32_e32 v199, v199
	v_exp_f32_e32 v200, v200
	v_exp_f32_e32 v201, v201
	v_add_f32_e32 v198, 1.0, v198
	v_add_f32_e32 v199, 1.0, v199
	v_add_f32_e32 v200, 1.0, v200
	v_add_f32_e32 v201, 1.0, v201
	v_rcp_f32_e32 v198, v198
	v_rcp_f32_e32 v199, v199
	v_rcp_f32_e32 v200, v200
	v_rcp_f32_e32 v201, v201
	v_mul_f32_e32 v198, v44, v198
	v_mul_f32_e32 v199, v45, v199
	v_mul_f32_e32 v200, v46, v200
	v_mul_f32_e32 v201, v47, v201
	v_mul_f32_e32 v198, v60, v198
	v_mul_f32_e32 v199, v61, v199
	v_mul_f32_e32 v200, v62, v200
	v_mul_f32_e32 v201, v63, v201
	v_mov_b32_dpp v206, v198 quad_perm:[1,0,3,2] row_mask:0xf bank_mask:0xf
	v_mov_b32_dpp v207, v199 quad_perm:[1,0,3,2] row_mask:0xf bank_mask:0xf
	v_add_u32_e32 v204, 0x8400, v204
	v_cndmask_b32_e32 v208, v198, v207, vcc
	v_cndmask_b32_e32 v209, v206, v199, vcc
	v_cvt_pk_bf16_f32 v202, v208, v209
	global_store_dword v204, v202, s[64:65]
	v_mov_b32_dpp v206, v200 quad_perm:[1,0,3,2] row_mask:0xf bank_mask:0xf
	v_mov_b32_dpp v207, v201 quad_perm:[1,0,3,2] row_mask:0xf bank_mask:0xf
	v_add_u32_e32 v204, 0x2c00, v204
	v_cndmask_b32_e32 v208, v200, v207, vcc
; DI bf16_t to_bf16(float a) { return (bf16_t)(pk_bf16(a, 0.f) & 0xffffu); }
; DI int crow(int i, int h) { return (i & 3) + 8 * (i >> 2) + 4 * h; }
;     DI void operator()(const f32x16 (&acc)[2][2], int row0, int col0, int r, int h, const float*) const {
;         const int hc = (col0 >> 1) + r;
; #pragma unroll
;         for (int mi = 0; mi < 2; ++mi)
; #pragma unroll
;             for (int i = 0; i < 16; ++i) {
;                 const int row = row0 + mi * 32 + crow(i, h);
;                 const float gt = acc[mi][0][i], up = acc[mi][1][i];
;                 ACT[(size_t)row * DFF + hc] = to_bf16(gt * __builtin_amdgcn_rcpf(1.f + __expf(-gt)) * up);
;             }
	v_cndmask_b32_e32 v209, v206, v201, vcc
	v_cvt_pk_bf16_f32 v203, v208, v209
	global_store_dword v204, v203, s[64:65]
	v_mul_f32_e32 v198, 0xbfb8aa3b, v0
	v_mul_f32_e32 v199, 0xbfb8aa3b, v1
	v_mul_f32_e32 v200, 0xbfb8aa3b, v2
	v_mul_f32_e32 v201, 0xbfb8aa3b, v3
	v_exp_f32_e32 v198, v198
	v_exp_f32_e32 v199, v199
	v_exp_f32_e32 v200, v200
	v_exp_f32_e32 v201, v201
	v_add_f32_e32 v198, 1.0, v198
	v_add_f32_e32 v199, 1.0, v199
	v_add_f32_e32 v200, 1.0, v200
	v_add_f32_e32 v201, 1.0, v201
	v_rcp_f32_e32 v198, v198
	v_rcp_f32_e32 v199, v199
	v_rcp_f32_e32 v200, v200
	v_rcp_f32_e32 v201, v201
	v_mul_f32_e32 v198, v0, v198
	v_mul_f32_e32 v199, v1, v199
	v_mul_f32_e32 v200, v2, v200
	v_mul_f32_e32 v201, v3, v201
	v_mul_f32_e32 v198, v16, v198
	v_mul_f32_e32 v199, v17, v199
	v_mul_f32_e32 v200, v18, v200
	v_mul_f32_e32 v201, v19, v201
	v_mov_b32_dpp v206, v198 quad_perm:[1,0,3,2] row_mask:0xf bank_mask:0xf
	v_mov_b32_dpp v207, v199 quad_perm:[1,0,3,2] row_mask:0xf bank_mask:0xf
	v_add_u32_e32 v204, 0x8400, v204
	v_cndmask_b32_e32 v208, v198, v207, vcc
	v_cndmask_b32_e32 v209, v206, v199, vcc
	v_cvt_pk_bf16_f32 v202, v208, v209
	global_store_dword v204, v202, s[64:65]
	v_mov_b32_dpp v206, v200 quad_perm:[1,0,3,2] row_mask:0xf bank_mask:0xf
	v_mov_b32_dpp v207, v201 quad_perm:[1,0,3,2] row_mask:0xf bank_mask:0xf
	v_add_u32_e32 v204, 0x2c00, v204
	v_cndmask_b32_e32 v208, v200, v207, vcc
	v_cndmask_b32_e32 v209, v206, v201, vcc
	v_cvt_pk_bf16_f32 v203, v208, v209
	global_store_dword v204, v203, s[64:65]
	v_mul_f32_e32 v198, 0xbfb8aa3b, v4
	v_mul_f32_e32 v199, 0xbfb8aa3b, v5
	v_mul_f32_e32 v200, 0xbfb8aa3b, v6
	v_mul_f32_e32 v201, 0xbfb8aa3b, v7
	v_exp_f32_e32 v198, v198
	v_exp_f32_e32 v199, v199
	v_exp_f32_e32 v200, v200
	v_exp_f32_e32 v201, v201
	v_add_f32_e32 v198, 1.0, v198
	v_add_f32_e32 v199, 1.0, v199
	v_add_f32_e32 v200, 1.0, v200
	v_add_f32_e32 v201, 1.0, v201
	v_rcp_f32_e32 v198, v198
	v_rcp_f32_e32 v199, v199
	v_rcp_f32_e32 v200, v200
	v_rcp_f32_e32 v201, v201
	v_mul_f32_e32 v198, v4, v198
	v_mul_f32_e32 v199, v5, v199
	v_mul_f32_e32 v200, v6, v200
	v_mul_f32_e32 v201, v7, v201
	v_mul_f32_e32 v198, v20, v198
	v_mul_f32_e32 v199, v21, v199
	v_mul_f32_e32 v200, v22, v200
	v_mul_f32_e32 v201, v23, v201
	v_mov_b32_dpp v206, v198 quad_perm:[1,0,3,2] row_mask:0xf bank_mask:0xf
	v_mov_b32_dpp v207, v199 quad_perm:[1,0,3,2] row_mask:0xf bank_mask:0xf
	v_add_u32_e32 v204, 0x8400, v204
	v_cndmask_b32_e32 v208, v198, v207, vcc
	v_cndmask_b32_e32 v209, v206, v199, vcc
	v_cvt_pk_bf16_f32 v202, v208, v209
	global_store_dword v204, v202, s[64:65]
	v_mov_b32_dpp v206, v200 quad_perm:[1,0,3,2] row_mask:0xf bank_mask:0xf
	v_mov_b32_dpp v207, v201 quad_perm:[1,0,3,2] row_mask:0xf bank_mask:0xf
	v_add_u32_e32 v204, 0x2c00, v204
	v_cndmask_b32_e32 v208, v200, v207, vcc
	v_cndmask_b32_e32 v209, v206, v201, vcc
	v_cvt_pk_bf16_f32 v203, v208, v209
	global_store_dword v204, v203, s[64:65]
	v_mul_f32_e32 v198, 0xbfb8aa3b, v8
	v_mul_f32_e32 v199, 0xbfb8aa3b, v9
	v_mul_f32_e32 v200, 0xbfb8aa3b, v10
	v_mul_f32_e32 v201, 0xbfb8aa3b, v11
	v_exp_f32_e32 v198, v198
	v_exp_f32_e32 v199, v199
	v_exp_f32_e32 v200, v200
	v_exp_f32_e32 v201, v201
	v_add_f32_e32 v198, 1.0, v198
	v_add_f32_e32 v199, 1.0, v199
	v_add_f32_e32 v200, 1.0, v200
	v_add_f32_e32 v201, 1.0, v201
	v_rcp_f32_e32 v198, v198
	v_rcp_f32_e32 v199, v199
	v_rcp_f32_e32 v200, v200
	v_rcp_f32_e32 v201, v201
	v_mul_f32_e32 v198, v8, v198
	v_mul_f32_e32 v199, v9, v199
	v_mul_f32_e32 v200, v10, v200
	v_mul_f32_e32 v201, v11, v201
	v_mul_f32_e32 v198, v24, v198
	v_mul_f32_e32 v199, v25, v199
	v_mul_f32_e32 v200, v26, v200
	v_mul_f32_e32 v201, v27, v201
	v_mov_b32_dpp v206, v198 quad_perm:[1,0,3,2] row_mask:0xf bank_mask:0xf
	v_mov_b32_dpp v207, v199 quad_perm:[1,0,3,2] row_mask:0xf bank_mask:0xf
	v_add_u32_e32 v204, 0x8400, v204
	v_cndmask_b32_e32 v208, v198, v207, vcc
	v_cndmask_b32_e32 v209, v206, v199, vcc
	v_cvt_pk_bf16_f32 v202, v208, v209
	global_store_dword v204, v202, s[64:65]
	v_mov_b32_dpp v206, v200 quad_perm:[1,0,3,2] row_mask:0xf bank_mask:0xf
	v_mov_b32_dpp v207, v201 quad_perm:[1,0,3,2] row_mask:0xf bank_mask:0xf
	v_add_u32_e32 v204, 0x2c00, v204
	v_cndmask_b32_e32 v208, v200, v207, vcc
	v_cndmask_b32_e32 v209, v206, v201, vcc
	v_cvt_pk_bf16_f32 v203, v208, v209
	global_store_dword v204, v203, s[64:65]
	v_mul_f32_e32 v198, 0xbfb8aa3b, v12
	v_mul_f32_e32 v199, 0xbfb8aa3b, v13
	v_mul_f32_e32 v200, 0xbfb8aa3b, v14
	v_mul_f32_e32 v201, 0xbfb8aa3b, v15
	v_exp_f32_e32 v198, v198
	v_exp_f32_e32 v199, v199
	v_exp_f32_e32 v200, v200
	v_exp_f32_e32 v201, v201
	v_add_f32_e32 v198, 1.0, v198
	v_add_f32_e32 v199, 1.0, v199
	v_add_f32_e32 v200, 1.0, v200
	v_add_f32_e32 v201, 1.0, v201
	v_rcp_f32_e32 v198, v198
	v_rcp_f32_e32 v199, v199
	v_rcp_f32_e32 v200, v200
	v_rcp_f32_e32 v201, v201
	v_mul_f32_e32 v198, v12, v198
	v_mul_f32_e32 v199, v13, v199
	v_mul_f32_e32 v200, v14, v200
	v_mul_f32_e32 v201, v15, v201
	v_mul_f32_e32 v198, v28, v198
	v_mul_f32_e32 v199, v29, v199
	v_mul_f32_e32 v200, v30, v200
	v_mul_f32_e32 v201, v31, v201
	v_mov_b32_dpp v206, v198 quad_perm:[1,0,3,2] row_mask:0xf bank_mask:0xf
	v_mov_b32_dpp v207, v199 quad_perm:[1,0,3,2] row_mask:0xf bank_mask:0xf
	v_add_u32_e32 v204, 0x8400, v204
	v_cndmask_b32_e32 v208, v198, v207, vcc
	v_cndmask_b32_e32 v209, v206, v199, vcc
	v_cvt_pk_bf16_f32 v202, v208, v209
	global_store_dword v204, v202, s[64:65]
	v_mov_b32_dpp v206, v200 quad_perm:[1,0,3,2] row_mask:0xf bank_mask:0xf
	v_mov_b32_dpp v207, v201 quad_perm:[1,0,3,2] row_mask:0xf bank_mask:0xf
	v_add_u32_e32 v204, 0x2c00, v204
	v_cndmask_b32_e32 v208, v200, v207, vcc
	v_cndmask_b32_e32 v209, v206, v201, vcc
	v_cvt_pk_bf16_f32 v203, v208, v209
	global_store_dword v204, v203, s[64:65]
